# A/B: every s_setprio removed from the nine GEMM mainloops (equal priority for both waves of a SIMD)
# speedup vs baseline: 1.0090x; 1.0090x over previous
; #define PG8_STAGE(bufoff, gbase, voff) do { _Pragma("unroll") for (int _i = 0; _i < 2; ++_i) \
;         __builtin_amdgcn_global_load_lds((const unsigned*)((const char*)(gbase) + (voff)[_i]), (LAS unsigned*)(lds + (bufoff) + ldsw + _i * 8192), 16, 0, 0); } while (0)
; #define PG8_LDA(dst, b, h) do { _Pragma("unroll") for (int m = 0; m < 4; ++m) _Pragma("unroll") for (int k = 0; k < 2; ++k) dst[m][k] = *(const LAS bf16x8*)(lds + PG8_SA(b, h) + aoff + m * 2048 + k * 1024); } while (0)
; #define PG8_LDB(dst, b, h) do { _Pragma("unroll") for (int n = 0; n < 2; ++n) _Pragma("unroll") for (int k = 0; k < 2; ++k) dst[n][k] = *(const LAS bf16x8*)(lds + PG8_SB(b, h) + boff + n * 2048 + k * 1024); } while (0)
; #define PG8_MMA(ai, bj, At, Bt) do { __builtin_amdgcn_s_setprio(1); _Pragma("unroll") for (int m = 0; m < 4; ++m) _Pragma("unroll") for (int n = 0; n < 2; ++n) _Pragma("unroll") for (int k = 0; k < 2; ++k) \
;         acc[ai][bj][m][n] = __builtin_amdgcn_mfma_f32_16x16x32_bf16(Bt[n][k], At[m][k], acc[ai][bj][m][n], 0, 0, 0); __builtin_amdgcn_s_setprio(0); } while (0)
; #define PG8_WAIT_V(n) asm volatile("s_waitcnt vmcnt(" #n ")" ::: "memory")
; #define PG8_WAIT_L(n) asm volatile("s_waitcnt lgkmcnt(" #n ")" ::: "memory")
; #define PG8_BAR __builtin_amdgcn_s_barrier()
; #define PG8_SCHED __builtin_amdgcn_sched_barrier(0)
; template <class Epi>
; __device__ __forceinline__ void gemm_phase(LAS unsigned char* lds, const Sched& S, const int K, const Epi& E) {
;     ...
;         for (int t = 0; t < nt; t += 2) {
;             const bool last = (t == nt - 2);
;             const char* a1 = cA + (size_t)(t + 1) * kstep;
;             const char* a2 = last ? nA : cA + (size_t)(t + 2) * kstep; const char* b2 = last ? nB : cB + (size_t)(t + 2) * kstep;
;             const char* a3 = a2 + kstep; const char* b3 = b2 + kstep;
;             PG8_LDB(B0, 0, 0); PG8_LDB(B1, 0, 1); PG8_SCHED; PG8_LDA(At, 0, 0); PG8_STAGE(PG8_SA(1, 1), a1 + hstepA, voffA);
;             PG8_WAIT_V(8); PG8_WAIT_L(0); PG8_BAR; PG8_MMA(0, 0, At, B0); PG8_MMA(0, 1, At, B1); PG8_BAR; PG8_SCHED;
;             PG8_LDA(At, 0, 1); PG8_STAGE(PG8_SB(0, 0), b2, voffB); PG8_STAGE(PG8_SB(0, 1), b2 + hstepB, voffB); PG8_STAGE(PG8_SA(0, 0), a2, voffA);
;             PG8_WAIT_V(8); PG8_WAIT_L(0); PG8_BAR; PG8_MMA(1, 0, At, B0); PG8_MMA(1, 1, At, B1); PG8_BAR; PG8_SCHED;
.LBB0_457:
	s_add_u32 s58, s36, 0xfff80080
	s_addc_u32 s59, s37, -1
	s_add_i32 s76, 0, 0x10000
	s_cmp_eq_u32 s97, 28
	s_cselect_b32 s93, s29, s59
	s_cselect_b32 s92, s28, s58
	v_add_u32_e32 v143, s76, v151
	s_cselect_b32 s59, s35, s64
	s_cselect_b32 s58, s34, s51
	s_add_i32 s77, 0, 0x14000
	ds_read_b128 v[144:147], v143
	ds_read_b128 v[156:159], v143 offset:1024
	ds_read_b128 v[160:163], v143 offset:2048
	ds_read_b128 v[164:167], v143 offset:3072
	v_add_u32_e32 v143, s77, v151
	ds_read_b128 v[168:171], v143
	ds_read_b128 v[198:201], v143 offset:1024
	ds_read_b128 v[202:205], v143 offset:2048
	ds_read_b128 v[206:209], v143 offset:3072
	v_lshl_add_u64 v[148:149], s[36:37], 0, v[138:139]
	s_add_i32 m0, s60, 0xc000
	ds_read_b128 v[210:213], v154
	ds_read_b128 v[214:217], v154 offset:1024
	ds_read_b128 v[218:221], v154 offset:2048
	ds_read_b128 v[228:231], v154 offset:3072
	ds_read_b128 v[232:235], v154 offset:4096
	ds_read_b128 v[236:239], v154 offset:5120
	ds_read_b128 v[240:243], v154 offset:6144
	ds_read_b128 v[244:247], v154 offset:7168
	global_load_lds_dwordx4 v[148:149], off
	v_lshl_add_u64 v[148:149], s[36:37], 0, v[140:141]
	s_add_i32 m0, s60, 0xe000
	s_nop 0
	global_load_lds_dwordx4 v[148:149], off
	s_waitcnt vmcnt(8)
	s_waitcnt lgkmcnt(0)
	s_barrier
	s_waitcnt lgkmcnt(0)
	v_mfma_f32_16x16x32_bf16 v[124:127], v[144:147], v[210:213], v[124:127]
	v_mfma_f32_16x16x32_bf16 v[120:123], v[160:163], v[210:213], v[120:123]
	v_mfma_f32_16x16x32_bf16 v[108:111], v[144:147], v[218:221], v[108:111]
	v_mfma_f32_16x16x32_bf16 v[104:107], v[160:163], v[218:221], v[104:107]
	v_mfma_f32_16x16x32_bf16 v[92:95], v[144:147], v[232:235], v[92:95]
	v_mfma_f32_16x16x32_bf16 v[88:91], v[160:163], v[232:235], v[88:91]
	v_mfma_f32_16x16x32_bf16 v[76:79], v[144:147], v[240:243], v[76:79]
	v_mfma_f32_16x16x32_bf16 v[72:75], v[160:163], v[240:243], v[72:75]
	v_mfma_f32_16x16x32_bf16 v[124:127], v[156:159], v[214:217], v[124:127]
	v_mfma_f32_16x16x32_bf16 v[120:123], v[164:167], v[214:217], v[120:123]
	v_mfma_f32_16x16x32_bf16 v[108:111], v[156:159], v[228:231], v[108:111]
	v_mfma_f32_16x16x32_bf16 v[104:107], v[164:167], v[228:231], v[104:107]
	v_mfma_f32_16x16x32_bf16 v[92:95], v[156:159], v[236:239], v[92:95]
	v_mfma_f32_16x16x32_bf16 v[88:91], v[164:167], v[236:239], v[88:91]
	v_mfma_f32_16x16x32_bf16 v[76:79], v[156:159], v[244:247], v[76:79]
	v_mfma_f32_16x16x32_bf16 v[72:75], v[164:167], v[244:247], v[72:75]
	v_mfma_f32_16x16x32_bf16 v[116:119], v[168:171], v[210:213], v[116:119]
	v_mfma_f32_16x16x32_bf16 v[112:115], v[202:205], v[210:213], v[112:115]
	v_mfma_f32_16x16x32_bf16 v[100:103], v[168:171], v[218:221], v[100:103]
	v_mfma_f32_16x16x32_bf16 v[96:99], v[202:205], v[218:221], v[96:99]
	v_mfma_f32_16x16x32_bf16 v[84:87], v[168:171], v[232:235], v[84:87]
	v_mfma_f32_16x16x32_bf16 v[80:83], v[202:205], v[232:235], v[80:83]
	v_mfma_f32_16x16x32_bf16 v[68:71], v[168:171], v[240:243], v[68:71]
	v_mfma_f32_16x16x32_bf16 v[64:67], v[202:205], v[240:243], v[64:67]
	v_mfma_f32_16x16x32_bf16 v[116:119], v[198:201], v[214:217], v[116:119]
	v_mfma_f32_16x16x32_bf16 v[112:115], v[206:209], v[214:217], v[112:115]
	v_mfma_f32_16x16x32_bf16 v[100:103], v[198:201], v[228:231], v[100:103]
	v_mfma_f32_16x16x32_bf16 v[96:99], v[206:209], v[228:231], v[96:99]
	v_mfma_f32_16x16x32_bf16 v[84:87], v[198:201], v[236:239], v[84:87]
	v_mfma_f32_16x16x32_bf16 v[80:83], v[206:209], v[236:239], v[80:83]
	v_mfma_f32_16x16x32_bf16 v[68:71], v[198:201], v[244:247], v[68:71]
	v_mfma_f32_16x16x32_bf16 v[64:67], v[206:209], v[244:247], v[64:67]
	s_barrier
	s_add_i32 s76, s76, s57
	v_lshl_add_u64 v[148:149], s[58:59], 0, v[132:133]
	s_mov_b32 m0, s76
	ds_read_b128 v[210:213], v154 offset:16384
	ds_read_b128 v[214:217], v154 offset:17408
	ds_read_b128 v[218:221], v154 offset:18432
	ds_read_b128 v[228:231], v154 offset:19456
	ds_read_b128 v[232:235], v154 offset:20480
	ds_read_b128 v[236:239], v154 offset:21504
	ds_read_b128 v[240:243], v154 offset:22528
	ds_read_b128 v[244:247], v154 offset:23552
	global_load_lds_dwordx4 v[148:149], off
	s_add_i32 m0, s76, 0x2000
	s_add_u32 vcc_lo, s58, 0x80000
	v_lshl_add_u64 v[248:249], s[58:59], 0, v[128:129]
	s_addc_u32 vcc_hi, s59, 0
	s_add_i32 s76, s77, s57
	global_load_lds_dwordx4 v[248:249], off
	v_lshl_add_u64 v[250:251], vcc, 0, v[132:133]
	s_mov_b32 m0, s76
	v_lshl_add_u64 v[224:225], s[92:93], 0, v[130:131]
	global_load_lds_dwordx4 v[250:251], off
	v_lshl_add_u64 v[250:251], vcc, 0, v[128:129]
	s_add_i32 m0, s76, 0x2000
	s_nop 0
	global_load_lds_dwordx4 v[250:251], off
	v_lshl_add_u64 v[250:251], s[92:93], 0, v[134:135]
	s_mov_b32 m0, s60
	s_nop 0
	global_load_lds_dwordx4 v[250:251], off
	s_mov_b32 m0, s63
	s_nop 0
	global_load_lds_dwordx4 v[224:225], off
	s_waitcnt vmcnt(8)
	s_waitcnt lgkmcnt(0)
	s_barrier
; #define PG8_STAGE(bufoff, gbase, voff) do { _Pragma("unroll") for (int _i = 0; _i < 2; ++_i) \
;         __builtin_amdgcn_global_load_lds((const unsigned*)((const char*)(gbase) + (voff)[_i]), (LAS unsigned*)(lds + (bufoff) + ldsw + _i * 8192), 16, 0, 0); } while (0)
; #define PG8_LDA(dst, b, h) do { _Pragma("unroll") for (int m = 0; m < 4; ++m) _Pragma("unroll") for (int k = 0; k < 2; ++k) dst[m][k] = *(const LAS bf16x8*)(lds + PG8_SA(b, h) + aoff + m * 2048 + k * 1024); } while (0)
; #define PG8_LDB(dst, b, h) do { _Pragma("unroll") for (int n = 0; n < 2; ++n) _Pragma("unroll") for (int k = 0; k < 2; ++k) dst[n][k] = *(const LAS bf16x8*)(lds + PG8_SB(b, h) + boff + n * 2048 + k * 1024); } while (0)
; #define PG8_MMA(ai, bj, At, Bt) do { __builtin_amdgcn_s_setprio(1); _Pragma("unroll") for (int m = 0; m < 4; ++m) _Pragma("unroll") for (int n = 0; n < 2; ++n) _Pragma("unroll") for (int k = 0; k < 2; ++k) \
;         acc[ai][bj][m][n] = __builtin_amdgcn_mfma_f32_16x16x32_bf16(Bt[n][k], At[m][k], acc[ai][bj][m][n], 0, 0, 0); __builtin_amdgcn_s_setprio(0); } while (0)
; #define PG8_WAIT_V(n) asm volatile("s_waitcnt vmcnt(" #n ")" ::: "memory")
; #define PG8_WAIT_L(n) asm volatile("s_waitcnt lgkmcnt(" #n ")" ::: "memory")
; #define PG8_BAR __builtin_amdgcn_s_barrier()
; #define PG8_SCHED __builtin_amdgcn_sched_barrier(0)
; template <class Epi>
; __device__ __forceinline__ void gemm_phase(LAS unsigned char* lds, const Sched& S, const int K, const Epi& E) {
;     ...
;             PG8_WAIT_V(8); PG8_WAIT_L(0); PG8_BAR; PG8_MMA(1, 0, At, B0); PG8_MMA(1, 1, At, B1); PG8_BAR; PG8_SCHED;
;             PG8_LDB(B0, 1, 0); PG8_LDB(B1, 1, 1); PG8_SCHED; PG8_LDA(At, 1, 0); PG8_STAGE(PG8_SA(0, 1), a2 + hstepA, voffA);
;             PG8_WAIT_V(8); PG8_WAIT_L(0); PG8_BAR; PG8_MMA(0, 0, At, B0); PG8_MMA(0, 1, At, B1); PG8_BAR; PG8_SCHED;
	s_waitcnt lgkmcnt(0)
	v_mfma_f32_16x16x32_bf16 v[60:63], v[144:147], v[210:213], v[60:63]
	v_mfma_f32_16x16x32_bf16 v[56:59], v[160:163], v[210:213], v[56:59]
	v_mfma_f32_16x16x32_bf16 v[44:47], v[144:147], v[218:221], v[44:47]
	v_mfma_f32_16x16x32_bf16 v[40:43], v[160:163], v[218:221], v[40:43]
	v_mfma_f32_16x16x32_bf16 v[28:31], v[144:147], v[232:235], v[28:31]
	v_mfma_f32_16x16x32_bf16 v[24:27], v[160:163], v[232:235], v[24:27]
	v_mfma_f32_16x16x32_bf16 v[12:15], v[144:147], v[240:243], v[12:15]
	v_mfma_f32_16x16x32_bf16 v[8:11], v[160:163], v[240:243], v[8:11]
	v_mfma_f32_16x16x32_bf16 v[60:63], v[156:159], v[214:217], v[60:63]
	v_mfma_f32_16x16x32_bf16 v[56:59], v[164:167], v[214:217], v[56:59]
	v_mfma_f32_16x16x32_bf16 v[44:47], v[156:159], v[228:231], v[44:47]
	v_mfma_f32_16x16x32_bf16 v[40:43], v[164:167], v[228:231], v[40:43]
	v_mfma_f32_16x16x32_bf16 v[28:31], v[156:159], v[236:239], v[28:31]
	v_mfma_f32_16x16x32_bf16 v[24:27], v[164:167], v[236:239], v[24:27]
	v_mfma_f32_16x16x32_bf16 v[12:15], v[156:159], v[244:247], v[12:15]
	v_mfma_f32_16x16x32_bf16 v[8:11], v[164:167], v[244:247], v[8:11]
	v_mfma_f32_16x16x32_bf16 v[52:55], v[168:171], v[210:213], v[52:55]
	v_mfma_f32_16x16x32_bf16 v[48:51], v[202:205], v[210:213], v[48:51]
	v_mfma_f32_16x16x32_bf16 v[36:39], v[168:171], v[218:221], v[36:39]
	v_mfma_f32_16x16x32_bf16 v[32:35], v[202:205], v[218:221], v[32:35]
	v_mfma_f32_16x16x32_bf16 v[20:23], v[168:171], v[232:235], v[20:23]
	v_mfma_f32_16x16x32_bf16 v[16:19], v[202:205], v[232:235], v[16:19]
	v_mfma_f32_16x16x32_bf16 v[4:7], v[168:171], v[240:243], v[4:7]
	v_mfma_f32_16x16x32_bf16 v[0:3], v[202:205], v[240:243], v[0:3]
	v_mfma_f32_16x16x32_bf16 v[52:55], v[198:201], v[214:217], v[52:55]
	v_mfma_f32_16x16x32_bf16 v[48:51], v[206:209], v[214:217], v[48:51]
	v_mfma_f32_16x16x32_bf16 v[36:39], v[198:201], v[228:231], v[36:39]
	v_mfma_f32_16x16x32_bf16 v[32:35], v[206:209], v[228:231], v[32:35]
	v_mfma_f32_16x16x32_bf16 v[20:23], v[198:201], v[236:239], v[20:23]
	v_mfma_f32_16x16x32_bf16 v[16:19], v[206:209], v[236:239], v[16:19]
	v_mfma_f32_16x16x32_bf16 v[4:7], v[198:201], v[244:247], v[4:7]
	v_mfma_f32_16x16x32_bf16 v[0:3], v[206:209], v[244:247], v[0:3]
	s_barrier
	s_add_i32 s76, 0, 0x18000
	v_add_u32_e32 v143, s76, v151
	s_add_i32 s77, 0, 0x1c000
	ds_read_b128 v[144:147], v143
	ds_read_b128 v[156:159], v143 offset:1024
	ds_read_b128 v[160:163], v143 offset:2048
	ds_read_b128 v[164:167], v143 offset:3072
	v_add_u32_e32 v143, s77, v151
	ds_read_b128 v[168:171], v143
	ds_read_b128 v[198:201], v143 offset:1024
	ds_read_b128 v[202:205], v143 offset:2048
	ds_read_b128 v[206:209], v143 offset:3072
	s_add_u32 s92, s92, 0x80000
	s_addc_u32 s93, s93, 0
	s_mov_b32 m0, s66
	v_lshl_add_u64 v[194:195], s[92:93], 0, v[134:135]
	ds_read_b128 v[210:213], v154 offset:32768
	ds_read_b128 v[214:217], v154 offset:33792
	ds_read_b128 v[218:221], v154 offset:34816
	ds_read_b128 v[228:231], v154 offset:35840
	ds_read_b128 v[232:235], v154 offset:36864
	ds_read_b128 v[236:239], v154 offset:37888
	ds_read_b128 v[240:243], v154 offset:38912
	ds_read_b128 v[244:247], v154 offset:39936
	global_load_lds_dwordx4 v[194:195], off
	v_lshl_add_u64 v[194:195], s[92:93], 0, v[130:131]
	s_mov_b32 m0, s67
	s_nop 0
	global_load_lds_dwordx4 v[194:195], off
	s_waitcnt vmcnt(8)
	s_waitcnt lgkmcnt(0)
	s_barrier
	s_waitcnt lgkmcnt(0)
	v_mfma_f32_16x16x32_bf16 v[124:127], v[144:147], v[210:213], v[124:127]
	v_mfma_f32_16x16x32_bf16 v[120:123], v[160:163], v[210:213], v[120:123]
	v_mfma_f32_16x16x32_bf16 v[108:111], v[144:147], v[218:221], v[108:111]
	v_mfma_f32_16x16x32_bf16 v[104:107], v[160:163], v[218:221], v[104:107]
	v_mfma_f32_16x16x32_bf16 v[92:95], v[144:147], v[232:235], v[92:95]
	v_mfma_f32_16x16x32_bf16 v[88:91], v[160:163], v[232:235], v[88:91]
	v_mfma_f32_16x16x32_bf16 v[76:79], v[144:147], v[240:243], v[76:79]
	v_mfma_f32_16x16x32_bf16 v[72:75], v[160:163], v[240:243], v[72:75]
	v_mfma_f32_16x16x32_bf16 v[124:127], v[156:159], v[214:217], v[124:127]
	v_mfma_f32_16x16x32_bf16 v[120:123], v[164:167], v[214:217], v[120:123]
	v_mfma_f32_16x16x32_bf16 v[108:111], v[156:159], v[228:231], v[108:111]
	v_mfma_f32_16x16x32_bf16 v[104:107], v[164:167], v[228:231], v[104:107]
	v_mfma_f32_16x16x32_bf16 v[92:95], v[156:159], v[236:239], v[92:95]
	v_mfma_f32_16x16x32_bf16 v[88:91], v[164:167], v[236:239], v[88:91]
	v_mfma_f32_16x16x32_bf16 v[76:79], v[156:159], v[244:247], v[76:79]
	v_mfma_f32_16x16x32_bf16 v[72:75], v[164:167], v[244:247], v[72:75]
	v_mfma_f32_16x16x32_bf16 v[116:119], v[168:171], v[210:213], v[116:119]
	v_mfma_f32_16x16x32_bf16 v[112:115], v[202:205], v[210:213], v[112:115]
	v_mfma_f32_16x16x32_bf16 v[100:103], v[168:171], v[218:221], v[100:103]
	v_mfma_f32_16x16x32_bf16 v[96:99], v[202:205], v[218:221], v[96:99]
	v_mfma_f32_16x16x32_bf16 v[84:87], v[168:171], v[232:235], v[84:87]
	v_mfma_f32_16x16x32_bf16 v[80:83], v[202:205], v[232:235], v[80:83]
	v_mfma_f32_16x16x32_bf16 v[68:71], v[168:171], v[240:243], v[68:71]
	v_mfma_f32_16x16x32_bf16 v[64:67], v[202:205], v[240:243], v[64:67]
	v_mfma_f32_16x16x32_bf16 v[116:119], v[198:201], v[214:217], v[116:119]
	v_mfma_f32_16x16x32_bf16 v[112:115], v[206:209], v[214:217], v[112:115]
	v_mfma_f32_16x16x32_bf16 v[100:103], v[198:201], v[228:231], v[100:103]
	v_mfma_f32_16x16x32_bf16 v[96:99], v[206:209], v[228:231], v[96:99]
	v_mfma_f32_16x16x32_bf16 v[84:87], v[198:201], v[236:239], v[84:87]
	v_mfma_f32_16x16x32_bf16 v[80:83], v[206:209], v[236:239], v[80:83]
	v_mfma_f32_16x16x32_bf16 v[68:71], v[198:201], v[244:247], v[68:71]
	v_mfma_f32_16x16x32_bf16 v[64:67], v[206:209], v[244:247], v[64:67]
	s_barrier
; #define PG8_STAGE(bufoff, gbase, voff) do { _Pragma("unroll") for (int _i = 0; _i < 2; ++_i) \
;         __builtin_amdgcn_global_load_lds((const unsigned*)((const char*)(gbase) + (voff)[_i]), (LAS unsigned*)(lds + (bufoff) + ldsw + _i * 8192), 16, 0, 0); } while (0)
; #define PG8_LDA(dst, b, h) do { _Pragma("unroll") for (int m = 0; m < 4; ++m) _Pragma("unroll") for (int k = 0; k < 2; ++k) dst[m][k] = *(const LAS bf16x8*)(lds + PG8_SA(b, h) + aoff + m * 2048 + k * 1024); } while (0)
; #define PG8_MMA(ai, bj, At, Bt) do { __builtin_amdgcn_s_setprio(1); _Pragma("unroll") for (int m = 0; m < 4; ++m) _Pragma("unroll") for (int n = 0; n < 2; ++n) _Pragma("unroll") for (int k = 0; k < 2; ++k) \
;         acc[ai][bj][m][n] = __builtin_amdgcn_mfma_f32_16x16x32_bf16(Bt[n][k], At[m][k], acc[ai][bj][m][n], 0, 0, 0); __builtin_amdgcn_s_setprio(0); } while (0)
; #define PG8_WAIT_V(n) asm volatile("s_waitcnt vmcnt(" #n ")" ::: "memory")
; #define PG8_WAIT_L(n) asm volatile("s_waitcnt lgkmcnt(" #n ")" ::: "memory")
; #define PG8_BAR __builtin_amdgcn_s_barrier()
; #define PG8_SCHED __builtin_amdgcn_sched_barrier(0)
; template <class Epi>
; __device__ __forceinline__ void gemm_phase(LAS unsigned char* lds, const Sched& S, const int K, const Epi& E) {
;     ...
;             PG8_LDA(At, 1, 1); PG8_STAGE(PG8_SB(1, 0), b3, voffB); PG8_STAGE(PG8_SB(1, 1), b3 + hstepB, voffB); PG8_STAGE(PG8_SA(1, 0), a3, voffA);
;             PG8_WAIT_V(8); PG8_WAIT_L(0); PG8_BAR; PG8_MMA(1, 0, At, B0); PG8_MMA(1, 1, At, B1); PG8_BAR; PG8_SCHED;
;         }
;         if (wr == 0) PG8_BAR;
	s_add_i32 s76, s76, s57
	v_lshl_add_u64 v[148:149], v[148:149], 0, s[74:75]
	s_mov_b32 m0, s76
	ds_read_b128 v[210:213], v154 offset:49152
	ds_read_b128 v[214:217], v154 offset:50176
	ds_read_b128 v[218:221], v154 offset:51200
	ds_read_b128 v[228:231], v154 offset:52224
	ds_read_b128 v[232:235], v154 offset:53248
	ds_read_b128 v[236:239], v154 offset:54272
	ds_read_b128 v[240:243], v154 offset:55296
	ds_read_b128 v[244:247], v154 offset:56320
	global_load_lds_dwordx4 v[148:149], off
	s_add_i32 m0, s76, 0x2000
	s_add_u32 s58, s58, 0x80080
	v_lshl_add_u64 v[148:149], v[248:249], 0, s[74:75]
	s_addc_u32 s59, s59, 0
	s_add_i32 s76, s77, s57
	global_load_lds_dwordx4 v[148:149], off
	v_lshl_add_u64 v[148:149], s[58:59], 0, v[132:133]
	s_mov_b32 m0, s76
	s_nop 0
	global_load_lds_dwordx4 v[148:149], off
	v_lshl_add_u64 v[148:149], s[58:59], 0, v[128:129]
	s_add_i32 m0, s76, 0x2000
	s_nop 0
	global_load_lds_dwordx4 v[148:149], off
	v_lshl_add_u64 v[148:149], v[250:251], 0, s[74:75]
	s_mov_b32 m0, s69
	s_nop 0
	global_load_lds_dwordx4 v[148:149], off
	v_lshl_add_u64 v[148:149], v[224:225], 0, s[74:75]
	s_mov_b32 m0, s70
	s_nop 0
	global_load_lds_dwordx4 v[148:149], off
	s_waitcnt vmcnt(8)
	s_waitcnt lgkmcnt(0)
	s_barrier
	s_waitcnt lgkmcnt(0)
	v_mfma_f32_16x16x32_bf16 v[60:63], v[144:147], v[210:213], v[60:63]
	v_mfma_f32_16x16x32_bf16 v[56:59], v[160:163], v[210:213], v[56:59]
	v_mfma_f32_16x16x32_bf16 v[44:47], v[144:147], v[218:221], v[44:47]
	v_mfma_f32_16x16x32_bf16 v[40:43], v[160:163], v[218:221], v[40:43]
	v_mfma_f32_16x16x32_bf16 v[28:31], v[144:147], v[232:235], v[28:31]
	v_mfma_f32_16x16x32_bf16 v[24:27], v[160:163], v[232:235], v[24:27]
	v_mfma_f32_16x16x32_bf16 v[12:15], v[144:147], v[240:243], v[12:15]
	v_mfma_f32_16x16x32_bf16 v[8:11], v[160:163], v[240:243], v[8:11]
	v_mfma_f32_16x16x32_bf16 v[60:63], v[156:159], v[214:217], v[60:63]
	v_mfma_f32_16x16x32_bf16 v[56:59], v[164:167], v[214:217], v[56:59]
	v_mfma_f32_16x16x32_bf16 v[44:47], v[156:159], v[228:231], v[44:47]
	v_mfma_f32_16x16x32_bf16 v[40:43], v[164:167], v[228:231], v[40:43]
	v_mfma_f32_16x16x32_bf16 v[28:31], v[156:159], v[236:239], v[28:31]
	v_mfma_f32_16x16x32_bf16 v[24:27], v[164:167], v[236:239], v[24:27]
	v_mfma_f32_16x16x32_bf16 v[12:15], v[156:159], v[244:247], v[12:15]
	v_mfma_f32_16x16x32_bf16 v[8:11], v[164:167], v[244:247], v[8:11]
	v_mfma_f32_16x16x32_bf16 v[52:55], v[168:171], v[210:213], v[52:55]
	v_mfma_f32_16x16x32_bf16 v[48:51], v[202:205], v[210:213], v[48:51]
	v_mfma_f32_16x16x32_bf16 v[36:39], v[168:171], v[218:221], v[36:39]
	v_mfma_f32_16x16x32_bf16 v[32:35], v[202:205], v[218:221], v[32:35]
	v_mfma_f32_16x16x32_bf16 v[20:23], v[168:171], v[232:235], v[20:23]
	v_mfma_f32_16x16x32_bf16 v[16:19], v[202:205], v[232:235], v[16:19]
	v_mfma_f32_16x16x32_bf16 v[4:7], v[168:171], v[240:243], v[4:7]
	v_mfma_f32_16x16x32_bf16 v[0:3], v[202:205], v[240:243], v[0:3]
	v_mfma_f32_16x16x32_bf16 v[52:55], v[198:201], v[214:217], v[52:55]
	v_mfma_f32_16x16x32_bf16 v[48:51], v[206:209], v[214:217], v[48:51]
	v_mfma_f32_16x16x32_bf16 v[36:39], v[198:201], v[228:231], v[36:39]
	v_mfma_f32_16x16x32_bf16 v[32:35], v[206:209], v[228:231], v[32:35]
	v_mfma_f32_16x16x32_bf16 v[20:23], v[198:201], v[236:239], v[20:23]
	v_mfma_f32_16x16x32_bf16 v[16:19], v[206:209], v[236:239], v[16:19]
	v_mfma_f32_16x16x32_bf16 v[4:7], v[198:201], v[244:247], v[4:7]
	v_mfma_f32_16x16x32_bf16 v[0:3], v[206:209], v[244:247], v[0:3]
	s_barrier
	s_add_i32 s97, s97, 2
	s_add_u32 s51, s51, 0x100
	s_addc_u32 s64, s64, 0
	s_add_u32 s36, s36, 0x100
	s_addc_u32 s37, s37, 0
	s_cmp_gt_u32 s97, 29
	s_cbranch_scc0 .LBB0_457
	s_and_b64 vcc, exec, s[48:49]
	s_cbranch_vccz .LBB0_460
	s_barrier

; #define PG8_STAGE(bufoff, gbase, voff) do { _Pragma("unroll") for (int _i = 0; _i < 2; ++_i) \
;         __builtin_amdgcn_global_load_lds((const unsigned*)((const char*)(gbase) + (voff)[_i]), (LAS unsigned*)(lds + (bufoff) + ldsw + _i * 8192), 16, 0, 0); } while (0)
; #define PG8_LDA(dst, b, h) do { _Pragma("unroll") for (int m = 0; m < 4; ++m) _Pragma("unroll") for (int k = 0; k < 2; ++k) dst[m][k] = *(const LAS bf16x8*)(lds + PG8_SA(b, h) + aoff + m * 2048 + k * 1024); } while (0)
; #define PG8_LDB(dst, b, h) do { _Pragma("unroll") for (int n = 0; n < 2; ++n) _Pragma("unroll") for (int k = 0; k < 2; ++k) dst[n][k] = *(const LAS bf16x8*)(lds + PG8_SB(b, h) + boff + n * 2048 + k * 1024); } while (0)
; #define PG8_MMA(ai, bj, At, Bt) do { __builtin_amdgcn_s_setprio(1); _Pragma("unroll") for (int m = 0; m < 4; ++m) _Pragma("unroll") for (int n = 0; n < 2; ++n) _Pragma("unroll") for (int k = 0; k < 2; ++k) \
;         acc[ai][bj][m][n] = __builtin_amdgcn_mfma_f32_16x16x32_bf16(Bt[n][k], At[m][k], acc[ai][bj][m][n], 0, 0, 0); __builtin_amdgcn_s_setprio(0); } while (0)
; #define PG8_WAIT_V(n) asm volatile("s_waitcnt vmcnt(" #n ")" ::: "memory")
; #define PG8_WAIT_L(n) asm volatile("s_waitcnt lgkmcnt(" #n ")" ::: "memory")
; #define PG8_BAR __builtin_amdgcn_s_barrier()
; #define PG8_SCHED __builtin_amdgcn_sched_barrier(0)
; template <class Epi>
; __device__ __forceinline__ void gemm_phase(LAS unsigned char* lds, const Sched& S, const int K, const Epi& E) {
;     ...
;         for (int t = 0; t < nt; t += 2) {
;             const bool last = (t == nt - 2);
;             const char* a1 = cA + (size_t)(t + 1) * kstep;
;             const char* a2 = last ? nA : cA + (size_t)(t + 2) * kstep; const char* b2 = last ? nB : cB + (size_t)(t + 2) * kstep;
;             const char* a3 = a2 + kstep; const char* b3 = b2 + kstep;
;             PG8_LDB(B0, 0, 0); PG8_LDB(B1, 0, 1); PG8_SCHED; PG8_LDA(At, 0, 0); PG8_STAGE(PG8_SA(1, 1), a1 + hstepA, voffA);
;             PG8_WAIT_V(8); PG8_WAIT_L(0); PG8_BAR; PG8_MMA(0, 0, At, B0); PG8_MMA(0, 1, At, B1); PG8_BAR; PG8_SCHED;
;             PG8_LDA(At, 0, 1); PG8_STAGE(PG8_SB(0, 0), b2, voffB); PG8_STAGE(PG8_SB(0, 1), b2 + hstepB, voffB); PG8_STAGE(PG8_SA(0, 0), a2, voffA);
;             PG8_WAIT_V(8); PG8_WAIT_L(0); PG8_BAR; PG8_MMA(1, 0, At, B0); PG8_MMA(1, 1, At, B1); PG8_BAR; PG8_SCHED;
.LBB0_477:
	s_add_u32 s50, s48, 0xfff80080
	s_addc_u32 s51, s49, -1
	s_add_i32 s76, 0, 0x10000
	s_cmp_eq_u32 s92, 28
	s_cselect_b32 s53, s45, s51
	s_cselect_b32 s52, s44, s50
	s_cselect_b32 s51, s47, s73
	s_cselect_b32 s50, s46, s72
	s_add_i32 s77, 0, 0x14000
	v_add_u32_e32 v156, s76, v141
	v_add_u32_e32 v194, s77, v141
	ds_read_b128 v[144:147], v156
	ds_read_b128 v[148:151], v156 offset:1024
	ds_read_b128 v[152:155], v156 offset:2048
	ds_read_b128 v[156:159], v156 offset:3072
	ds_read_b128 v[160:163], v194
	ds_read_b128 v[164:167], v194 offset:1024
	ds_read_b128 v[168:171], v194 offset:2048
	ds_read_b128 v[198:201], v194 offset:3072
	v_lshl_add_u64 v[194:195], s[48:49], 0, v[136:137]
	s_add_i32 m0, s57, 0xc000
	ds_read_b128 v[202:205], v143
	ds_read_b128 v[206:209], v143 offset:1024
	ds_read_b128 v[210:213], v143 offset:2048
	ds_read_b128 v[214:217], v143 offset:3072
	ds_read_b128 v[218:221], v143 offset:4096
	ds_read_b128 v[228:231], v143 offset:5120
	ds_read_b128 v[232:235], v143 offset:6144
	ds_read_b128 v[236:239], v143 offset:7168
	global_load_lds_dwordx4 v[194:195], off
	v_lshl_add_u64 v[194:195], s[48:49], 0, v[138:139]
	s_add_i32 m0, s57, 0xe000
	s_nop 0
	global_load_lds_dwordx4 v[194:195], off
	s_waitcnt vmcnt(8)
	s_waitcnt lgkmcnt(0)
	s_barrier
	s_waitcnt lgkmcnt(0)
	v_mfma_f32_16x16x32_bf16 v[124:127], v[144:147], v[202:205], v[124:127]
	v_mfma_f32_16x16x32_bf16 v[120:123], v[152:155], v[202:205], v[120:123]
	v_mfma_f32_16x16x32_bf16 v[112:115], v[144:147], v[210:213], v[112:115]
	v_mfma_f32_16x16x32_bf16 v[104:107], v[152:155], v[210:213], v[104:107]
	v_mfma_f32_16x16x32_bf16 v[96:99], v[144:147], v[218:221], v[96:99]
	v_mfma_f32_16x16x32_bf16 v[88:91], v[152:155], v[218:221], v[88:91]
	v_mfma_f32_16x16x32_bf16 v[80:83], v[144:147], v[232:235], v[80:83]
	v_mfma_f32_16x16x32_bf16 v[72:75], v[152:155], v[232:235], v[72:75]
	v_mfma_f32_16x16x32_bf16 v[124:127], v[148:151], v[206:209], v[124:127]
	v_mfma_f32_16x16x32_bf16 v[120:123], v[156:159], v[206:209], v[120:123]
	v_mfma_f32_16x16x32_bf16 v[112:115], v[148:151], v[214:217], v[112:115]
	v_mfma_f32_16x16x32_bf16 v[104:107], v[156:159], v[214:217], v[104:107]
	v_mfma_f32_16x16x32_bf16 v[96:99], v[148:151], v[228:231], v[96:99]
	v_mfma_f32_16x16x32_bf16 v[88:91], v[156:159], v[228:231], v[88:91]
	v_mfma_f32_16x16x32_bf16 v[80:83], v[148:151], v[236:239], v[80:83]
	v_mfma_f32_16x16x32_bf16 v[72:75], v[156:159], v[236:239], v[72:75]
	v_mfma_f32_16x16x32_bf16 v[116:119], v[160:163], v[202:205], v[116:119]
	v_mfma_f32_16x16x32_bf16 v[108:111], v[168:171], v[202:205], v[108:111]
	v_mfma_f32_16x16x32_bf16 v[100:103], v[160:163], v[210:213], v[100:103]
	v_mfma_f32_16x16x32_bf16 v[92:95], v[168:171], v[210:213], v[92:95]
	v_mfma_f32_16x16x32_bf16 v[84:87], v[160:163], v[218:221], v[84:87]
	v_mfma_f32_16x16x32_bf16 v[76:79], v[168:171], v[218:221], v[76:79]
	v_mfma_f32_16x16x32_bf16 v[68:71], v[160:163], v[232:235], v[68:71]
	v_mfma_f32_16x16x32_bf16 v[64:67], v[168:171], v[232:235], v[64:67]
	v_mfma_f32_16x16x32_bf16 v[116:119], v[164:167], v[206:209], v[116:119]
	v_mfma_f32_16x16x32_bf16 v[108:111], v[198:201], v[206:209], v[108:111]
	v_mfma_f32_16x16x32_bf16 v[100:103], v[164:167], v[214:217], v[100:103]
	v_mfma_f32_16x16x32_bf16 v[92:95], v[198:201], v[214:217], v[92:95]
	v_mfma_f32_16x16x32_bf16 v[84:87], v[164:167], v[228:231], v[84:87]
	v_mfma_f32_16x16x32_bf16 v[76:79], v[198:201], v[228:231], v[76:79]
	v_mfma_f32_16x16x32_bf16 v[68:71], v[164:167], v[236:239], v[68:71]
	v_mfma_f32_16x16x32_bf16 v[64:67], v[198:201], v[236:239], v[64:67]
	s_barrier
	s_add_i32 s76, s76, s55
	v_lshl_add_u64 v[194:195], s[50:51], 0, v[132:133]
	s_mov_b32 m0, s76
	ds_read_b128 v[202:205], v143 offset:16384
	ds_read_b128 v[206:209], v143 offset:17408
	ds_read_b128 v[210:213], v143 offset:18432
	ds_read_b128 v[214:217], v143 offset:19456
	ds_read_b128 v[218:221], v143 offset:20480
	ds_read_b128 v[228:231], v143 offset:21504
	ds_read_b128 v[232:235], v143 offset:22528
	ds_read_b128 v[236:239], v143 offset:23552
	global_load_lds_dwordx4 v[194:195], off
	s_add_i32 m0, s76, 0x2000
	s_add_u32 s96, s50, 0x8000
	v_lshl_add_u64 v[224:225], s[50:51], 0, v[128:129]
	s_addc_u32 s97, s51, 0
	s_add_i32 s76, s77, s55
	global_load_lds_dwordx4 v[224:225], off
	v_lshl_add_u64 v[240:241], s[96:97], 0, v[132:133]
	s_mov_b32 m0, s76
	v_lshl_add_u64 v[242:243], s[52:53], 0, v[130:131]
	global_load_lds_dwordx4 v[240:241], off
	v_lshl_add_u64 v[240:241], s[96:97], 0, v[128:129]
	s_add_i32 m0, s76, 0x2000
	s_nop 0
	global_load_lds_dwordx4 v[240:241], off
	v_lshl_add_u64 v[240:241], s[52:53], 0, v[134:135]
	s_mov_b32 m0, s57
	s_nop 0
	global_load_lds_dwordx4 v[240:241], off
	s_mov_b32 m0, s58
	s_nop 0
	global_load_lds_dwordx4 v[242:243], off
	s_waitcnt vmcnt(8)
	s_waitcnt lgkmcnt(0)
	s_barrier
; #define PG8_STAGE(bufoff, gbase, voff) do { _Pragma("unroll") for (int _i = 0; _i < 2; ++_i) \
;         __builtin_amdgcn_global_load_lds((const unsigned*)((const char*)(gbase) + (voff)[_i]), (LAS unsigned*)(lds + (bufoff) + ldsw + _i * 8192), 16, 0, 0); } while (0)
; #define PG8_LDA(dst, b, h) do { _Pragma("unroll") for (int m = 0; m < 4; ++m) _Pragma("unroll") for (int k = 0; k < 2; ++k) dst[m][k] = *(const LAS bf16x8*)(lds + PG8_SA(b, h) + aoff + m * 2048 + k * 1024); } while (0)
; #define PG8_LDB(dst, b, h) do { _Pragma("unroll") for (int n = 0; n < 2; ++n) _Pragma("unroll") for (int k = 0; k < 2; ++k) dst[n][k] = *(const LAS bf16x8*)(lds + PG8_SB(b, h) + boff + n * 2048 + k * 1024); } while (0)
; #define PG8_MMA(ai, bj, At, Bt) do { __builtin_amdgcn_s_setprio(1); _Pragma("unroll") for (int m = 0; m < 4; ++m) _Pragma("unroll") for (int n = 0; n < 2; ++n) _Pragma("unroll") for (int k = 0; k < 2; ++k) \
;         acc[ai][bj][m][n] = __builtin_amdgcn_mfma_f32_16x16x32_bf16(Bt[n][k], At[m][k], acc[ai][bj][m][n], 0, 0, 0); __builtin_amdgcn_s_setprio(0); } while (0)
; #define PG8_WAIT_V(n) asm volatile("s_waitcnt vmcnt(" #n ")" ::: "memory")
; #define PG8_WAIT_L(n) asm volatile("s_waitcnt lgkmcnt(" #n ")" ::: "memory")
; #define PG8_BAR __builtin_amdgcn_s_barrier()
; #define PG8_SCHED __builtin_amdgcn_sched_barrier(0)
; template <class Epi>
; __device__ __forceinline__ void gemm_phase(LAS unsigned char* lds, const Sched& S, const int K, const Epi& E) {
;     ...
;             PG8_WAIT_V(8); PG8_WAIT_L(0); PG8_BAR; PG8_MMA(1, 0, At, B0); PG8_MMA(1, 1, At, B1); PG8_BAR; PG8_SCHED;
;             PG8_LDB(B0, 1, 0); PG8_LDB(B1, 1, 1); PG8_SCHED; PG8_LDA(At, 1, 0); PG8_STAGE(PG8_SA(0, 1), a2 + hstepA, voffA);
;             PG8_WAIT_V(8); PG8_WAIT_L(0); PG8_BAR; PG8_MMA(0, 0, At, B0); PG8_MMA(0, 1, At, B1); PG8_BAR; PG8_SCHED;
	s_waitcnt lgkmcnt(0)
	v_mfma_f32_16x16x32_bf16 v[60:63], v[144:147], v[202:205], v[60:63]
	v_mfma_f32_16x16x32_bf16 v[56:59], v[152:155], v[202:205], v[56:59]
	v_mfma_f32_16x16x32_bf16 v[48:51], v[144:147], v[210:213], v[48:51]
	v_mfma_f32_16x16x32_bf16 v[40:43], v[152:155], v[210:213], v[40:43]
	v_mfma_f32_16x16x32_bf16 v[32:35], v[144:147], v[218:221], v[32:35]
	v_mfma_f32_16x16x32_bf16 v[24:27], v[152:155], v[218:221], v[24:27]
	v_mfma_f32_16x16x32_bf16 v[16:19], v[144:147], v[232:235], v[16:19]
	v_mfma_f32_16x16x32_bf16 v[8:11], v[152:155], v[232:235], v[8:11]
	v_mfma_f32_16x16x32_bf16 v[60:63], v[148:151], v[206:209], v[60:63]
	v_mfma_f32_16x16x32_bf16 v[56:59], v[156:159], v[206:209], v[56:59]
	v_mfma_f32_16x16x32_bf16 v[48:51], v[148:151], v[214:217], v[48:51]
	v_mfma_f32_16x16x32_bf16 v[40:43], v[156:159], v[214:217], v[40:43]
	v_mfma_f32_16x16x32_bf16 v[32:35], v[148:151], v[228:231], v[32:35]
	v_mfma_f32_16x16x32_bf16 v[24:27], v[156:159], v[228:231], v[24:27]
	v_mfma_f32_16x16x32_bf16 v[16:19], v[148:151], v[236:239], v[16:19]
	v_mfma_f32_16x16x32_bf16 v[8:11], v[156:159], v[236:239], v[8:11]
	v_mfma_f32_16x16x32_bf16 v[52:55], v[160:163], v[202:205], v[52:55]
	v_mfma_f32_16x16x32_bf16 v[44:47], v[168:171], v[202:205], v[44:47]
	v_mfma_f32_16x16x32_bf16 v[36:39], v[160:163], v[210:213], v[36:39]
	v_mfma_f32_16x16x32_bf16 v[28:31], v[168:171], v[210:213], v[28:31]
	v_mfma_f32_16x16x32_bf16 v[20:23], v[160:163], v[218:221], v[20:23]
	v_mfma_f32_16x16x32_bf16 v[12:15], v[168:171], v[218:221], v[12:15]
	v_mfma_f32_16x16x32_bf16 v[4:7], v[160:163], v[232:235], v[4:7]
	v_mfma_f32_16x16x32_bf16 v[0:3], v[168:171], v[232:235], v[0:3]
	v_mfma_f32_16x16x32_bf16 v[52:55], v[164:167], v[206:209], v[52:55]
	v_mfma_f32_16x16x32_bf16 v[44:47], v[198:201], v[206:209], v[44:47]
	v_mfma_f32_16x16x32_bf16 v[36:39], v[164:167], v[214:217], v[36:39]
	v_mfma_f32_16x16x32_bf16 v[28:31], v[198:201], v[214:217], v[28:31]
	v_mfma_f32_16x16x32_bf16 v[20:23], v[164:167], v[228:231], v[20:23]
	v_mfma_f32_16x16x32_bf16 v[12:15], v[198:201], v[228:231], v[12:15]
	v_mfma_f32_16x16x32_bf16 v[4:7], v[164:167], v[236:239], v[4:7]
	v_mfma_f32_16x16x32_bf16 v[0:3], v[198:201], v[236:239], v[0:3]
	s_barrier
	s_add_i32 s76, 0, 0x18000
	s_add_i32 s77, 0, 0x1c000
	v_add_u32_e32 v156, s76, v141
	v_add_u32_e32 v198, s77, v141
	ds_read_b128 v[144:147], v156
	ds_read_b128 v[148:151], v156 offset:1024
	ds_read_b128 v[152:155], v156 offset:2048
	ds_read_b128 v[156:159], v156 offset:3072
	ds_read_b128 v[160:163], v198
	ds_read_b128 v[164:167], v198 offset:1024
	ds_read_b128 v[168:171], v198 offset:2048
	ds_read_b128 v[198:201], v198 offset:3072
	s_add_u32 s52, s52, 0x80000
	s_addc_u32 s53, s53, 0
	s_mov_b32 m0, s59
	v_lshl_add_u64 v[244:245], s[52:53], 0, v[134:135]
	ds_read_b128 v[202:205], v143 offset:32768
	ds_read_b128 v[206:209], v143 offset:33792
	ds_read_b128 v[210:213], v143 offset:34816
	ds_read_b128 v[214:217], v143 offset:35840
	ds_read_b128 v[218:221], v143 offset:36864
	ds_read_b128 v[228:231], v143 offset:37888
	ds_read_b128 v[232:235], v143 offset:38912
	ds_read_b128 v[236:239], v143 offset:39936
	global_load_lds_dwordx4 v[244:245], off
	v_lshl_add_u64 v[244:245], s[52:53], 0, v[130:131]
	s_mov_b32 m0, s60
	s_nop 0
	global_load_lds_dwordx4 v[244:245], off
	s_waitcnt vmcnt(8)
	s_waitcnt lgkmcnt(0)
	s_barrier
	s_waitcnt lgkmcnt(0)
	v_mfma_f32_16x16x32_bf16 v[124:127], v[144:147], v[202:205], v[124:127]
	v_mfma_f32_16x16x32_bf16 v[120:123], v[152:155], v[202:205], v[120:123]
	v_mfma_f32_16x16x32_bf16 v[112:115], v[144:147], v[210:213], v[112:115]
	v_mfma_f32_16x16x32_bf16 v[104:107], v[152:155], v[210:213], v[104:107]
	v_mfma_f32_16x16x32_bf16 v[96:99], v[144:147], v[218:221], v[96:99]
	v_mfma_f32_16x16x32_bf16 v[88:91], v[152:155], v[218:221], v[88:91]
	v_mfma_f32_16x16x32_bf16 v[80:83], v[144:147], v[232:235], v[80:83]
	v_mfma_f32_16x16x32_bf16 v[72:75], v[152:155], v[232:235], v[72:75]
	v_mfma_f32_16x16x32_bf16 v[124:127], v[148:151], v[206:209], v[124:127]
	v_mfma_f32_16x16x32_bf16 v[120:123], v[156:159], v[206:209], v[120:123]
	v_mfma_f32_16x16x32_bf16 v[112:115], v[148:151], v[214:217], v[112:115]
	v_mfma_f32_16x16x32_bf16 v[104:107], v[156:159], v[214:217], v[104:107]
	v_mfma_f32_16x16x32_bf16 v[96:99], v[148:151], v[228:231], v[96:99]
	v_mfma_f32_16x16x32_bf16 v[88:91], v[156:159], v[228:231], v[88:91]
	v_mfma_f32_16x16x32_bf16 v[80:83], v[148:151], v[236:239], v[80:83]
	v_mfma_f32_16x16x32_bf16 v[72:75], v[156:159], v[236:239], v[72:75]
	v_mfma_f32_16x16x32_bf16 v[116:119], v[160:163], v[202:205], v[116:119]
	v_mfma_f32_16x16x32_bf16 v[108:111], v[168:171], v[202:205], v[108:111]
	v_mfma_f32_16x16x32_bf16 v[100:103], v[160:163], v[210:213], v[100:103]
	v_mfma_f32_16x16x32_bf16 v[92:95], v[168:171], v[210:213], v[92:95]
	v_mfma_f32_16x16x32_bf16 v[84:87], v[160:163], v[218:221], v[84:87]
	v_mfma_f32_16x16x32_bf16 v[76:79], v[168:171], v[218:221], v[76:79]
	v_mfma_f32_16x16x32_bf16 v[68:71], v[160:163], v[232:235], v[68:71]
	v_mfma_f32_16x16x32_bf16 v[64:67], v[168:171], v[232:235], v[64:67]
	v_mfma_f32_16x16x32_bf16 v[116:119], v[164:167], v[206:209], v[116:119]
	v_mfma_f32_16x16x32_bf16 v[108:111], v[198:201], v[206:209], v[108:111]
	v_mfma_f32_16x16x32_bf16 v[100:103], v[164:167], v[214:217], v[100:103]
	v_mfma_f32_16x16x32_bf16 v[92:95], v[198:201], v[214:217], v[92:95]
	v_mfma_f32_16x16x32_bf16 v[84:87], v[164:167], v[228:231], v[84:87]
	v_mfma_f32_16x16x32_bf16 v[76:79], v[198:201], v[228:231], v[76:79]
	v_mfma_f32_16x16x32_bf16 v[68:71], v[164:167], v[236:239], v[68:71]
	v_mfma_f32_16x16x32_bf16 v[64:67], v[198:201], v[236:239], v[64:67]
	s_barrier
; #define PG8_STAGE(bufoff, gbase, voff) do { _Pragma("unroll") for (int _i = 0; _i < 2; ++_i) \
;         __builtin_amdgcn_global_load_lds((const unsigned*)((const char*)(gbase) + (voff)[_i]), (LAS unsigned*)(lds + (bufoff) + ldsw + _i * 8192), 16, 0, 0); } while (0)
; #define PG8_LDA(dst, b, h) do { _Pragma("unroll") for (int m = 0; m < 4; ++m) _Pragma("unroll") for (int k = 0; k < 2; ++k) dst[m][k] = *(const LAS bf16x8*)(lds + PG8_SA(b, h) + aoff + m * 2048 + k * 1024); } while (0)
; #define PG8_MMA(ai, bj, At, Bt) do { __builtin_amdgcn_s_setprio(1); _Pragma("unroll") for (int m = 0; m < 4; ++m) _Pragma("unroll") for (int n = 0; n < 2; ++n) _Pragma("unroll") for (int k = 0; k < 2; ++k) \
;         acc[ai][bj][m][n] = __builtin_amdgcn_mfma_f32_16x16x32_bf16(Bt[n][k], At[m][k], acc[ai][bj][m][n], 0, 0, 0); __builtin_amdgcn_s_setprio(0); } while (0)
; #define PG8_WAIT_V(n) asm volatile("s_waitcnt vmcnt(" #n ")" ::: "memory")
; #define PG8_WAIT_L(n) asm volatile("s_waitcnt lgkmcnt(" #n ")" ::: "memory")
; #define PG8_BAR __builtin_amdgcn_s_barrier()
; #define PG8_SCHED __builtin_amdgcn_sched_barrier(0)
; template <class Epi>
; __device__ __forceinline__ void gemm_phase(LAS unsigned char* lds, const Sched& S, const int K, const Epi& E) {
;     ...
;             PG8_LDA(At, 1, 1); PG8_STAGE(PG8_SB(1, 0), b3, voffB); PG8_STAGE(PG8_SB(1, 1), b3 + hstepB, voffB); PG8_STAGE(PG8_SA(1, 0), a3, voffA);
;             PG8_WAIT_V(8); PG8_WAIT_L(0); PG8_BAR; PG8_MMA(1, 0, At, B0); PG8_MMA(1, 1, At, B1); PG8_BAR; PG8_SCHED;
;         }
;         if (wr == 0) PG8_BAR;
	s_add_i32 s52, s76, s55
	v_lshl_add_u64 v[194:195], v[194:195], 0, s[74:75]
	s_mov_b32 m0, s52
	ds_read_b128 v[202:205], v143 offset:49152
	ds_read_b128 v[206:209], v143 offset:50176
	ds_read_b128 v[210:213], v143 offset:51200
	ds_read_b128 v[214:217], v143 offset:52224
	ds_read_b128 v[218:221], v143 offset:53248
	ds_read_b128 v[228:231], v143 offset:54272
	ds_read_b128 v[232:235], v143 offset:55296
	ds_read_b128 v[236:239], v143 offset:56320
	global_load_lds_dwordx4 v[194:195], off
	s_add_i32 m0, s52, 0x2000
	s_add_u32 s50, s50, 0x8080
	v_lshl_add_u64 v[194:195], v[224:225], 0, s[74:75]
	s_addc_u32 s51, s51, 0
	s_add_i32 s52, s77, s55
	global_load_lds_dwordx4 v[194:195], off
	v_lshl_add_u64 v[194:195], s[50:51], 0, v[132:133]
	s_mov_b32 m0, s52
	s_nop 0
	global_load_lds_dwordx4 v[194:195], off
	v_lshl_add_u64 v[194:195], s[50:51], 0, v[128:129]
	s_add_i32 m0, s52, 0x2000
	s_nop 0
	global_load_lds_dwordx4 v[194:195], off
	v_lshl_add_u64 v[194:195], v[240:241], 0, s[74:75]
	s_mov_b32 m0, s66
	s_nop 0
	global_load_lds_dwordx4 v[194:195], off
	v_lshl_add_u64 v[194:195], v[242:243], 0, s[74:75]
	s_mov_b32 m0, s67
	s_nop 0
	global_load_lds_dwordx4 v[194:195], off
	s_waitcnt vmcnt(8)
	s_waitcnt lgkmcnt(0)
	s_barrier
	s_waitcnt lgkmcnt(0)
	v_mfma_f32_16x16x32_bf16 v[60:63], v[144:147], v[202:205], v[60:63]
	v_mfma_f32_16x16x32_bf16 v[56:59], v[152:155], v[202:205], v[56:59]
	v_mfma_f32_16x16x32_bf16 v[48:51], v[144:147], v[210:213], v[48:51]
	v_mfma_f32_16x16x32_bf16 v[40:43], v[152:155], v[210:213], v[40:43]
	v_mfma_f32_16x16x32_bf16 v[32:35], v[144:147], v[218:221], v[32:35]
	v_mfma_f32_16x16x32_bf16 v[24:27], v[152:155], v[218:221], v[24:27]
	v_mfma_f32_16x16x32_bf16 v[16:19], v[144:147], v[232:235], v[16:19]
	v_mfma_f32_16x16x32_bf16 v[8:11], v[152:155], v[232:235], v[8:11]
	v_mfma_f32_16x16x32_bf16 v[60:63], v[148:151], v[206:209], v[60:63]
	v_mfma_f32_16x16x32_bf16 v[56:59], v[156:159], v[206:209], v[56:59]
	v_mfma_f32_16x16x32_bf16 v[48:51], v[148:151], v[214:217], v[48:51]
	v_mfma_f32_16x16x32_bf16 v[40:43], v[156:159], v[214:217], v[40:43]
	v_mfma_f32_16x16x32_bf16 v[32:35], v[148:151], v[228:231], v[32:35]
	v_mfma_f32_16x16x32_bf16 v[24:27], v[156:159], v[228:231], v[24:27]
	v_mfma_f32_16x16x32_bf16 v[16:19], v[148:151], v[236:239], v[16:19]
	v_mfma_f32_16x16x32_bf16 v[8:11], v[156:159], v[236:239], v[8:11]
	v_mfma_f32_16x16x32_bf16 v[52:55], v[160:163], v[202:205], v[52:55]
	v_mfma_f32_16x16x32_bf16 v[44:47], v[168:171], v[202:205], v[44:47]
	v_mfma_f32_16x16x32_bf16 v[36:39], v[160:163], v[210:213], v[36:39]
	v_mfma_f32_16x16x32_bf16 v[28:31], v[168:171], v[210:213], v[28:31]
	v_mfma_f32_16x16x32_bf16 v[20:23], v[160:163], v[218:221], v[20:23]
	v_mfma_f32_16x16x32_bf16 v[12:15], v[168:171], v[218:221], v[12:15]
	v_mfma_f32_16x16x32_bf16 v[4:7], v[160:163], v[232:235], v[4:7]
	v_mfma_f32_16x16x32_bf16 v[0:3], v[168:171], v[232:235], v[0:3]
	v_mfma_f32_16x16x32_bf16 v[52:55], v[164:167], v[206:209], v[52:55]
	v_mfma_f32_16x16x32_bf16 v[44:47], v[198:201], v[206:209], v[44:47]
	v_mfma_f32_16x16x32_bf16 v[36:39], v[164:167], v[214:217], v[36:39]
	v_mfma_f32_16x16x32_bf16 v[28:31], v[198:201], v[214:217], v[28:31]
	v_mfma_f32_16x16x32_bf16 v[20:23], v[164:167], v[228:231], v[20:23]
	v_mfma_f32_16x16x32_bf16 v[12:15], v[198:201], v[228:231], v[12:15]
	v_mfma_f32_16x16x32_bf16 v[4:7], v[164:167], v[236:239], v[4:7]
	v_mfma_f32_16x16x32_bf16 v[0:3], v[198:201], v[236:239], v[0:3]
	s_barrier
	s_add_i32 s92, s92, 2
	s_add_u32 s72, s72, 0x100
	s_addc_u32 s73, s73, 0
	s_add_u32 s48, s48, 0x100
	s_addc_u32 s49, s49, 0
	s_cmp_gt_u32 s92, 29
	s_cbranch_scc0 .LBB0_477
	s_and_b64 vcc, exec, s[36:37]
	s_cbranch_vccz .LBB0_480
	s_barrier

; #define PG8_STAGE(bufoff, gbase, voff) do { _Pragma("unroll") for (int _i = 0; _i < 2; ++_i) \
;         __builtin_amdgcn_global_load_lds((const unsigned*)((const char*)(gbase) + (voff)[_i]), (LAS unsigned*)(lds + (bufoff) + ldsw + _i * 8192), 16, 0, 0); } while (0)
; #define PG8_LDA(dst, b, h) do { _Pragma("unroll") for (int m = 0; m < 4; ++m) _Pragma("unroll") for (int k = 0; k < 2; ++k) dst[m][k] = *(const LAS bf16x8*)(lds + PG8_SA(b, h) + aoff + m * 2048 + k * 1024); } while (0)
; #define PG8_LDB(dst, b, h) do { _Pragma("unroll") for (int n = 0; n < 2; ++n) _Pragma("unroll") for (int k = 0; k < 2; ++k) dst[n][k] = *(const LAS bf16x8*)(lds + PG8_SB(b, h) + boff + n * 2048 + k * 1024); } while (0)
; #define PG8_MMA(ai, bj, At, Bt) do { __builtin_amdgcn_s_setprio(1); _Pragma("unroll") for (int m = 0; m < 4; ++m) _Pragma("unroll") for (int n = 0; n < 2; ++n) _Pragma("unroll") for (int k = 0; k < 2; ++k) \
;         acc[ai][bj][m][n] = __builtin_amdgcn_mfma_f32_16x16x32_bf16(Bt[n][k], At[m][k], acc[ai][bj][m][n], 0, 0, 0); __builtin_amdgcn_s_setprio(0); } while (0)
; #define PG8_WAIT_V(n) asm volatile("s_waitcnt vmcnt(" #n ")" ::: "memory")
; #define PG8_WAIT_L(n) asm volatile("s_waitcnt lgkmcnt(" #n ")" ::: "memory")
; #define PG8_BAR __builtin_amdgcn_s_barrier()
; #define PG8_SCHED __builtin_amdgcn_sched_barrier(0)
; template <class Epi>
; __device__ __forceinline__ void gemm_phase(LAS unsigned char* lds, const Sched& S, const int K, const Epi& E) {
;     ...
;         for (int t = 0; t < nt; t += 2) {
;             const bool last = (t == nt - 2);
;             const char* a1 = cA + (size_t)(t + 1) * kstep;
;             const char* a2 = last ? nA : cA + (size_t)(t + 2) * kstep; const char* b2 = last ? nB : cB + (size_t)(t + 2) * kstep;
;             const char* a3 = a2 + kstep; const char* b3 = b2 + kstep;
;             PG8_LDB(B0, 0, 0); PG8_LDB(B1, 0, 1); PG8_SCHED; PG8_LDA(At, 0, 0); PG8_STAGE(PG8_SA(1, 1), a1 + hstepA, voffA);
;             PG8_WAIT_V(8); PG8_WAIT_L(0); PG8_BAR; PG8_MMA(0, 0, At, B0); PG8_MMA(0, 1, At, B1); PG8_BAR; PG8_SCHED;
;             PG8_LDA(At, 0, 1); PG8_STAGE(PG8_SB(0, 0), b2, voffB); PG8_STAGE(PG8_SB(0, 1), b2 + hstepB, voffB); PG8_STAGE(PG8_SA(0, 0), a2, voffA);
;             PG8_WAIT_V(8); PG8_WAIT_L(0); PG8_BAR; PG8_MMA(1, 0, At, B0); PG8_MMA(1, 1, At, B1); PG8_BAR; PG8_SCHED;
.LBB0_582:
	s_add_u32 s58, s54, 0x100
	s_addc_u32 s59, s55, 0
	s_add_i32 s76, 0, 0x10000
	s_cmp_eq_u32 s73, 4
	s_cselect_b32 vcc_hi, s51, s59
	s_cselect_b32 vcc_lo, s50, s58
	v_add_u32_e32 v145, s76, v143
	s_cselect_b32 s93, s53, s72
	s_cselect_b32 s92, s52, s36
	s_add_i32 s77, 0, 0x14000
	ds_read_b128 v[146:149], v145
	ds_read_b128 v[150:153], v145 offset:1024
	ds_read_b128 v[154:157], v145 offset:2048
	ds_read_b128 v[158:161], v145 offset:3072
	v_add_u32_e32 v145, s77, v143
	ds_read_b128 v[162:165], v145
	ds_read_b128 v[166:169], v145 offset:1024
	ds_read_b128 v[198:201], v145 offset:2048
	ds_read_b128 v[202:205], v145 offset:3072
	v_lshl_add_u64 v[170:171], s[54:55], 0, v[138:139]
	s_add_i32 m0, s60, 0xc000
	ds_read_b128 v[206:209], v144
	ds_read_b128 v[210:213], v144 offset:1024
	ds_read_b128 v[214:217], v144 offset:2048
	ds_read_b128 v[218:221], v144 offset:3072
	ds_read_b128 v[228:231], v144 offset:4096
	ds_read_b128 v[232:235], v144 offset:5120
	ds_read_b128 v[236:239], v144 offset:6144
	ds_read_b128 v[240:243], v144 offset:7168
	global_load_lds_dwordx4 v[170:171], off
	v_lshl_add_u64 v[170:171], s[54:55], 0, v[140:141]
	s_add_i32 m0, s60, 0xe000
	s_nop 0
	global_load_lds_dwordx4 v[170:171], off
	s_waitcnt vmcnt(8)
	s_waitcnt lgkmcnt(0)
	s_barrier
	s_waitcnt lgkmcnt(0)
	v_mfma_f32_16x16x32_bf16 v[124:127], v[146:149], v[206:209], v[124:127]
	v_mfma_f32_16x16x32_bf16 v[120:123], v[154:157], v[206:209], v[120:123]
	v_mfma_f32_16x16x32_bf16 v[116:119], v[146:149], v[214:217], v[116:119]
	v_mfma_f32_16x16x32_bf16 v[112:115], v[154:157], v[214:217], v[112:115]
	v_mfma_f32_16x16x32_bf16 v[108:111], v[146:149], v[228:231], v[108:111]
	v_mfma_f32_16x16x32_bf16 v[100:103], v[154:157], v[228:231], v[100:103]
	v_mfma_f32_16x16x32_bf16 v[92:95], v[146:149], v[236:239], v[92:95]
	v_mfma_f32_16x16x32_bf16 v[84:87], v[154:157], v[236:239], v[84:87]
	v_mfma_f32_16x16x32_bf16 v[124:127], v[150:153], v[210:213], v[124:127]
	v_mfma_f32_16x16x32_bf16 v[120:123], v[158:161], v[210:213], v[120:123]
	v_mfma_f32_16x16x32_bf16 v[116:119], v[150:153], v[218:221], v[116:119]
	v_mfma_f32_16x16x32_bf16 v[112:115], v[158:161], v[218:221], v[112:115]
	v_mfma_f32_16x16x32_bf16 v[108:111], v[150:153], v[232:235], v[108:111]
	v_mfma_f32_16x16x32_bf16 v[100:103], v[158:161], v[232:235], v[100:103]
	v_mfma_f32_16x16x32_bf16 v[92:95], v[150:153], v[240:243], v[92:95]
	v_mfma_f32_16x16x32_bf16 v[84:87], v[158:161], v[240:243], v[84:87]
	v_mfma_f32_16x16x32_bf16 v[104:107], v[162:165], v[206:209], v[104:107]
	v_mfma_f32_16x16x32_bf16 v[96:99], v[198:201], v[206:209], v[96:99]
	v_mfma_f32_16x16x32_bf16 v[88:91], v[162:165], v[214:217], v[88:91]
	v_mfma_f32_16x16x32_bf16 v[80:83], v[198:201], v[214:217], v[80:83]
	v_mfma_f32_16x16x32_bf16 v[76:79], v[162:165], v[228:231], v[76:79]
	v_mfma_f32_16x16x32_bf16 v[72:75], v[198:201], v[228:231], v[72:75]
	v_mfma_f32_16x16x32_bf16 v[68:71], v[162:165], v[236:239], v[68:71]
	v_mfma_f32_16x16x32_bf16 v[64:67], v[198:201], v[236:239], v[64:67]
	v_mfma_f32_16x16x32_bf16 v[104:107], v[166:169], v[210:213], v[104:107]
	v_mfma_f32_16x16x32_bf16 v[96:99], v[202:205], v[210:213], v[96:99]
	v_mfma_f32_16x16x32_bf16 v[88:91], v[166:169], v[218:221], v[88:91]
	v_mfma_f32_16x16x32_bf16 v[80:83], v[202:205], v[218:221], v[80:83]
	v_mfma_f32_16x16x32_bf16 v[76:79], v[166:169], v[232:235], v[76:79]
	v_mfma_f32_16x16x32_bf16 v[72:75], v[202:205], v[232:235], v[72:75]
	v_mfma_f32_16x16x32_bf16 v[68:71], v[166:169], v[240:243], v[68:71]
	v_mfma_f32_16x16x32_bf16 v[64:67], v[202:205], v[240:243], v[64:67]
	s_barrier
	s_add_i32 s54, s76, s57
	v_lshl_add_u64 v[170:171], s[92:93], 0, v[132:133]
	s_mov_b32 m0, s54
	ds_read_b128 v[206:209], v144 offset:16384
	ds_read_b128 v[210:213], v144 offset:17408
	ds_read_b128 v[214:217], v144 offset:18432
	ds_read_b128 v[218:221], v144 offset:19456
	ds_read_b128 v[228:231], v144 offset:20480
	ds_read_b128 v[232:235], v144 offset:21504
	ds_read_b128 v[236:239], v144 offset:22528
	ds_read_b128 v[240:243], v144 offset:23552
	global_load_lds_dwordx4 v[170:171], off
	s_add_i32 m0, s54, 0x2000
	s_add_u32 s54, s92, 0x20000
	v_lshl_add_u64 v[194:195], s[92:93], 0, v[128:129]
	s_addc_u32 s55, s93, 0
	s_add_i32 s76, s77, s57
	global_load_lds_dwordx4 v[194:195], off
	v_lshl_add_u64 v[224:225], s[54:55], 0, v[132:133]
	s_mov_b32 m0, s76
	v_lshl_add_u64 v[244:245], vcc, 0, v[130:131]
	global_load_lds_dwordx4 v[224:225], off
	v_lshl_add_u64 v[224:225], s[54:55], 0, v[128:129]
	s_add_i32 m0, s76, 0x2000
	s_nop 0
	global_load_lds_dwordx4 v[224:225], off
	v_lshl_add_u64 v[224:225], vcc, 0, v[134:135]
	s_mov_b32 m0, s60
	s_nop 0
	global_load_lds_dwordx4 v[224:225], off
	s_mov_b32 m0, s61
	s_nop 0
	global_load_lds_dwordx4 v[244:245], off
	s_waitcnt vmcnt(8)
	s_waitcnt lgkmcnt(0)
	s_barrier
; #define PG8_STAGE(bufoff, gbase, voff) do { _Pragma("unroll") for (int _i = 0; _i < 2; ++_i) \
;         __builtin_amdgcn_global_load_lds((const unsigned*)((const char*)(gbase) + (voff)[_i]), (LAS unsigned*)(lds + (bufoff) + ldsw + _i * 8192), 16, 0, 0); } while (0)
; #define PG8_LDA(dst, b, h) do { _Pragma("unroll") for (int m = 0; m < 4; ++m) _Pragma("unroll") for (int k = 0; k < 2; ++k) dst[m][k] = *(const LAS bf16x8*)(lds + PG8_SA(b, h) + aoff + m * 2048 + k * 1024); } while (0)
; #define PG8_LDB(dst, b, h) do { _Pragma("unroll") for (int n = 0; n < 2; ++n) _Pragma("unroll") for (int k = 0; k < 2; ++k) dst[n][k] = *(const LAS bf16x8*)(lds + PG8_SB(b, h) + boff + n * 2048 + k * 1024); } while (0)
; #define PG8_MMA(ai, bj, At, Bt) do { __builtin_amdgcn_s_setprio(1); _Pragma("unroll") for (int m = 0; m < 4; ++m) _Pragma("unroll") for (int n = 0; n < 2; ++n) _Pragma("unroll") for (int k = 0; k < 2; ++k) \
;         acc[ai][bj][m][n] = __builtin_amdgcn_mfma_f32_16x16x32_bf16(Bt[n][k], At[m][k], acc[ai][bj][m][n], 0, 0, 0); __builtin_amdgcn_s_setprio(0); } while (0)
; #define PG8_WAIT_V(n) asm volatile("s_waitcnt vmcnt(" #n ")" ::: "memory")
; #define PG8_WAIT_L(n) asm volatile("s_waitcnt lgkmcnt(" #n ")" ::: "memory")
; #define PG8_BAR __builtin_amdgcn_s_barrier()
; #define PG8_SCHED __builtin_amdgcn_sched_barrier(0)
; template <class Epi>
; __device__ __forceinline__ void gemm_phase(LAS unsigned char* lds, const Sched& S, const int K, const Epi& E) {
;     ...
;             PG8_WAIT_V(8); PG8_WAIT_L(0); PG8_BAR; PG8_MMA(1, 0, At, B0); PG8_MMA(1, 1, At, B1); PG8_BAR; PG8_SCHED;
;             PG8_LDB(B0, 1, 0); PG8_LDB(B1, 1, 1); PG8_SCHED; PG8_LDA(At, 1, 0); PG8_STAGE(PG8_SA(0, 1), a2 + hstepA, voffA);
;             PG8_WAIT_V(8); PG8_WAIT_L(0); PG8_BAR; PG8_MMA(0, 0, At, B0); PG8_MMA(0, 1, At, B1); PG8_BAR; PG8_SCHED;
	s_waitcnt lgkmcnt(0)
	v_mfma_f32_16x16x32_bf16 v[60:63], v[146:149], v[206:209], v[60:63]
	v_mfma_f32_16x16x32_bf16 v[56:59], v[154:157], v[206:209], v[56:59]
	v_mfma_f32_16x16x32_bf16 v[52:55], v[146:149], v[214:217], v[52:55]
	v_mfma_f32_16x16x32_bf16 v[48:51], v[154:157], v[214:217], v[48:51]
	v_mfma_f32_16x16x32_bf16 v[36:39], v[146:149], v[228:231], v[36:39]
	v_mfma_f32_16x16x32_bf16 v[32:35], v[154:157], v[228:231], v[32:35]
	v_mfma_f32_16x16x32_bf16 v[20:23], v[146:149], v[236:239], v[20:23]
	v_mfma_f32_16x16x32_bf16 v[16:19], v[154:157], v[236:239], v[16:19]
	v_mfma_f32_16x16x32_bf16 v[60:63], v[150:153], v[210:213], v[60:63]
	v_mfma_f32_16x16x32_bf16 v[56:59], v[158:161], v[210:213], v[56:59]
	v_mfma_f32_16x16x32_bf16 v[52:55], v[150:153], v[218:221], v[52:55]
	v_mfma_f32_16x16x32_bf16 v[48:51], v[158:161], v[218:221], v[48:51]
	v_mfma_f32_16x16x32_bf16 v[36:39], v[150:153], v[232:235], v[36:39]
	v_mfma_f32_16x16x32_bf16 v[32:35], v[158:161], v[232:235], v[32:35]
	v_mfma_f32_16x16x32_bf16 v[20:23], v[150:153], v[240:243], v[20:23]
	v_mfma_f32_16x16x32_bf16 v[16:19], v[158:161], v[240:243], v[16:19]
	v_mfma_f32_16x16x32_bf16 v[44:47], v[162:165], v[206:209], v[44:47]
	v_mfma_f32_16x16x32_bf16 v[40:43], v[198:201], v[206:209], v[40:43]
	v_mfma_f32_16x16x32_bf16 v[28:31], v[162:165], v[214:217], v[28:31]
	v_mfma_f32_16x16x32_bf16 v[24:27], v[198:201], v[214:217], v[24:27]
	v_mfma_f32_16x16x32_bf16 v[12:15], v[162:165], v[228:231], v[12:15]
	v_mfma_f32_16x16x32_bf16 v[8:11], v[198:201], v[228:231], v[8:11]
	v_mfma_f32_16x16x32_bf16 v[4:7], v[162:165], v[236:239], v[4:7]
	v_mfma_f32_16x16x32_bf16 v[0:3], v[198:201], v[236:239], v[0:3]
	v_mfma_f32_16x16x32_bf16 v[44:47], v[166:169], v[210:213], v[44:47]
	v_mfma_f32_16x16x32_bf16 v[40:43], v[202:205], v[210:213], v[40:43]
	v_mfma_f32_16x16x32_bf16 v[28:31], v[166:169], v[218:221], v[28:31]
	v_mfma_f32_16x16x32_bf16 v[24:27], v[202:205], v[218:221], v[24:27]
	v_mfma_f32_16x16x32_bf16 v[12:15], v[166:169], v[232:235], v[12:15]
	v_mfma_f32_16x16x32_bf16 v[8:11], v[202:205], v[232:235], v[8:11]
	v_mfma_f32_16x16x32_bf16 v[4:7], v[166:169], v[240:243], v[4:7]
	v_mfma_f32_16x16x32_bf16 v[0:3], v[202:205], v[240:243], v[0:3]
	s_barrier
	s_add_i32 s76, 0, 0x18000
	v_add_u32_e32 v145, s76, v143
	s_add_i32 s77, 0, 0x1c000
	ds_read_b128 v[146:149], v145
	ds_read_b128 v[150:153], v145 offset:1024
	ds_read_b128 v[154:157], v145 offset:2048
	ds_read_b128 v[158:161], v145 offset:3072
	v_add_u32_e32 v145, s77, v143
	ds_read_b128 v[162:165], v145
	ds_read_b128 v[166:169], v145 offset:1024
	ds_read_b128 v[198:201], v145 offset:2048
	ds_read_b128 v[202:205], v145 offset:3072
	s_add_u32 s54, vcc_lo, 0x30000
	s_addc_u32 s55, vcc_hi, 0
	s_mov_b32 m0, s63
	v_lshl_add_u64 v[246:247], s[54:55], 0, v[134:135]
	ds_read_b128 v[206:209], v144 offset:32768
	ds_read_b128 v[210:213], v144 offset:33792
	ds_read_b128 v[214:217], v144 offset:34816
	ds_read_b128 v[218:221], v144 offset:35840
	ds_read_b128 v[228:231], v144 offset:36864
	ds_read_b128 v[232:235], v144 offset:37888
	ds_read_b128 v[236:239], v144 offset:38912
	ds_read_b128 v[240:243], v144 offset:39936
	global_load_lds_dwordx4 v[246:247], off
	v_lshl_add_u64 v[246:247], s[54:55], 0, v[130:131]
	s_mov_b32 m0, s67
	s_nop 0
	global_load_lds_dwordx4 v[246:247], off
	s_waitcnt vmcnt(8)
	s_waitcnt lgkmcnt(0)
	s_barrier
	s_waitcnt lgkmcnt(0)
	v_mfma_f32_16x16x32_bf16 v[124:127], v[146:149], v[206:209], v[124:127]
	v_mfma_f32_16x16x32_bf16 v[120:123], v[154:157], v[206:209], v[120:123]
	v_mfma_f32_16x16x32_bf16 v[116:119], v[146:149], v[214:217], v[116:119]
	v_mfma_f32_16x16x32_bf16 v[112:115], v[154:157], v[214:217], v[112:115]
	v_mfma_f32_16x16x32_bf16 v[108:111], v[146:149], v[228:231], v[108:111]
	v_mfma_f32_16x16x32_bf16 v[100:103], v[154:157], v[228:231], v[100:103]
	v_mfma_f32_16x16x32_bf16 v[92:95], v[146:149], v[236:239], v[92:95]
	v_mfma_f32_16x16x32_bf16 v[84:87], v[154:157], v[236:239], v[84:87]
	v_mfma_f32_16x16x32_bf16 v[124:127], v[150:153], v[210:213], v[124:127]
	v_mfma_f32_16x16x32_bf16 v[120:123], v[158:161], v[210:213], v[120:123]
	v_mfma_f32_16x16x32_bf16 v[116:119], v[150:153], v[218:221], v[116:119]
	v_mfma_f32_16x16x32_bf16 v[112:115], v[158:161], v[218:221], v[112:115]
	v_mfma_f32_16x16x32_bf16 v[108:111], v[150:153], v[232:235], v[108:111]
	v_mfma_f32_16x16x32_bf16 v[100:103], v[158:161], v[232:235], v[100:103]
	v_mfma_f32_16x16x32_bf16 v[92:95], v[150:153], v[240:243], v[92:95]
	v_mfma_f32_16x16x32_bf16 v[84:87], v[158:161], v[240:243], v[84:87]
	v_mfma_f32_16x16x32_bf16 v[104:107], v[162:165], v[206:209], v[104:107]
	v_mfma_f32_16x16x32_bf16 v[96:99], v[198:201], v[206:209], v[96:99]
	v_mfma_f32_16x16x32_bf16 v[88:91], v[162:165], v[214:217], v[88:91]
	v_mfma_f32_16x16x32_bf16 v[80:83], v[198:201], v[214:217], v[80:83]
	v_mfma_f32_16x16x32_bf16 v[76:79], v[162:165], v[228:231], v[76:79]
	v_mfma_f32_16x16x32_bf16 v[72:75], v[198:201], v[228:231], v[72:75]
	v_mfma_f32_16x16x32_bf16 v[68:71], v[162:165], v[236:239], v[68:71]
	v_mfma_f32_16x16x32_bf16 v[64:67], v[198:201], v[236:239], v[64:67]
	v_mfma_f32_16x16x32_bf16 v[104:107], v[166:169], v[210:213], v[104:107]
	v_mfma_f32_16x16x32_bf16 v[96:99], v[202:205], v[210:213], v[96:99]
	v_mfma_f32_16x16x32_bf16 v[88:91], v[166:169], v[218:221], v[88:91]
	v_mfma_f32_16x16x32_bf16 v[80:83], v[202:205], v[218:221], v[80:83]
	v_mfma_f32_16x16x32_bf16 v[76:79], v[166:169], v[232:235], v[76:79]
	v_mfma_f32_16x16x32_bf16 v[72:75], v[202:205], v[232:235], v[72:75]
	v_mfma_f32_16x16x32_bf16 v[68:71], v[166:169], v[240:243], v[68:71]
	v_mfma_f32_16x16x32_bf16 v[64:67], v[202:205], v[240:243], v[64:67]
	s_barrier
; #define PG8_STAGE(bufoff, gbase, voff) do { _Pragma("unroll") for (int _i = 0; _i < 2; ++_i) \
;         __builtin_amdgcn_global_load_lds((const unsigned*)((const char*)(gbase) + (voff)[_i]), (LAS unsigned*)(lds + (bufoff) + ldsw + _i * 8192), 16, 0, 0); } while (0)
; #define PG8_LDA(dst, b, h) do { _Pragma("unroll") for (int m = 0; m < 4; ++m) _Pragma("unroll") for (int k = 0; k < 2; ++k) dst[m][k] = *(const LAS bf16x8*)(lds + PG8_SA(b, h) + aoff + m * 2048 + k * 1024); } while (0)
; #define PG8_MMA(ai, bj, At, Bt) do { __builtin_amdgcn_s_setprio(1); _Pragma("unroll") for (int m = 0; m < 4; ++m) _Pragma("unroll") for (int n = 0; n < 2; ++n) _Pragma("unroll") for (int k = 0; k < 2; ++k) \
;         acc[ai][bj][m][n] = __builtin_amdgcn_mfma_f32_16x16x32_bf16(Bt[n][k], At[m][k], acc[ai][bj][m][n], 0, 0, 0); __builtin_amdgcn_s_setprio(0); } while (0)
; #define PG8_WAIT_V(n) asm volatile("s_waitcnt vmcnt(" #n ")" ::: "memory")
; #define PG8_WAIT_L(n) asm volatile("s_waitcnt lgkmcnt(" #n ")" ::: "memory")
; #define PG8_BAR __builtin_amdgcn_s_barrier()
; #define PG8_SCHED __builtin_amdgcn_sched_barrier(0)
; template <class Epi>
; __device__ __forceinline__ void gemm_phase(LAS unsigned char* lds, const Sched& S, const int K, const Epi& E) {
;     ...
;             PG8_LDA(At, 1, 1); PG8_STAGE(PG8_SB(1, 0), b3, voffB); PG8_STAGE(PG8_SB(1, 1), b3 + hstepB, voffB); PG8_STAGE(PG8_SA(1, 0), a3, voffA);
;             PG8_WAIT_V(8); PG8_WAIT_L(0); PG8_BAR; PG8_MMA(1, 0, At, B0); PG8_MMA(1, 1, At, B1); PG8_BAR; PG8_SCHED;
;         }
;         if (wr == 0) PG8_BAR;
	s_add_i32 s54, s76, s57
	v_lshl_add_u64 v[170:171], v[170:171], 0, s[74:75]
	s_mov_b32 m0, s54
	ds_read_b128 v[206:209], v144 offset:49152
	ds_read_b128 v[210:213], v144 offset:50176
	ds_read_b128 v[214:217], v144 offset:51200
	ds_read_b128 v[218:221], v144 offset:52224
	ds_read_b128 v[228:231], v144 offset:53248
	ds_read_b128 v[232:235], v144 offset:54272
	ds_read_b128 v[236:239], v144 offset:55296
	ds_read_b128 v[240:243], v144 offset:56320
	global_load_lds_dwordx4 v[170:171], off
	s_add_i32 m0, s54, 0x2000
	s_add_u32 s54, s92, 0x20080
	v_lshl_add_u64 v[170:171], v[194:195], 0, s[74:75]
	s_addc_u32 s55, s93, 0
	s_add_i32 s76, s77, s57
	global_load_lds_dwordx4 v[170:171], off
	v_lshl_add_u64 v[170:171], s[54:55], 0, v[132:133]
	s_mov_b32 m0, s76
	s_nop 0
	global_load_lds_dwordx4 v[170:171], off
	v_lshl_add_u64 v[170:171], s[54:55], 0, v[128:129]
	s_add_i32 m0, s76, 0x2000
	s_nop 0
	global_load_lds_dwordx4 v[170:171], off
	v_lshl_add_u64 v[170:171], v[224:225], 0, s[74:75]
	s_mov_b32 m0, s64
	s_nop 0
	global_load_lds_dwordx4 v[170:171], off
	v_lshl_add_u64 v[170:171], v[244:245], 0, s[74:75]
	s_mov_b32 m0, s68
	s_nop 0
	global_load_lds_dwordx4 v[170:171], off
	s_waitcnt vmcnt(8)
	s_waitcnt lgkmcnt(0)
	s_barrier
	s_waitcnt lgkmcnt(0)
	v_mfma_f32_16x16x32_bf16 v[60:63], v[146:149], v[206:209], v[60:63]
	v_mfma_f32_16x16x32_bf16 v[56:59], v[154:157], v[206:209], v[56:59]
	v_mfma_f32_16x16x32_bf16 v[52:55], v[146:149], v[214:217], v[52:55]
	v_mfma_f32_16x16x32_bf16 v[48:51], v[154:157], v[214:217], v[48:51]
	v_mfma_f32_16x16x32_bf16 v[36:39], v[146:149], v[228:231], v[36:39]
	v_mfma_f32_16x16x32_bf16 v[32:35], v[154:157], v[228:231], v[32:35]
	v_mfma_f32_16x16x32_bf16 v[20:23], v[146:149], v[236:239], v[20:23]
	v_mfma_f32_16x16x32_bf16 v[16:19], v[154:157], v[236:239], v[16:19]
	v_mfma_f32_16x16x32_bf16 v[60:63], v[150:153], v[210:213], v[60:63]
	v_mfma_f32_16x16x32_bf16 v[56:59], v[158:161], v[210:213], v[56:59]
	v_mfma_f32_16x16x32_bf16 v[52:55], v[150:153], v[218:221], v[52:55]
	v_mfma_f32_16x16x32_bf16 v[48:51], v[158:161], v[218:221], v[48:51]
	v_mfma_f32_16x16x32_bf16 v[36:39], v[150:153], v[232:235], v[36:39]
	v_mfma_f32_16x16x32_bf16 v[32:35], v[158:161], v[232:235], v[32:35]
	v_mfma_f32_16x16x32_bf16 v[20:23], v[150:153], v[240:243], v[20:23]
	v_mfma_f32_16x16x32_bf16 v[16:19], v[158:161], v[240:243], v[16:19]
	v_mfma_f32_16x16x32_bf16 v[44:47], v[162:165], v[206:209], v[44:47]
	v_mfma_f32_16x16x32_bf16 v[40:43], v[198:201], v[206:209], v[40:43]
	v_mfma_f32_16x16x32_bf16 v[28:31], v[162:165], v[214:217], v[28:31]
	v_mfma_f32_16x16x32_bf16 v[24:27], v[198:201], v[214:217], v[24:27]
	v_mfma_f32_16x16x32_bf16 v[12:15], v[162:165], v[228:231], v[12:15]
	v_mfma_f32_16x16x32_bf16 v[8:11], v[198:201], v[228:231], v[8:11]
	v_mfma_f32_16x16x32_bf16 v[4:7], v[162:165], v[236:239], v[4:7]
	v_mfma_f32_16x16x32_bf16 v[0:3], v[198:201], v[236:239], v[0:3]
	v_mfma_f32_16x16x32_bf16 v[44:47], v[166:169], v[210:213], v[44:47]
	v_mfma_f32_16x16x32_bf16 v[40:43], v[202:205], v[210:213], v[40:43]
	v_mfma_f32_16x16x32_bf16 v[28:31], v[166:169], v[218:221], v[28:31]
	v_mfma_f32_16x16x32_bf16 v[24:27], v[202:205], v[218:221], v[24:27]
	v_mfma_f32_16x16x32_bf16 v[12:15], v[166:169], v[232:235], v[12:15]
	v_mfma_f32_16x16x32_bf16 v[8:11], v[202:205], v[232:235], v[8:11]
	v_mfma_f32_16x16x32_bf16 v[4:7], v[166:169], v[240:243], v[4:7]
	v_mfma_f32_16x16x32_bf16 v[0:3], v[202:205], v[240:243], v[0:3]
	s_barrier
	s_add_i32 s73, s73, 2
	s_add_u32 s36, s36, 0x100
	s_addc_u32 s72, s72, 0
	s_cmp_gt_u32 s73, 5
	s_mov_b64 s[54:55], s[58:59]
	s_cbranch_scc0 .LBB0_582
	s_and_b64 vcc, exec, s[34:35]
	s_cbranch_vccz .LBB0_585
	s_barrier

; #define PG8_STAGE(bufoff, gbase, voff) do { _Pragma("unroll") for (int _i = 0; _i < 2; ++_i) \
;         __builtin_amdgcn_global_load_lds((const unsigned*)((const char*)(gbase) + (voff)[_i]), (LAS unsigned*)(lds + (bufoff) + ldsw + _i * 8192), 16, 0, 0); } while (0)
; #define PG8_LDA(dst, b, h) do { _Pragma("unroll") for (int m = 0; m < 4; ++m) _Pragma("unroll") for (int k = 0; k < 2; ++k) dst[m][k] = *(const LAS bf16x8*)(lds + PG8_SA(b, h) + aoff + m * 2048 + k * 1024); } while (0)
; #define PG8_LDB(dst, b, h) do { _Pragma("unroll") for (int n = 0; n < 2; ++n) _Pragma("unroll") for (int k = 0; k < 2; ++k) dst[n][k] = *(const LAS bf16x8*)(lds + PG8_SB(b, h) + boff + n * 2048 + k * 1024); } while (0)
; #define PG8_MMA(ai, bj, At, Bt) do { __builtin_amdgcn_s_setprio(1); _Pragma("unroll") for (int m = 0; m < 4; ++m) _Pragma("unroll") for (int n = 0; n < 2; ++n) _Pragma("unroll") for (int k = 0; k < 2; ++k) \
;         acc[ai][bj][m][n] = __builtin_amdgcn_mfma_f32_16x16x32_bf16(Bt[n][k], At[m][k], acc[ai][bj][m][n], 0, 0, 0); __builtin_amdgcn_s_setprio(0); } while (0)
; #define PG8_WAIT_V(n) asm volatile("s_waitcnt vmcnt(" #n ")" ::: "memory")
; #define PG8_WAIT_L(n) asm volatile("s_waitcnt lgkmcnt(" #n ")" ::: "memory")
; #define PG8_BAR __builtin_amdgcn_s_barrier()
; #define PG8_SCHED __builtin_amdgcn_sched_barrier(0)
; template <class Epi>
; __device__ __forceinline__ void gemm_phase(LAS unsigned char* lds, const Sched& S, const int K, const Epi& E) {
;     ...
;         for (int t = 0; t < nt; t += 2) {
;             const bool last = (t == nt - 2);
;             const char* a1 = cA + (size_t)(t + 1) * kstep;
;             const char* a2 = last ? nA : cA + (size_t)(t + 2) * kstep; const char* b2 = last ? nB : cB + (size_t)(t + 2) * kstep;
;             const char* a3 = a2 + kstep; const char* b3 = b2 + kstep;
;             PG8_LDB(B0, 0, 0); PG8_LDB(B1, 0, 1); PG8_SCHED; PG8_LDA(At, 0, 0); PG8_STAGE(PG8_SA(1, 1), a1 + hstepA, voffA);
;             PG8_WAIT_V(8); PG8_WAIT_L(0); PG8_BAR; PG8_MMA(0, 0, At, B0); PG8_MMA(0, 1, At, B1); PG8_BAR; PG8_SCHED;
;             PG8_LDA(At, 0, 1); PG8_STAGE(PG8_SB(0, 0), b2, voffB); PG8_STAGE(PG8_SB(0, 1), b2 + hstepB, voffB); PG8_STAGE(PG8_SA(0, 0), a2, voffA);
.LBB0_747:
	s_add_u32 s50, s48, 0xfffe0080
	s_addc_u32 s51, s49, -1
	s_add_i32 s69, 0, 0x10000
	s_cmp_eq_u32 s68, 4
	s_cselect_b32 s53, s35, s51
	s_cselect_b32 s52, s34, s50
	v_add_u32_e32 v140, s69, v142
	s_cselect_b32 s51, s47, s67
	s_cselect_b32 s50, s46, s43
	s_add_i32 s72, 0, 0x14000
	ds_read_b128 v[146:149], v140
	ds_read_b128 v[150:153], v140 offset:1024
	ds_read_b128 v[154:157], v140 offset:2048
	ds_read_b128 v[158:161], v140 offset:3072
	v_add_u32_e32 v140, s72, v142
	ds_read_b128 v[162:165], v140
	ds_read_b128 v[166:169], v140 offset:1024
	ds_read_b128 v[198:201], v140 offset:2048
	ds_read_b128 v[202:205], v140 offset:3072
	v_lshl_add_u64 v[140:141], s[48:49], 0, v[136:137]
	s_add_i32 m0, s55, 0xc000
	ds_read_b128 v[206:209], v145
	ds_read_b128 v[210:213], v145 offset:1024
	ds_read_b128 v[214:217], v145 offset:2048
	ds_read_b128 v[218:221], v145 offset:3072
	ds_read_b128 v[228:231], v145 offset:4096
	ds_read_b128 v[232:235], v145 offset:5120
	ds_read_b128 v[236:239], v145 offset:6144
	ds_read_b128 v[240:243], v145 offset:7168
	global_load_lds_dwordx4 v[140:141], off
	v_lshl_add_u64 v[140:141], s[48:49], 0, v[138:139]
	s_add_i32 m0, s55, 0xe000
	s_nop 0
	global_load_lds_dwordx4 v[140:141], off
	s_waitcnt vmcnt(8)
	s_waitcnt lgkmcnt(0)
	s_barrier
	s_waitcnt lgkmcnt(0)
	v_mfma_f32_16x16x32_bf16 v[124:127], v[146:149], v[206:209], v[124:127]
	v_mfma_f32_16x16x32_bf16 v[120:123], v[154:157], v[206:209], v[120:123]
	v_mfma_f32_16x16x32_bf16 v[116:119], v[146:149], v[214:217], v[116:119]
	v_mfma_f32_16x16x32_bf16 v[108:111], v[154:157], v[214:217], v[108:111]
	v_mfma_f32_16x16x32_bf16 v[100:103], v[146:149], v[228:231], v[100:103]
	v_mfma_f32_16x16x32_bf16 v[92:95], v[154:157], v[228:231], v[92:95]
	v_mfma_f32_16x16x32_bf16 v[84:87], v[146:149], v[236:239], v[84:87]
	v_mfma_f32_16x16x32_bf16 v[76:79], v[154:157], v[236:239], v[76:79]
	v_mfma_f32_16x16x32_bf16 v[124:127], v[150:153], v[210:213], v[124:127]
	v_mfma_f32_16x16x32_bf16 v[120:123], v[158:161], v[210:213], v[120:123]
	v_mfma_f32_16x16x32_bf16 v[116:119], v[150:153], v[218:221], v[116:119]
	v_mfma_f32_16x16x32_bf16 v[108:111], v[158:161], v[218:221], v[108:111]
	v_mfma_f32_16x16x32_bf16 v[100:103], v[150:153], v[232:235], v[100:103]
	v_mfma_f32_16x16x32_bf16 v[92:95], v[158:161], v[232:235], v[92:95]
	v_mfma_f32_16x16x32_bf16 v[84:87], v[150:153], v[240:243], v[84:87]
	v_mfma_f32_16x16x32_bf16 v[76:79], v[158:161], v[240:243], v[76:79]
	v_mfma_f32_16x16x32_bf16 v[112:115], v[162:165], v[206:209], v[112:115]
	v_mfma_f32_16x16x32_bf16 v[104:107], v[198:201], v[206:209], v[104:107]
	v_mfma_f32_16x16x32_bf16 v[96:99], v[162:165], v[214:217], v[96:99]
	v_mfma_f32_16x16x32_bf16 v[88:91], v[198:201], v[214:217], v[88:91]
	v_mfma_f32_16x16x32_bf16 v[80:83], v[162:165], v[228:231], v[80:83]
	v_mfma_f32_16x16x32_bf16 v[72:75], v[198:201], v[228:231], v[72:75]
	v_mfma_f32_16x16x32_bf16 v[68:71], v[162:165], v[236:239], v[68:71]
	v_mfma_f32_16x16x32_bf16 v[64:67], v[198:201], v[236:239], v[64:67]
	v_mfma_f32_16x16x32_bf16 v[112:115], v[166:169], v[210:213], v[112:115]
	v_mfma_f32_16x16x32_bf16 v[104:107], v[202:205], v[210:213], v[104:107]
	v_mfma_f32_16x16x32_bf16 v[96:99], v[166:169], v[218:221], v[96:99]
	v_mfma_f32_16x16x32_bf16 v[88:91], v[202:205], v[218:221], v[88:91]
	v_mfma_f32_16x16x32_bf16 v[80:83], v[166:169], v[232:235], v[80:83]
	v_mfma_f32_16x16x32_bf16 v[72:75], v[202:205], v[232:235], v[72:75]
	v_mfma_f32_16x16x32_bf16 v[68:71], v[166:169], v[240:243], v[68:71]
	v_mfma_f32_16x16x32_bf16 v[64:67], v[202:205], v[240:243], v[64:67]
	s_barrier
	s_add_i32 s69, s69, s54
	v_lshl_add_u64 v[140:141], s[50:51], 0, v[132:133]
	s_mov_b32 m0, s69
	ds_read_b128 v[206:209], v145 offset:16384
	ds_read_b128 v[210:213], v145 offset:17408
	ds_read_b128 v[214:217], v145 offset:18432
	ds_read_b128 v[218:221], v145 offset:19456
	ds_read_b128 v[228:231], v145 offset:20480
	ds_read_b128 v[232:235], v145 offset:21504
	ds_read_b128 v[236:239], v145 offset:22528
	ds_read_b128 v[240:243], v145 offset:23552
	global_load_lds_dwordx4 v[140:141], off
	s_add_i32 m0, s69, 0x2000
	s_add_u32 s70, s50, 0x20000
	v_lshl_add_u64 v[170:171], s[50:51], 0, v[128:129]
	s_addc_u32 s71, s51, 0
	s_add_i32 s69, s72, s54
	global_load_lds_dwordx4 v[170:171], off
	v_lshl_add_u64 v[194:195], s[70:71], 0, v[132:133]
	s_mov_b32 m0, s69
	v_lshl_add_u64 v[224:225], s[52:53], 0, v[130:131]
	global_load_lds_dwordx4 v[194:195], off
	v_lshl_add_u64 v[194:195], s[70:71], 0, v[128:129]
	s_add_i32 m0, s69, 0x2000
	s_nop 0
	global_load_lds_dwordx4 v[194:195], off
	v_lshl_add_u64 v[194:195], s[52:53], 0, v[134:135]
	s_mov_b32 m0, s55
	s_nop 0
	global_load_lds_dwordx4 v[194:195], off
	s_mov_b32 m0, s57
	s_nop 0
	global_load_lds_dwordx4 v[224:225], off
	s_waitcnt vmcnt(8)
	s_waitcnt lgkmcnt(0)
	s_barrier
; #define PG8_STAGE(bufoff, gbase, voff) do { _Pragma("unroll") for (int _i = 0; _i < 2; ++_i) \
;         __builtin_amdgcn_global_load_lds((const unsigned*)((const char*)(gbase) + (voff)[_i]), (LAS unsigned*)(lds + (bufoff) + ldsw + _i * 8192), 16, 0, 0); } while (0)
; #define PG8_LDA(dst, b, h) do { _Pragma("unroll") for (int m = 0; m < 4; ++m) _Pragma("unroll") for (int k = 0; k < 2; ++k) dst[m][k] = *(const LAS bf16x8*)(lds + PG8_SA(b, h) + aoff + m * 2048 + k * 1024); } while (0)
; #define PG8_LDB(dst, b, h) do { _Pragma("unroll") for (int n = 0; n < 2; ++n) _Pragma("unroll") for (int k = 0; k < 2; ++k) dst[n][k] = *(const LAS bf16x8*)(lds + PG8_SB(b, h) + boff + n * 2048 + k * 1024); } while (0)
; #define PG8_MMA(ai, bj, At, Bt) do { __builtin_amdgcn_s_setprio(1); _Pragma("unroll") for (int m = 0; m < 4; ++m) _Pragma("unroll") for (int n = 0; n < 2; ++n) _Pragma("unroll") for (int k = 0; k < 2; ++k) \
;         acc[ai][bj][m][n] = __builtin_amdgcn_mfma_f32_16x16x32_bf16(Bt[n][k], At[m][k], acc[ai][bj][m][n], 0, 0, 0); __builtin_amdgcn_s_setprio(0); } while (0)
; #define PG8_WAIT_V(n) asm volatile("s_waitcnt vmcnt(" #n ")" ::: "memory")
; #define PG8_WAIT_L(n) asm volatile("s_waitcnt lgkmcnt(" #n ")" ::: "memory")
; #define PG8_BAR __builtin_amdgcn_s_barrier()
; #define PG8_SCHED __builtin_amdgcn_sched_barrier(0)
; template <class Epi>
; __device__ __forceinline__ void gemm_phase(LAS unsigned char* lds, const Sched& S, const int K, const Epi& E) {
;     ...
;             PG8_WAIT_V(8); PG8_WAIT_L(0); PG8_BAR; PG8_MMA(1, 0, At, B0); PG8_MMA(1, 1, At, B1); PG8_BAR; PG8_SCHED;
;             PG8_LDB(B0, 1, 0); PG8_LDB(B1, 1, 1); PG8_SCHED; PG8_LDA(At, 1, 0); PG8_STAGE(PG8_SA(0, 1), a2 + hstepA, voffA);
;             PG8_WAIT_V(8); PG8_WAIT_L(0); PG8_BAR; PG8_MMA(0, 0, At, B0); PG8_MMA(0, 1, At, B1); PG8_BAR; PG8_SCHED;
	s_waitcnt lgkmcnt(0)
	v_mfma_f32_16x16x32_bf16 v[60:63], v[146:149], v[206:209], v[60:63]
	v_mfma_f32_16x16x32_bf16 v[56:59], v[154:157], v[206:209], v[56:59]
	v_mfma_f32_16x16x32_bf16 v[52:55], v[146:149], v[214:217], v[52:55]
	v_mfma_f32_16x16x32_bf16 v[44:47], v[154:157], v[214:217], v[44:47]
	v_mfma_f32_16x16x32_bf16 v[36:39], v[146:149], v[228:231], v[36:39]
	v_mfma_f32_16x16x32_bf16 v[28:31], v[154:157], v[228:231], v[28:31]
	v_mfma_f32_16x16x32_bf16 v[20:23], v[146:149], v[236:239], v[20:23]
	v_mfma_f32_16x16x32_bf16 v[12:15], v[154:157], v[236:239], v[12:15]
	v_mfma_f32_16x16x32_bf16 v[60:63], v[150:153], v[210:213], v[60:63]
	v_mfma_f32_16x16x32_bf16 v[56:59], v[158:161], v[210:213], v[56:59]
	v_mfma_f32_16x16x32_bf16 v[52:55], v[150:153], v[218:221], v[52:55]
	v_mfma_f32_16x16x32_bf16 v[44:47], v[158:161], v[218:221], v[44:47]
	v_mfma_f32_16x16x32_bf16 v[36:39], v[150:153], v[232:235], v[36:39]
	v_mfma_f32_16x16x32_bf16 v[28:31], v[158:161], v[232:235], v[28:31]
	v_mfma_f32_16x16x32_bf16 v[20:23], v[150:153], v[240:243], v[20:23]
	v_mfma_f32_16x16x32_bf16 v[12:15], v[158:161], v[240:243], v[12:15]
	v_mfma_f32_16x16x32_bf16 v[48:51], v[162:165], v[206:209], v[48:51]
	v_mfma_f32_16x16x32_bf16 v[40:43], v[198:201], v[206:209], v[40:43]
	v_mfma_f32_16x16x32_bf16 v[32:35], v[162:165], v[214:217], v[32:35]
	v_mfma_f32_16x16x32_bf16 v[24:27], v[198:201], v[214:217], v[24:27]
	v_mfma_f32_16x16x32_bf16 v[16:19], v[162:165], v[228:231], v[16:19]
	v_mfma_f32_16x16x32_bf16 v[8:11], v[198:201], v[228:231], v[8:11]
	v_mfma_f32_16x16x32_bf16 v[4:7], v[162:165], v[236:239], v[4:7]
	v_mfma_f32_16x16x32_bf16 v[0:3], v[198:201], v[236:239], v[0:3]
	v_mfma_f32_16x16x32_bf16 v[48:51], v[166:169], v[210:213], v[48:51]
	v_mfma_f32_16x16x32_bf16 v[40:43], v[202:205], v[210:213], v[40:43]
	v_mfma_f32_16x16x32_bf16 v[32:35], v[166:169], v[218:221], v[32:35]
	v_mfma_f32_16x16x32_bf16 v[24:27], v[202:205], v[218:221], v[24:27]
	v_mfma_f32_16x16x32_bf16 v[16:19], v[166:169], v[232:235], v[16:19]
	v_mfma_f32_16x16x32_bf16 v[8:11], v[202:205], v[232:235], v[8:11]
	v_mfma_f32_16x16x32_bf16 v[4:7], v[166:169], v[240:243], v[4:7]
	v_mfma_f32_16x16x32_bf16 v[0:3], v[202:205], v[240:243], v[0:3]
	s_barrier
	s_add_i32 s69, 0, 0x18000
	s_add_i32 s70, 0, 0x1c000
	v_add_u32_e32 v158, s69, v142
	v_add_u32_e32 v172, s70, v142
	ds_read_b128 v[146:149], v158
	ds_read_b128 v[150:153], v158 offset:1024
	ds_read_b128 v[154:157], v158 offset:2048
	ds_read_b128 v[158:161], v158 offset:3072
	ds_read_b128 v[162:165], v172
	ds_read_b128 v[166:169], v172 offset:1024
	ds_read_b128 v[198:201], v172 offset:2048
	ds_read_b128 v[202:205], v172 offset:3072
	s_add_u32 s52, s52, 0x20000
	s_addc_u32 s53, s53, 0
	s_mov_b32 m0, s58
	v_lshl_add_u64 v[244:245], s[52:53], 0, v[134:135]
	ds_read_b128 v[206:209], v145 offset:32768
	ds_read_b128 v[210:213], v145 offset:33792
	ds_read_b128 v[214:217], v145 offset:34816
	ds_read_b128 v[218:221], v145 offset:35840
	ds_read_b128 v[228:231], v145 offset:36864
	ds_read_b128 v[232:235], v145 offset:37888
	ds_read_b128 v[236:239], v145 offset:38912
	ds_read_b128 v[240:243], v145 offset:39936
	global_load_lds_dwordx4 v[244:245], off
	v_lshl_add_u64 v[244:245], s[52:53], 0, v[130:131]
	s_mov_b32 m0, s59
	s_nop 0
	global_load_lds_dwordx4 v[244:245], off
	s_waitcnt vmcnt(8)
	s_waitcnt lgkmcnt(0)
	s_barrier
	s_waitcnt lgkmcnt(0)
	v_mfma_f32_16x16x32_bf16 v[124:127], v[146:149], v[206:209], v[124:127]
	v_mfma_f32_16x16x32_bf16 v[120:123], v[154:157], v[206:209], v[120:123]
	v_mfma_f32_16x16x32_bf16 v[116:119], v[146:149], v[214:217], v[116:119]
	v_mfma_f32_16x16x32_bf16 v[108:111], v[154:157], v[214:217], v[108:111]
	v_mfma_f32_16x16x32_bf16 v[100:103], v[146:149], v[228:231], v[100:103]
	v_mfma_f32_16x16x32_bf16 v[92:95], v[154:157], v[228:231], v[92:95]
	v_mfma_f32_16x16x32_bf16 v[84:87], v[146:149], v[236:239], v[84:87]
	v_mfma_f32_16x16x32_bf16 v[76:79], v[154:157], v[236:239], v[76:79]
	v_mfma_f32_16x16x32_bf16 v[124:127], v[150:153], v[210:213], v[124:127]
	v_mfma_f32_16x16x32_bf16 v[120:123], v[158:161], v[210:213], v[120:123]
	v_mfma_f32_16x16x32_bf16 v[116:119], v[150:153], v[218:221], v[116:119]
	v_mfma_f32_16x16x32_bf16 v[108:111], v[158:161], v[218:221], v[108:111]
	v_mfma_f32_16x16x32_bf16 v[100:103], v[150:153], v[232:235], v[100:103]
	v_mfma_f32_16x16x32_bf16 v[92:95], v[158:161], v[232:235], v[92:95]
	v_mfma_f32_16x16x32_bf16 v[84:87], v[150:153], v[240:243], v[84:87]
	v_mfma_f32_16x16x32_bf16 v[76:79], v[158:161], v[240:243], v[76:79]
	v_mfma_f32_16x16x32_bf16 v[112:115], v[162:165], v[206:209], v[112:115]
	v_mfma_f32_16x16x32_bf16 v[104:107], v[198:201], v[206:209], v[104:107]
	v_mfma_f32_16x16x32_bf16 v[96:99], v[162:165], v[214:217], v[96:99]
	v_mfma_f32_16x16x32_bf16 v[88:91], v[198:201], v[214:217], v[88:91]
	v_mfma_f32_16x16x32_bf16 v[80:83], v[162:165], v[228:231], v[80:83]
	v_mfma_f32_16x16x32_bf16 v[72:75], v[198:201], v[228:231], v[72:75]
	v_mfma_f32_16x16x32_bf16 v[68:71], v[162:165], v[236:239], v[68:71]
	v_mfma_f32_16x16x32_bf16 v[64:67], v[198:201], v[236:239], v[64:67]
	v_mfma_f32_16x16x32_bf16 v[112:115], v[166:169], v[210:213], v[112:115]
	v_mfma_f32_16x16x32_bf16 v[104:107], v[202:205], v[210:213], v[104:107]
	v_mfma_f32_16x16x32_bf16 v[96:99], v[166:169], v[218:221], v[96:99]
	v_mfma_f32_16x16x32_bf16 v[88:91], v[202:205], v[218:221], v[88:91]
	v_mfma_f32_16x16x32_bf16 v[80:83], v[166:169], v[232:235], v[80:83]
	v_mfma_f32_16x16x32_bf16 v[72:75], v[202:205], v[232:235], v[72:75]
	v_mfma_f32_16x16x32_bf16 v[68:71], v[166:169], v[240:243], v[68:71]
	v_mfma_f32_16x16x32_bf16 v[64:67], v[202:205], v[240:243], v[64:67]
	s_barrier
; #define PG8_STAGE(bufoff, gbase, voff) do { _Pragma("unroll") for (int _i = 0; _i < 2; ++_i) \
;         __builtin_amdgcn_global_load_lds((const unsigned*)((const char*)(gbase) + (voff)[_i]), (LAS unsigned*)(lds + (bufoff) + ldsw + _i * 8192), 16, 0, 0); } while (0)
; #define PG8_LDA(dst, b, h) do { _Pragma("unroll") for (int m = 0; m < 4; ++m) _Pragma("unroll") for (int k = 0; k < 2; ++k) dst[m][k] = *(const LAS bf16x8*)(lds + PG8_SA(b, h) + aoff + m * 2048 + k * 1024); } while (0)
; #define PG8_MMA(ai, bj, At, Bt) do { __builtin_amdgcn_s_setprio(1); _Pragma("unroll") for (int m = 0; m < 4; ++m) _Pragma("unroll") for (int n = 0; n < 2; ++n) _Pragma("unroll") for (int k = 0; k < 2; ++k) \
;         acc[ai][bj][m][n] = __builtin_amdgcn_mfma_f32_16x16x32_bf16(Bt[n][k], At[m][k], acc[ai][bj][m][n], 0, 0, 0); __builtin_amdgcn_s_setprio(0); } while (0)
; #define PG8_WAIT_V(n) asm volatile("s_waitcnt vmcnt(" #n ")" ::: "memory")
; #define PG8_WAIT_L(n) asm volatile("s_waitcnt lgkmcnt(" #n ")" ::: "memory")
; #define PG8_BAR __builtin_amdgcn_s_barrier()
; #define PG8_SCHED __builtin_amdgcn_sched_barrier(0)
; template <class Epi>
; __device__ __forceinline__ void gemm_phase(LAS unsigned char* lds, const Sched& S, const int K, const Epi& E) {
;     ...
;             PG8_LDA(At, 1, 1); PG8_STAGE(PG8_SB(1, 0), b3, voffB); PG8_STAGE(PG8_SB(1, 1), b3 + hstepB, voffB); PG8_STAGE(PG8_SA(1, 0), a3, voffA);
;             PG8_WAIT_V(8); PG8_WAIT_L(0); PG8_BAR; PG8_MMA(1, 0, At, B0); PG8_MMA(1, 1, At, B1); PG8_BAR; PG8_SCHED;
;         }
	s_add_i32 s52, s69, s54
	v_lshl_add_u64 v[140:141], v[140:141], 0, s[74:75]
	s_mov_b32 m0, s52
	ds_read_b128 v[206:209], v145 offset:49152
	ds_read_b128 v[210:213], v145 offset:50176
	ds_read_b128 v[214:217], v145 offset:51200
	ds_read_b128 v[218:221], v145 offset:52224
	ds_read_b128 v[228:231], v145 offset:53248
	ds_read_b128 v[232:235], v145 offset:54272
	ds_read_b128 v[236:239], v145 offset:55296
	ds_read_b128 v[240:243], v145 offset:56320
	global_load_lds_dwordx4 v[140:141], off
	s_add_i32 m0, s52, 0x2000
	s_add_u32 s50, s50, 0x20080
	v_lshl_add_u64 v[140:141], v[170:171], 0, s[74:75]
	s_addc_u32 s51, s51, 0
	s_add_i32 s52, s70, s54
	global_load_lds_dwordx4 v[140:141], off
	v_lshl_add_u64 v[140:141], s[50:51], 0, v[132:133]
	s_mov_b32 m0, s52
	s_nop 0
	global_load_lds_dwordx4 v[140:141], off
	v_lshl_add_u64 v[140:141], s[50:51], 0, v[128:129]
	s_add_i32 m0, s52, 0x2000
	s_nop 0
	global_load_lds_dwordx4 v[140:141], off
	v_lshl_add_u64 v[140:141], v[194:195], 0, s[74:75]
	s_mov_b32 m0, s60
	s_nop 0
	global_load_lds_dwordx4 v[140:141], off
	v_lshl_add_u64 v[140:141], v[224:225], 0, s[74:75]
	s_mov_b32 m0, s61
	s_nop 0
	global_load_lds_dwordx4 v[140:141], off
	s_waitcnt vmcnt(8)
	s_waitcnt lgkmcnt(0)
	s_barrier
	s_waitcnt lgkmcnt(0)
	v_mfma_f32_16x16x32_bf16 v[60:63], v[146:149], v[206:209], v[60:63]
	v_mfma_f32_16x16x32_bf16 v[56:59], v[154:157], v[206:209], v[56:59]
	v_mfma_f32_16x16x32_bf16 v[52:55], v[146:149], v[214:217], v[52:55]
	v_mfma_f32_16x16x32_bf16 v[44:47], v[154:157], v[214:217], v[44:47]
	v_mfma_f32_16x16x32_bf16 v[36:39], v[146:149], v[228:231], v[36:39]
	v_mfma_f32_16x16x32_bf16 v[28:31], v[154:157], v[228:231], v[28:31]
	v_mfma_f32_16x16x32_bf16 v[20:23], v[146:149], v[236:239], v[20:23]
	v_mfma_f32_16x16x32_bf16 v[12:15], v[154:157], v[236:239], v[12:15]
	v_mfma_f32_16x16x32_bf16 v[60:63], v[150:153], v[210:213], v[60:63]
	v_mfma_f32_16x16x32_bf16 v[56:59], v[158:161], v[210:213], v[56:59]
	v_mfma_f32_16x16x32_bf16 v[52:55], v[150:153], v[218:221], v[52:55]
	v_mfma_f32_16x16x32_bf16 v[44:47], v[158:161], v[218:221], v[44:47]
	v_mfma_f32_16x16x32_bf16 v[36:39], v[150:153], v[232:235], v[36:39]
	v_mfma_f32_16x16x32_bf16 v[28:31], v[158:161], v[232:235], v[28:31]
	v_mfma_f32_16x16x32_bf16 v[20:23], v[150:153], v[240:243], v[20:23]
	v_mfma_f32_16x16x32_bf16 v[12:15], v[158:161], v[240:243], v[12:15]
	v_mfma_f32_16x16x32_bf16 v[48:51], v[162:165], v[206:209], v[48:51]
	v_mfma_f32_16x16x32_bf16 v[40:43], v[198:201], v[206:209], v[40:43]
	v_mfma_f32_16x16x32_bf16 v[32:35], v[162:165], v[214:217], v[32:35]
	v_mfma_f32_16x16x32_bf16 v[24:27], v[198:201], v[214:217], v[24:27]
	v_mfma_f32_16x16x32_bf16 v[16:19], v[162:165], v[228:231], v[16:19]
	v_mfma_f32_16x16x32_bf16 v[8:11], v[198:201], v[228:231], v[8:11]
	v_mfma_f32_16x16x32_bf16 v[4:7], v[162:165], v[236:239], v[4:7]
	v_mfma_f32_16x16x32_bf16 v[0:3], v[198:201], v[236:239], v[0:3]
	v_mfma_f32_16x16x32_bf16 v[48:51], v[166:169], v[210:213], v[48:51]
	v_mfma_f32_16x16x32_bf16 v[40:43], v[202:205], v[210:213], v[40:43]
	v_mfma_f32_16x16x32_bf16 v[32:35], v[166:169], v[218:221], v[32:35]
	v_mfma_f32_16x16x32_bf16 v[24:27], v[202:205], v[218:221], v[24:27]
	v_mfma_f32_16x16x32_bf16 v[16:19], v[166:169], v[232:235], v[16:19]
	v_mfma_f32_16x16x32_bf16 v[8:11], v[202:205], v[232:235], v[8:11]
	v_mfma_f32_16x16x32_bf16 v[4:7], v[166:169], v[240:243], v[4:7]
	v_mfma_f32_16x16x32_bf16 v[0:3], v[202:205], v[240:243], v[0:3]
	s_barrier
	s_add_i32 s68, s68, 2
	s_add_u32 s43, s43, 0x100
	s_addc_u32 s67, s67, 0
	s_add_u32 s48, s48, 0x100
	s_addc_u32 s49, s49, 0
	s_cmp_gt_u32 s68, 5
	s_cbranch_scc0 .LBB0_747
	s_and_b64 vcc, exec, s[40:41]
	s_cbranch_vccz .LBB0_750
	s_barrier

; #define PG8_STAGE(bufoff, gbase, voff) do { _Pragma("unroll") for (int _i = 0; _i < 2; ++_i) \
;         __builtin_amdgcn_global_load_lds((const unsigned*)((const char*)(gbase) + (voff)[_i]), (LAS unsigned*)(lds + (bufoff) + ldsw + _i * 8192), 16, 0, 0); } while (0)
; #define PG8_LDA(dst, b, h) do { _Pragma("unroll") for (int m = 0; m < 4; ++m) _Pragma("unroll") for (int k = 0; k < 2; ++k) dst[m][k] = *(const LAS bf16x8*)(lds + PG8_SA(b, h) + aoff + m * 2048 + k * 1024); } while (0)
; #define PG8_LDB(dst, b, h) do { _Pragma("unroll") for (int n = 0; n < 2; ++n) _Pragma("unroll") for (int k = 0; k < 2; ++k) dst[n][k] = *(const LAS bf16x8*)(lds + PG8_SB(b, h) + boff + n * 2048 + k * 1024); } while (0)
; #define PG8_MMA(ai, bj, At, Bt) do { __builtin_amdgcn_s_setprio(1); _Pragma("unroll") for (int m = 0; m < 4; ++m) _Pragma("unroll") for (int n = 0; n < 2; ++n) _Pragma("unroll") for (int k = 0; k < 2; ++k) \
;         acc[ai][bj][m][n] = __builtin_amdgcn_mfma_f32_16x16x32_bf16(Bt[n][k], At[m][k], acc[ai][bj][m][n], 0, 0, 0); __builtin_amdgcn_s_setprio(0); } while (0)
; #define PG8_WAIT_V(n) asm volatile("s_waitcnt vmcnt(" #n ")" ::: "memory")
; #define PG8_WAIT_L(n) asm volatile("s_waitcnt lgkmcnt(" #n ")" ::: "memory")
; #define PG8_BAR __builtin_amdgcn_s_barrier()
; #define PG8_SCHED __builtin_amdgcn_sched_barrier(0)
; template <class Epi>
; __device__ __forceinline__ void gemm_phase(LAS unsigned char* lds, const Sched& S, const int K, const Epi& E) {
;     ...
;         for (int t = 0; t < nt; t += 2) {
;             const bool last = (t == nt - 2);
;             const char* a1 = cA + (size_t)(t + 1) * kstep;
;             const char* a2 = last ? nA : cA + (size_t)(t + 2) * kstep; const char* b2 = last ? nB : cB + (size_t)(t + 2) * kstep;
;             const char* a3 = a2 + kstep; const char* b3 = b2 + kstep;
;             PG8_LDB(B0, 0, 0); PG8_LDB(B1, 0, 1); PG8_SCHED; PG8_LDA(At, 0, 0); PG8_STAGE(PG8_SA(1, 1), a1 + hstepA, voffA);
;             PG8_WAIT_V(8); PG8_WAIT_L(0); PG8_BAR; PG8_MMA(0, 0, At, B0); PG8_MMA(0, 1, At, B1); PG8_BAR; PG8_SCHED;
;             PG8_LDA(At, 0, 1); PG8_STAGE(PG8_SB(0, 0), b2, voffB); PG8_STAGE(PG8_SB(0, 1), b2 + hstepB, voffB); PG8_STAGE(PG8_SA(0, 0), a2, voffA);
.LBB0_834:
	s_add_u32 s52, s36, 0x100
	s_addc_u32 s53, s37, 0
	s_add_i32 s76, 0, 0x10000
	s_cmp_eq_u32 s96, 8
	s_cselect_b32 s59, s29, s53
	s_cselect_b32 s58, s28, s52
	s_cselect_b32 s55, s35, vcc_hi
	s_cselect_b32 s54, s34, vcc_lo
	s_add_i32 s77, 0, 0x14000
	v_add_u32_e32 v156, s76, v140
	v_add_u32_e32 v194, s77, v140
	ds_read_b128 v[144:147], v156
	ds_read_b128 v[148:151], v156 offset:1024
	ds_read_b128 v[152:155], v156 offset:2048
	ds_read_b128 v[156:159], v156 offset:3072
	ds_read_b128 v[160:163], v194
	ds_read_b128 v[164:167], v194 offset:1024
	ds_read_b128 v[168:171], v194 offset:2048
	ds_read_b128 v[198:201], v194 offset:3072
	v_lshl_add_u64 v[194:195], s[36:37], 0, v[136:137]
	s_add_i32 m0, s67, 0xc000
	ds_read_b128 v[202:205], v143
	ds_read_b128 v[206:209], v143 offset:1024
	ds_read_b128 v[210:213], v143 offset:2048
	ds_read_b128 v[214:217], v143 offset:3072
	ds_read_b128 v[218:221], v143 offset:4096
	ds_read_b128 v[228:231], v143 offset:5120
	ds_read_b128 v[232:235], v143 offset:6144
	ds_read_b128 v[236:239], v143 offset:7168
	global_load_lds_dwordx4 v[194:195], off
	v_lshl_add_u64 v[194:195], s[36:37], 0, v[138:139]
	s_add_i32 m0, s67, 0xe000
	s_nop 0
	global_load_lds_dwordx4 v[194:195], off
	s_waitcnt vmcnt(8)
	s_waitcnt lgkmcnt(0)
	s_barrier
	s_waitcnt lgkmcnt(0)
	v_mfma_f32_16x16x32_bf16 v[124:127], v[144:147], v[202:205], v[124:127]
	v_mfma_f32_16x16x32_bf16 v[120:123], v[152:155], v[202:205], v[120:123]
	v_mfma_f32_16x16x32_bf16 v[108:111], v[144:147], v[210:213], v[108:111]
	v_mfma_f32_16x16x32_bf16 v[104:107], v[152:155], v[210:213], v[104:107]
	v_mfma_f32_16x16x32_bf16 v[92:95], v[144:147], v[218:221], v[92:95]
	v_mfma_f32_16x16x32_bf16 v[88:91], v[152:155], v[218:221], v[88:91]
	v_mfma_f32_16x16x32_bf16 v[76:79], v[144:147], v[232:235], v[76:79]
	v_mfma_f32_16x16x32_bf16 v[72:75], v[152:155], v[232:235], v[72:75]
	v_mfma_f32_16x16x32_bf16 v[124:127], v[148:151], v[206:209], v[124:127]
	v_mfma_f32_16x16x32_bf16 v[120:123], v[156:159], v[206:209], v[120:123]
	v_mfma_f32_16x16x32_bf16 v[108:111], v[148:151], v[214:217], v[108:111]
	v_mfma_f32_16x16x32_bf16 v[104:107], v[156:159], v[214:217], v[104:107]
	v_mfma_f32_16x16x32_bf16 v[92:95], v[148:151], v[228:231], v[92:95]
	v_mfma_f32_16x16x32_bf16 v[88:91], v[156:159], v[228:231], v[88:91]
	v_mfma_f32_16x16x32_bf16 v[76:79], v[148:151], v[236:239], v[76:79]
	v_mfma_f32_16x16x32_bf16 v[72:75], v[156:159], v[236:239], v[72:75]
	v_mfma_f32_16x16x32_bf16 v[116:119], v[160:163], v[202:205], v[116:119]
	v_mfma_f32_16x16x32_bf16 v[112:115], v[168:171], v[202:205], v[112:115]
	v_mfma_f32_16x16x32_bf16 v[100:103], v[160:163], v[210:213], v[100:103]
	v_mfma_f32_16x16x32_bf16 v[96:99], v[168:171], v[210:213], v[96:99]
	v_mfma_f32_16x16x32_bf16 v[84:87], v[160:163], v[218:221], v[84:87]
	v_mfma_f32_16x16x32_bf16 v[80:83], v[168:171], v[218:221], v[80:83]
	v_mfma_f32_16x16x32_bf16 v[68:71], v[160:163], v[232:235], v[68:71]
	v_mfma_f32_16x16x32_bf16 v[64:67], v[168:171], v[232:235], v[64:67]
	v_mfma_f32_16x16x32_bf16 v[116:119], v[164:167], v[206:209], v[116:119]
	v_mfma_f32_16x16x32_bf16 v[112:115], v[198:201], v[206:209], v[112:115]
	v_mfma_f32_16x16x32_bf16 v[100:103], v[164:167], v[214:217], v[100:103]
	v_mfma_f32_16x16x32_bf16 v[96:99], v[198:201], v[214:217], v[96:99]
	v_mfma_f32_16x16x32_bf16 v[84:87], v[164:167], v[228:231], v[84:87]
	v_mfma_f32_16x16x32_bf16 v[80:83], v[198:201], v[228:231], v[80:83]
	v_mfma_f32_16x16x32_bf16 v[68:71], v[164:167], v[236:239], v[68:71]
	v_mfma_f32_16x16x32_bf16 v[64:67], v[198:201], v[236:239], v[64:67]
	s_barrier
	s_add_i32 s36, s76, s66
	v_lshl_add_u64 v[194:195], s[54:55], 0, v[132:133]
	s_mov_b32 m0, s36
	ds_read_b128 v[202:205], v143 offset:16384
	ds_read_b128 v[206:209], v143 offset:17408
	ds_read_b128 v[210:213], v143 offset:18432
	ds_read_b128 v[214:217], v143 offset:19456
	ds_read_b128 v[218:221], v143 offset:20480
	ds_read_b128 v[228:231], v143 offset:21504
	ds_read_b128 v[232:235], v143 offset:22528
	ds_read_b128 v[236:239], v143 offset:23552
	global_load_lds_dwordx4 v[194:195], off
	s_add_i32 m0, s36, 0x2000
	s_add_u32 s36, s54, 0x30000
	v_lshl_add_u64 v[224:225], s[54:55], 0, v[128:129]
	s_addc_u32 s37, s55, 0
	s_add_i32 s76, s77, s66
	global_load_lds_dwordx4 v[224:225], off
	v_lshl_add_u64 v[240:241], s[36:37], 0, v[132:133]
	s_mov_b32 m0, s76
	v_lshl_add_u64 v[242:243], s[58:59], 0, v[130:131]
	global_load_lds_dwordx4 v[240:241], off
	v_lshl_add_u64 v[240:241], s[36:37], 0, v[128:129]
	s_add_i32 m0, s76, 0x2000
	s_nop 0
	global_load_lds_dwordx4 v[240:241], off
	v_lshl_add_u64 v[240:241], s[58:59], 0, v[134:135]
	s_mov_b32 m0, s67
	s_nop 0
	global_load_lds_dwordx4 v[240:241], off
	s_mov_b32 m0, s68
	s_nop 0
	global_load_lds_dwordx4 v[242:243], off
	s_waitcnt vmcnt(8)
	s_waitcnt lgkmcnt(0)
	s_barrier
; #define PG8_STAGE(bufoff, gbase, voff) do { _Pragma("unroll") for (int _i = 0; _i < 2; ++_i) \
;         __builtin_amdgcn_global_load_lds((const unsigned*)((const char*)(gbase) + (voff)[_i]), (LAS unsigned*)(lds + (bufoff) + ldsw + _i * 8192), 16, 0, 0); } while (0)
; #define PG8_LDA(dst, b, h) do { _Pragma("unroll") for (int m = 0; m < 4; ++m) _Pragma("unroll") for (int k = 0; k < 2; ++k) dst[m][k] = *(const LAS bf16x8*)(lds + PG8_SA(b, h) + aoff + m * 2048 + k * 1024); } while (0)
; #define PG8_LDB(dst, b, h) do { _Pragma("unroll") for (int n = 0; n < 2; ++n) _Pragma("unroll") for (int k = 0; k < 2; ++k) dst[n][k] = *(const LAS bf16x8*)(lds + PG8_SB(b, h) + boff + n * 2048 + k * 1024); } while (0)
; #define PG8_MMA(ai, bj, At, Bt) do { __builtin_amdgcn_s_setprio(1); _Pragma("unroll") for (int m = 0; m < 4; ++m) _Pragma("unroll") for (int n = 0; n < 2; ++n) _Pragma("unroll") for (int k = 0; k < 2; ++k) \
;         acc[ai][bj][m][n] = __builtin_amdgcn_mfma_f32_16x16x32_bf16(Bt[n][k], At[m][k], acc[ai][bj][m][n], 0, 0, 0); __builtin_amdgcn_s_setprio(0); } while (0)
; #define PG8_WAIT_V(n) asm volatile("s_waitcnt vmcnt(" #n ")" ::: "memory")
; #define PG8_WAIT_L(n) asm volatile("s_waitcnt lgkmcnt(" #n ")" ::: "memory")
; #define PG8_BAR __builtin_amdgcn_s_barrier()
; #define PG8_SCHED __builtin_amdgcn_sched_barrier(0)
; template <class Epi>
; __device__ __forceinline__ void gemm_phase(LAS unsigned char* lds, const Sched& S, const int K, const Epi& E) {
;     ...
;             PG8_WAIT_V(8); PG8_WAIT_L(0); PG8_BAR; PG8_MMA(1, 0, At, B0); PG8_MMA(1, 1, At, B1); PG8_BAR; PG8_SCHED;
;             PG8_LDB(B0, 1, 0); PG8_LDB(B1, 1, 1); PG8_SCHED; PG8_LDA(At, 1, 0); PG8_STAGE(PG8_SA(0, 1), a2 + hstepA, voffA);
;             PG8_WAIT_V(8); PG8_WAIT_L(0); PG8_BAR; PG8_MMA(0, 0, At, B0); PG8_MMA(0, 1, At, B1); PG8_BAR; PG8_SCHED;
	s_waitcnt lgkmcnt(0)
	v_mfma_f32_16x16x32_bf16 v[60:63], v[144:147], v[202:205], v[60:63]
	v_mfma_f32_16x16x32_bf16 v[56:59], v[152:155], v[202:205], v[56:59]
	v_mfma_f32_16x16x32_bf16 v[44:47], v[144:147], v[210:213], v[44:47]
	v_mfma_f32_16x16x32_bf16 v[40:43], v[152:155], v[210:213], v[40:43]
	v_mfma_f32_16x16x32_bf16 v[28:31], v[144:147], v[218:221], v[28:31]
	v_mfma_f32_16x16x32_bf16 v[24:27], v[152:155], v[218:221], v[24:27]
	v_mfma_f32_16x16x32_bf16 v[12:15], v[144:147], v[232:235], v[12:15]
	v_mfma_f32_16x16x32_bf16 v[8:11], v[152:155], v[232:235], v[8:11]
	v_mfma_f32_16x16x32_bf16 v[60:63], v[148:151], v[206:209], v[60:63]
	v_mfma_f32_16x16x32_bf16 v[56:59], v[156:159], v[206:209], v[56:59]
	v_mfma_f32_16x16x32_bf16 v[44:47], v[148:151], v[214:217], v[44:47]
	v_mfma_f32_16x16x32_bf16 v[40:43], v[156:159], v[214:217], v[40:43]
	v_mfma_f32_16x16x32_bf16 v[28:31], v[148:151], v[228:231], v[28:31]
	v_mfma_f32_16x16x32_bf16 v[24:27], v[156:159], v[228:231], v[24:27]
	v_mfma_f32_16x16x32_bf16 v[12:15], v[148:151], v[236:239], v[12:15]
	v_mfma_f32_16x16x32_bf16 v[8:11], v[156:159], v[236:239], v[8:11]
	v_mfma_f32_16x16x32_bf16 v[52:55], v[160:163], v[202:205], v[52:55]
	v_mfma_f32_16x16x32_bf16 v[48:51], v[168:171], v[202:205], v[48:51]
	v_mfma_f32_16x16x32_bf16 v[36:39], v[160:163], v[210:213], v[36:39]
	v_mfma_f32_16x16x32_bf16 v[32:35], v[168:171], v[210:213], v[32:35]
	v_mfma_f32_16x16x32_bf16 v[20:23], v[160:163], v[218:221], v[20:23]
	v_mfma_f32_16x16x32_bf16 v[16:19], v[168:171], v[218:221], v[16:19]
	v_mfma_f32_16x16x32_bf16 v[4:7], v[160:163], v[232:235], v[4:7]
	v_mfma_f32_16x16x32_bf16 v[0:3], v[168:171], v[232:235], v[0:3]
	v_mfma_f32_16x16x32_bf16 v[52:55], v[164:167], v[206:209], v[52:55]
	v_mfma_f32_16x16x32_bf16 v[48:51], v[198:201], v[206:209], v[48:51]
	v_mfma_f32_16x16x32_bf16 v[36:39], v[164:167], v[214:217], v[36:39]
	v_mfma_f32_16x16x32_bf16 v[32:35], v[198:201], v[214:217], v[32:35]
	v_mfma_f32_16x16x32_bf16 v[20:23], v[164:167], v[228:231], v[20:23]
	v_mfma_f32_16x16x32_bf16 v[16:19], v[198:201], v[228:231], v[16:19]
	v_mfma_f32_16x16x32_bf16 v[4:7], v[164:167], v[236:239], v[4:7]
	v_mfma_f32_16x16x32_bf16 v[0:3], v[198:201], v[236:239], v[0:3]
	s_barrier
	s_add_i32 s76, 0, 0x18000
	s_add_i32 s77, 0, 0x1c000
	v_add_u32_e32 v156, s76, v140
	v_add_u32_e32 v198, s77, v140
	ds_read_b128 v[144:147], v156
	ds_read_b128 v[148:151], v156 offset:1024
	ds_read_b128 v[152:155], v156 offset:2048
	ds_read_b128 v[156:159], v156 offset:3072
	ds_read_b128 v[160:163], v198
	ds_read_b128 v[164:167], v198 offset:1024
	ds_read_b128 v[168:171], v198 offset:2048
	ds_read_b128 v[198:201], v198 offset:3072
	s_add_u32 s36, s58, 0x30000
	s_addc_u32 s37, s59, 0
	s_mov_b32 m0, s69
	v_lshl_add_u64 v[244:245], s[36:37], 0, v[134:135]
	ds_read_b128 v[202:205], v143 offset:32768
	ds_read_b128 v[206:209], v143 offset:33792
	ds_read_b128 v[210:213], v143 offset:34816
	ds_read_b128 v[214:217], v143 offset:35840
	ds_read_b128 v[218:221], v143 offset:36864
	ds_read_b128 v[228:231], v143 offset:37888
	ds_read_b128 v[232:235], v143 offset:38912
	ds_read_b128 v[236:239], v143 offset:39936
	global_load_lds_dwordx4 v[244:245], off
	v_lshl_add_u64 v[244:245], s[36:37], 0, v[130:131]
	s_mov_b32 m0, s70
	s_nop 0
	global_load_lds_dwordx4 v[244:245], off
	s_waitcnt vmcnt(8)
	s_waitcnt lgkmcnt(0)
	s_barrier
	s_waitcnt lgkmcnt(0)
	v_mfma_f32_16x16x32_bf16 v[124:127], v[144:147], v[202:205], v[124:127]
	v_mfma_f32_16x16x32_bf16 v[120:123], v[152:155], v[202:205], v[120:123]
	v_mfma_f32_16x16x32_bf16 v[108:111], v[144:147], v[210:213], v[108:111]
	v_mfma_f32_16x16x32_bf16 v[104:107], v[152:155], v[210:213], v[104:107]
	v_mfma_f32_16x16x32_bf16 v[92:95], v[144:147], v[218:221], v[92:95]
	v_mfma_f32_16x16x32_bf16 v[88:91], v[152:155], v[218:221], v[88:91]
	v_mfma_f32_16x16x32_bf16 v[76:79], v[144:147], v[232:235], v[76:79]
	v_mfma_f32_16x16x32_bf16 v[72:75], v[152:155], v[232:235], v[72:75]
	v_mfma_f32_16x16x32_bf16 v[124:127], v[148:151], v[206:209], v[124:127]
	v_mfma_f32_16x16x32_bf16 v[120:123], v[156:159], v[206:209], v[120:123]
	v_mfma_f32_16x16x32_bf16 v[108:111], v[148:151], v[214:217], v[108:111]
	v_mfma_f32_16x16x32_bf16 v[104:107], v[156:159], v[214:217], v[104:107]
	v_mfma_f32_16x16x32_bf16 v[92:95], v[148:151], v[228:231], v[92:95]
	v_mfma_f32_16x16x32_bf16 v[88:91], v[156:159], v[228:231], v[88:91]
	v_mfma_f32_16x16x32_bf16 v[76:79], v[148:151], v[236:239], v[76:79]
	v_mfma_f32_16x16x32_bf16 v[72:75], v[156:159], v[236:239], v[72:75]
	v_mfma_f32_16x16x32_bf16 v[116:119], v[160:163], v[202:205], v[116:119]
	v_mfma_f32_16x16x32_bf16 v[112:115], v[168:171], v[202:205], v[112:115]
	v_mfma_f32_16x16x32_bf16 v[100:103], v[160:163], v[210:213], v[100:103]
	v_mfma_f32_16x16x32_bf16 v[96:99], v[168:171], v[210:213], v[96:99]
	v_mfma_f32_16x16x32_bf16 v[84:87], v[160:163], v[218:221], v[84:87]
	v_mfma_f32_16x16x32_bf16 v[80:83], v[168:171], v[218:221], v[80:83]
	v_mfma_f32_16x16x32_bf16 v[68:71], v[160:163], v[232:235], v[68:71]
	v_mfma_f32_16x16x32_bf16 v[64:67], v[168:171], v[232:235], v[64:67]
	v_mfma_f32_16x16x32_bf16 v[116:119], v[164:167], v[206:209], v[116:119]
	v_mfma_f32_16x16x32_bf16 v[112:115], v[198:201], v[206:209], v[112:115]
	v_mfma_f32_16x16x32_bf16 v[100:103], v[164:167], v[214:217], v[100:103]
	v_mfma_f32_16x16x32_bf16 v[96:99], v[198:201], v[214:217], v[96:99]
	v_mfma_f32_16x16x32_bf16 v[84:87], v[164:167], v[228:231], v[84:87]
	v_mfma_f32_16x16x32_bf16 v[80:83], v[198:201], v[228:231], v[80:83]
	v_mfma_f32_16x16x32_bf16 v[68:71], v[164:167], v[236:239], v[68:71]
	v_mfma_f32_16x16x32_bf16 v[64:67], v[198:201], v[236:239], v[64:67]
	s_barrier
; #define PG8_STAGE(bufoff, gbase, voff) do { _Pragma("unroll") for (int _i = 0; _i < 2; ++_i) \
;         __builtin_amdgcn_global_load_lds((const unsigned*)((const char*)(gbase) + (voff)[_i]), (LAS unsigned*)(lds + (bufoff) + ldsw + _i * 8192), 16, 0, 0); } while (0)
; #define PG8_LDA(dst, b, h) do { _Pragma("unroll") for (int m = 0; m < 4; ++m) _Pragma("unroll") for (int k = 0; k < 2; ++k) dst[m][k] = *(const LAS bf16x8*)(lds + PG8_SA(b, h) + aoff + m * 2048 + k * 1024); } while (0)
; #define PG8_MMA(ai, bj, At, Bt) do { __builtin_amdgcn_s_setprio(1); _Pragma("unroll") for (int m = 0; m < 4; ++m) _Pragma("unroll") for (int n = 0; n < 2; ++n) _Pragma("unroll") for (int k = 0; k < 2; ++k) \
;         acc[ai][bj][m][n] = __builtin_amdgcn_mfma_f32_16x16x32_bf16(Bt[n][k], At[m][k], acc[ai][bj][m][n], 0, 0, 0); __builtin_amdgcn_s_setprio(0); } while (0)
; #define PG8_WAIT_V(n) asm volatile("s_waitcnt vmcnt(" #n ")" ::: "memory")
; #define PG8_WAIT_L(n) asm volatile("s_waitcnt lgkmcnt(" #n ")" ::: "memory")
; #define PG8_BAR __builtin_amdgcn_s_barrier()
; #define PG8_SCHED __builtin_amdgcn_sched_barrier(0)
; template <class Epi>
; __device__ __forceinline__ void gemm_phase(LAS unsigned char* lds, const Sched& S, const int K, const Epi& E) {
;     ...
;             PG8_LDA(At, 1, 1); PG8_STAGE(PG8_SB(1, 0), b3, voffB); PG8_STAGE(PG8_SB(1, 1), b3 + hstepB, voffB); PG8_STAGE(PG8_SA(1, 0), a3, voffA);
;             PG8_WAIT_V(8); PG8_WAIT_L(0); PG8_BAR; PG8_MMA(1, 0, At, B0); PG8_MMA(1, 1, At, B1); PG8_BAR; PG8_SCHED;
;         }
	s_add_i32 s36, s76, s66
	v_lshl_add_u64 v[194:195], v[194:195], 0, s[74:75]
	s_mov_b32 m0, s36
	ds_read_b128 v[202:205], v143 offset:49152
	ds_read_b128 v[206:209], v143 offset:50176
	ds_read_b128 v[210:213], v143 offset:51200
	ds_read_b128 v[214:217], v143 offset:52224
	ds_read_b128 v[218:221], v143 offset:53248
	ds_read_b128 v[228:231], v143 offset:54272
	ds_read_b128 v[232:235], v143 offset:55296
	ds_read_b128 v[236:239], v143 offset:56320
	global_load_lds_dwordx4 v[194:195], off
	s_add_i32 m0, s36, 0x2000
	s_add_u32 s36, s54, 0x30080
	v_lshl_add_u64 v[194:195], v[224:225], 0, s[74:75]
	s_addc_u32 s37, s55, 0
	s_add_i32 s54, s77, s66
	global_load_lds_dwordx4 v[194:195], off
	v_lshl_add_u64 v[194:195], s[36:37], 0, v[132:133]
	s_mov_b32 m0, s54
	s_nop 0
	global_load_lds_dwordx4 v[194:195], off
	v_lshl_add_u64 v[194:195], s[36:37], 0, v[128:129]
	s_add_i32 m0, s54, 0x2000
	s_nop 0
	global_load_lds_dwordx4 v[194:195], off
	v_lshl_add_u64 v[194:195], v[240:241], 0, s[74:75]
	s_mov_b32 m0, s71
	s_nop 0
	global_load_lds_dwordx4 v[194:195], off
	v_lshl_add_u64 v[194:195], v[242:243], 0, s[74:75]
	s_mov_b32 m0, s72
	s_nop 0
	global_load_lds_dwordx4 v[194:195], off
	s_waitcnt vmcnt(8)
	s_waitcnt lgkmcnt(0)
	s_barrier
	s_waitcnt lgkmcnt(0)
	v_mfma_f32_16x16x32_bf16 v[60:63], v[144:147], v[202:205], v[60:63]
	v_mfma_f32_16x16x32_bf16 v[56:59], v[152:155], v[202:205], v[56:59]
	v_mfma_f32_16x16x32_bf16 v[44:47], v[144:147], v[210:213], v[44:47]
	v_mfma_f32_16x16x32_bf16 v[40:43], v[152:155], v[210:213], v[40:43]
	v_mfma_f32_16x16x32_bf16 v[28:31], v[144:147], v[218:221], v[28:31]
	v_mfma_f32_16x16x32_bf16 v[24:27], v[152:155], v[218:221], v[24:27]
	v_mfma_f32_16x16x32_bf16 v[12:15], v[144:147], v[232:235], v[12:15]
	v_mfma_f32_16x16x32_bf16 v[8:11], v[152:155], v[232:235], v[8:11]
	v_mfma_f32_16x16x32_bf16 v[60:63], v[148:151], v[206:209], v[60:63]
	v_mfma_f32_16x16x32_bf16 v[56:59], v[156:159], v[206:209], v[56:59]
	v_mfma_f32_16x16x32_bf16 v[44:47], v[148:151], v[214:217], v[44:47]
	v_mfma_f32_16x16x32_bf16 v[40:43], v[156:159], v[214:217], v[40:43]
	v_mfma_f32_16x16x32_bf16 v[28:31], v[148:151], v[228:231], v[28:31]
	v_mfma_f32_16x16x32_bf16 v[24:27], v[156:159], v[228:231], v[24:27]
	v_mfma_f32_16x16x32_bf16 v[12:15], v[148:151], v[236:239], v[12:15]
	v_mfma_f32_16x16x32_bf16 v[8:11], v[156:159], v[236:239], v[8:11]
	v_mfma_f32_16x16x32_bf16 v[52:55], v[160:163], v[202:205], v[52:55]
	v_mfma_f32_16x16x32_bf16 v[48:51], v[168:171], v[202:205], v[48:51]
	v_mfma_f32_16x16x32_bf16 v[36:39], v[160:163], v[210:213], v[36:39]
	v_mfma_f32_16x16x32_bf16 v[32:35], v[168:171], v[210:213], v[32:35]
	v_mfma_f32_16x16x32_bf16 v[20:23], v[160:163], v[218:221], v[20:23]
	v_mfma_f32_16x16x32_bf16 v[16:19], v[168:171], v[218:221], v[16:19]
	v_mfma_f32_16x16x32_bf16 v[4:7], v[160:163], v[232:235], v[4:7]
	v_mfma_f32_16x16x32_bf16 v[0:3], v[168:171], v[232:235], v[0:3]
	v_mfma_f32_16x16x32_bf16 v[52:55], v[164:167], v[206:209], v[52:55]
	v_mfma_f32_16x16x32_bf16 v[48:51], v[198:201], v[206:209], v[48:51]
	v_mfma_f32_16x16x32_bf16 v[36:39], v[164:167], v[214:217], v[36:39]
	v_mfma_f32_16x16x32_bf16 v[32:35], v[198:201], v[214:217], v[32:35]
	v_mfma_f32_16x16x32_bf16 v[20:23], v[164:167], v[228:231], v[20:23]
	v_mfma_f32_16x16x32_bf16 v[16:19], v[198:201], v[228:231], v[16:19]
	v_mfma_f32_16x16x32_bf16 v[4:7], v[164:167], v[236:239], v[4:7]
	v_mfma_f32_16x16x32_bf16 v[0:3], v[198:201], v[236:239], v[0:3]
	s_barrier
	s_add_i32 s96, s96, 2
	s_add_u32 vcc_lo, vcc_lo, 0x100
	s_addc_u32 vcc_hi, vcc_hi, 0
	s_cmp_gt_u32 s96, 9
	s_mov_b64 s[36:37], s[52:53]
	s_cbranch_scc0 .LBB0_834
	s_and_b64 vcc, exec, s[46:47]
	s_cbranch_vccz .LBB0_837
	s_barrier

; #define PG8_STAGE(bufoff, gbase, voff) do { _Pragma("unroll") for (int _i = 0; _i < 2; ++_i) \
;         __builtin_amdgcn_global_load_lds((const unsigned*)((const char*)(gbase) + (voff)[_i]), (LAS unsigned*)(lds + (bufoff) + ldsw + _i * 8192), 16, 0, 0); } while (0)
; #define PG8_LDA(dst, b, h) do { _Pragma("unroll") for (int m = 0; m < 4; ++m) _Pragma("unroll") for (int k = 0; k < 2; ++k) dst[m][k] = *(const LAS bf16x8*)(lds + PG8_SA(b, h) + aoff + m * 2048 + k * 1024); } while (0)
; #define PG8_LDB(dst, b, h) do { _Pragma("unroll") for (int n = 0; n < 2; ++n) _Pragma("unroll") for (int k = 0; k < 2; ++k) dst[n][k] = *(const LAS bf16x8*)(lds + PG8_SB(b, h) + boff + n * 2048 + k * 1024); } while (0)
; #define PG8_MMA(ai, bj, At, Bt) do { __builtin_amdgcn_s_setprio(1); _Pragma("unroll") for (int m = 0; m < 4; ++m) _Pragma("unroll") for (int n = 0; n < 2; ++n) _Pragma("unroll") for (int k = 0; k < 2; ++k) \
;         acc[ai][bj][m][n] = __builtin_amdgcn_mfma_f32_16x16x32_bf16(Bt[n][k], At[m][k], acc[ai][bj][m][n], 0, 0, 0); __builtin_amdgcn_s_setprio(0); } while (0)
; #define PG8_WAIT_V(n) asm volatile("s_waitcnt vmcnt(" #n ")" ::: "memory")
; #define PG8_WAIT_L(n) asm volatile("s_waitcnt lgkmcnt(" #n ")" ::: "memory")
; #define PG8_BAR __builtin_amdgcn_s_barrier()
; #define PG8_SCHED __builtin_amdgcn_sched_barrier(0)
; template <class Epi>
; __device__ __forceinline__ void gemm_phase(LAS unsigned char* lds, const Sched& S, const int K, const Epi& E) {
;     ...
;         for (int t = 0; t < nt; t += 2) {
;             const bool last = (t == nt - 2);
;             const char* a1 = cA + (size_t)(t + 1) * kstep;
;             const char* a2 = last ? nA : cA + (size_t)(t + 2) * kstep; const char* b2 = last ? nB : cB + (size_t)(t + 2) * kstep;
;             const char* a3 = a2 + kstep; const char* b3 = b2 + kstep;
;             PG8_LDB(B0, 0, 0); PG8_LDB(B1, 0, 1); PG8_SCHED; PG8_LDA(At, 0, 0); PG8_STAGE(PG8_SA(1, 1), a1 + hstepA, voffA);
;             PG8_WAIT_V(8); PG8_WAIT_L(0); PG8_BAR; PG8_MMA(0, 0, At, B0); PG8_MMA(0, 1, At, B1); PG8_BAR; PG8_SCHED;
;             PG8_LDA(At, 0, 1); PG8_STAGE(PG8_SB(0, 0), b2, voffB); PG8_STAGE(PG8_SB(0, 1), b2 + hstepB, voffB); PG8_STAGE(PG8_SA(0, 0), a2, voffA);
.LBB0_993:
	s_add_u32 s58, s36, 0x100
	s_addc_u32 s59, s37, 0
	s_add_i32 s76, 0, 0x10000
	s_cmp_eq_u32 s96, 8
	s_cselect_b32 vcc_hi, s29, s59
	s_cselect_b32 vcc_lo, s28, s58
	s_cselect_b32 s93, s35, s97
	s_cselect_b32 s92, s34, s64
	s_add_i32 s77, 0, 0x14000
	v_add_u32_e32 v52, s76, v229
	v_add_u32_e32 v140, s77, v229
	ds_read_b128 v[32:35], v52
	ds_read_b128 v[36:39], v52 offset:1024
	ds_read_b128 v[48:51], v52 offset:2048
	ds_read_b128 v[52:55], v52 offset:3072
	ds_read_b128 v[104:107], v140
	ds_read_b128 v[116:119], v140 offset:1024
	ds_read_b128 v[128:131], v140 offset:2048
	ds_read_b128 v[140:143], v140 offset:3072
	v_lshl_add_u64 v[194:195], s[36:37], 0, v[204:205]
	s_add_i32 m0, s69, 0xc000
	ds_read_b128 v[144:147], v231
	ds_read_b128 v[156:159], v231 offset:1024
	ds_read_b128 v[160:163], v231 offset:2048
	ds_read_b128 v[208:211], v231 offset:3072
	ds_read_b128 v[212:215], v231 offset:4096
	ds_read_b128 v[216:219], v231 offset:5120
	ds_read_b128 v[232:235], v231 offset:6144
	ds_read_b128 v[236:239], v231 offset:7168
	global_load_lds_dwordx4 v[194:195], off
	v_lshl_add_u64 v[194:195], s[36:37], 0, v[206:207]
	s_add_i32 m0, s69, 0xe000
	s_nop 0
	global_load_lds_dwordx4 v[194:195], off
	s_waitcnt vmcnt(8)
	s_waitcnt lgkmcnt(0)
	s_barrier
	s_waitcnt lgkmcnt(0)
	v_mfma_f32_16x16x32_bf16 v[168:171], v[32:35], v[144:147], v[168:171]
	v_mfma_f32_16x16x32_bf16 v[164:167], v[48:51], v[144:147], v[164:167]
	v_mfma_f32_16x16x32_bf16 v[136:139], v[32:35], v[160:163], v[136:139]
	v_mfma_f32_16x16x32_bf16 v[132:135], v[48:51], v[160:163], v[132:135]
	v_mfma_f32_16x16x32_bf16 v[112:115], v[32:35], v[212:215], v[112:115]
	v_mfma_f32_16x16x32_bf16 v[108:111], v[48:51], v[212:215], v[108:111]
	v_mfma_f32_16x16x32_bf16 v[92:95], v[32:35], v[232:235], v[92:95]
	v_mfma_f32_16x16x32_bf16 v[88:91], v[48:51], v[232:235], v[88:91]
	v_mfma_f32_16x16x32_bf16 v[168:171], v[36:39], v[156:159], v[168:171]
	v_mfma_f32_16x16x32_bf16 v[164:167], v[52:55], v[156:159], v[164:167]
	v_mfma_f32_16x16x32_bf16 v[136:139], v[36:39], v[208:211], v[136:139]
	v_mfma_f32_16x16x32_bf16 v[132:135], v[52:55], v[208:211], v[132:135]
	v_mfma_f32_16x16x32_bf16 v[112:115], v[36:39], v[216:219], v[112:115]
	v_mfma_f32_16x16x32_bf16 v[108:111], v[52:55], v[216:219], v[108:111]
	v_mfma_f32_16x16x32_bf16 v[92:95], v[36:39], v[236:239], v[92:95]
	v_mfma_f32_16x16x32_bf16 v[88:91], v[52:55], v[236:239], v[88:91]
	v_mfma_f32_16x16x32_bf16 v[152:155], v[104:107], v[144:147], v[152:155]
	v_mfma_f32_16x16x32_bf16 v[124:127], v[104:107], v[160:163], v[124:127]
	v_mfma_f32_16x16x32_bf16 v[120:123], v[128:131], v[160:163], v[120:123]
	v_mfma_f32_16x16x32_bf16 v[100:103], v[104:107], v[212:215], v[100:103]
	v_mfma_f32_16x16x32_bf16 v[96:99], v[128:131], v[212:215], v[96:99]
	v_mfma_f32_16x16x32_bf16 v[84:87], v[104:107], v[232:235], v[84:87]
	v_mfma_f32_16x16x32_bf16 v[80:83], v[128:131], v[232:235], v[80:83]
	v_mfma_f32_16x16x32_bf16 v[152:155], v[116:119], v[156:159], v[152:155]
	v_mfma_f32_16x16x32_bf16 v[144:147], v[128:131], v[144:147], v[148:151]
	v_mfma_f32_16x16x32_bf16 v[124:127], v[116:119], v[208:211], v[124:127]
	v_mfma_f32_16x16x32_bf16 v[120:123], v[140:143], v[208:211], v[120:123]
	v_mfma_f32_16x16x32_bf16 v[100:103], v[116:119], v[216:219], v[100:103]
	v_mfma_f32_16x16x32_bf16 v[96:99], v[140:143], v[216:219], v[96:99]
	v_mfma_f32_16x16x32_bf16 v[84:87], v[116:119], v[236:239], v[84:87]
	v_mfma_f32_16x16x32_bf16 v[80:83], v[140:143], v[236:239], v[80:83]
	v_mfma_f32_16x16x32_bf16 v[144:147], v[140:143], v[156:159], v[144:147]
	s_barrier
	s_add_i32 s36, s76, s68
	v_lshl_add_u64 v[194:195], s[92:93], 0, v[172:173]
	s_mov_b32 m0, s36
	ds_read_b128 v[148:151], v231 offset:16384
	ds_read_b128 v[156:159], v231 offset:17408
	ds_read_b128 v[160:163], v231 offset:18432
	ds_read_b128 v[208:211], v231 offset:19456
	ds_read_b128 v[212:215], v231 offset:20480
	ds_read_b128 v[216:219], v231 offset:21504
	ds_read_b128 v[232:235], v231 offset:22528
	ds_read_b128 v[236:239], v231 offset:23552
	global_load_lds_dwordx4 v[194:195], off
	s_add_i32 m0, s36, 0x2000
	s_add_u32 s36, s92, 0x30000
	v_lshl_add_u64 v[220:221], s[92:93], 0, v[198:199]
	s_addc_u32 s37, s93, 0
	s_add_i32 s76, s77, s68
	global_load_lds_dwordx4 v[220:221], off
	v_lshl_add_u64 v[224:225], s[36:37], 0, v[172:173]
	s_mov_b32 m0, s76
	v_lshl_add_u64 v[240:241], vcc, 0, v[200:201]
	global_load_lds_dwordx4 v[224:225], off
	v_lshl_add_u64 v[224:225], s[36:37], 0, v[198:199]
	s_add_i32 m0, s76, 0x2000
	s_nop 0
	global_load_lds_dwordx4 v[224:225], off
	v_lshl_add_u64 v[224:225], vcc, 0, v[202:203]
	s_mov_b32 m0, s69
	s_nop 0
	global_load_lds_dwordx4 v[224:225], off
	s_mov_b32 m0, s70
	s_nop 0
	global_load_lds_dwordx4 v[240:241], off
	s_waitcnt vmcnt(8)
	s_waitcnt lgkmcnt(0)
	s_barrier
; #define PG8_STAGE(bufoff, gbase, voff) do { _Pragma("unroll") for (int _i = 0; _i < 2; ++_i) \
;         __builtin_amdgcn_global_load_lds((const unsigned*)((const char*)(gbase) + (voff)[_i]), (LAS unsigned*)(lds + (bufoff) + ldsw + _i * 8192), 16, 0, 0); } while (0)
; #define PG8_LDA(dst, b, h) do { _Pragma("unroll") for (int m = 0; m < 4; ++m) _Pragma("unroll") for (int k = 0; k < 2; ++k) dst[m][k] = *(const LAS bf16x8*)(lds + PG8_SA(b, h) + aoff + m * 2048 + k * 1024); } while (0)
; #define PG8_LDB(dst, b, h) do { _Pragma("unroll") for (int n = 0; n < 2; ++n) _Pragma("unroll") for (int k = 0; k < 2; ++k) dst[n][k] = *(const LAS bf16x8*)(lds + PG8_SB(b, h) + boff + n * 2048 + k * 1024); } while (0)
; #define PG8_MMA(ai, bj, At, Bt) do { __builtin_amdgcn_s_setprio(1); _Pragma("unroll") for (int m = 0; m < 4; ++m) _Pragma("unroll") for (int n = 0; n < 2; ++n) _Pragma("unroll") for (int k = 0; k < 2; ++k) \
;         acc[ai][bj][m][n] = __builtin_amdgcn_mfma_f32_16x16x32_bf16(Bt[n][k], At[m][k], acc[ai][bj][m][n], 0, 0, 0); __builtin_amdgcn_s_setprio(0); } while (0)
; #define PG8_WAIT_V(n) asm volatile("s_waitcnt vmcnt(" #n ")" ::: "memory")
; #define PG8_WAIT_L(n) asm volatile("s_waitcnt lgkmcnt(" #n ")" ::: "memory")
; #define PG8_BAR __builtin_amdgcn_s_barrier()
; #define PG8_SCHED __builtin_amdgcn_sched_barrier(0)
; template <class Epi>
; __device__ __forceinline__ void gemm_phase(LAS unsigned char* lds, const Sched& S, const int K, const Epi& E) {
;     ...
;             PG8_WAIT_V(8); PG8_WAIT_L(0); PG8_BAR; PG8_MMA(1, 0, At, B0); PG8_MMA(1, 1, At, B1); PG8_BAR; PG8_SCHED;
;             PG8_LDB(B0, 1, 0); PG8_LDB(B1, 1, 1); PG8_SCHED; PG8_LDA(At, 1, 0); PG8_STAGE(PG8_SA(0, 1), a2 + hstepA, voffA);
;             PG8_WAIT_V(8); PG8_WAIT_L(0); PG8_BAR; PG8_MMA(0, 0, At, B0); PG8_MMA(0, 1, At, B1); PG8_BAR; PG8_SCHED;
	s_waitcnt lgkmcnt(0)
	v_mfma_f32_16x16x32_bf16 v[76:79], v[32:35], v[148:151], v[76:79]
	v_mfma_f32_16x16x32_bf16 v[72:75], v[48:51], v[148:151], v[72:75]
	v_mfma_f32_16x16x32_bf16 v[60:63], v[32:35], v[160:163], v[60:63]
	v_mfma_f32_16x16x32_bf16 v[56:59], v[48:51], v[160:163], v[56:59]
	v_mfma_f32_16x16x32_bf16 v[28:31], v[32:35], v[212:215], v[28:31]
	v_mfma_f32_16x16x32_bf16 v[24:27], v[48:51], v[212:215], v[24:27]
	v_mfma_f32_16x16x32_bf16 v[12:15], v[32:35], v[232:235], v[12:15]
	v_mfma_f32_16x16x32_bf16 v[8:11], v[48:51], v[232:235], v[8:11]
	v_mfma_f32_16x16x32_bf16 v[76:79], v[36:39], v[156:159], v[76:79]
	v_mfma_f32_16x16x32_bf16 v[72:75], v[52:55], v[156:159], v[72:75]
	v_mfma_f32_16x16x32_bf16 v[60:63], v[36:39], v[208:211], v[60:63]
	v_mfma_f32_16x16x32_bf16 v[56:59], v[52:55], v[208:211], v[56:59]
	v_mfma_f32_16x16x32_bf16 v[28:31], v[36:39], v[216:219], v[28:31]
	v_mfma_f32_16x16x32_bf16 v[24:27], v[52:55], v[216:219], v[24:27]
	v_mfma_f32_16x16x32_bf16 v[12:15], v[36:39], v[236:239], v[12:15]
	v_mfma_f32_16x16x32_bf16 v[8:11], v[52:55], v[236:239], v[8:11]
	v_mfma_f32_16x16x32_bf16 v[44:47], v[104:107], v[160:163], v[44:47]
	v_mfma_f32_16x16x32_bf16 v[40:43], v[128:131], v[160:163], v[40:43]
	v_mfma_f32_16x16x32_bf16 v[20:23], v[104:107], v[212:215], v[20:23]
	v_mfma_f32_16x16x32_bf16 v[16:19], v[128:131], v[212:215], v[16:19]
	v_mfma_f32_16x16x32_bf16 v[4:7], v[104:107], v[232:235], v[4:7]
	v_mfma_f32_16x16x32_bf16 v[0:3], v[128:131], v[232:235], v[0:3]
	v_mfma_f32_16x16x32_bf16 v[32:35], v[104:107], v[148:151], v[68:71]
	v_mfma_f32_16x16x32_bf16 v[36:39], v[128:131], v[148:151], v[64:67]
	v_mfma_f32_16x16x32_bf16 v[44:47], v[116:119], v[208:211], v[44:47]
	v_mfma_f32_16x16x32_bf16 v[40:43], v[140:143], v[208:211], v[40:43]
	v_mfma_f32_16x16x32_bf16 v[20:23], v[116:119], v[216:219], v[20:23]
	v_mfma_f32_16x16x32_bf16 v[16:19], v[140:143], v[216:219], v[16:19]
	v_mfma_f32_16x16x32_bf16 v[4:7], v[116:119], v[236:239], v[4:7]
	v_mfma_f32_16x16x32_bf16 v[0:3], v[140:143], v[236:239], v[0:3]
	v_mfma_f32_16x16x32_bf16 v[32:35], v[116:119], v[156:159], v[32:35]
	v_mfma_f32_16x16x32_bf16 v[36:39], v[140:143], v[156:159], v[36:39]
	s_barrier
	s_add_i32 s76, 0, 0x18000
	s_add_i32 s77, 0, 0x1c000
	v_add_u32_e32 v68, s76, v229
	v_add_u32_e32 v140, s77, v229
	ds_read_b128 v[48:51], v68
	ds_read_b128 v[52:55], v68 offset:1024
	ds_read_b128 v[64:67], v68 offset:2048
	ds_read_b128 v[68:71], v68 offset:3072
	ds_read_b128 v[104:107], v140
	ds_read_b128 v[116:119], v140 offset:1024
	ds_read_b128 v[128:131], v140 offset:2048
	ds_read_b128 v[140:143], v140 offset:3072
	s_add_u32 s36, vcc_lo, 0x30000
	s_addc_u32 s37, vcc_hi, 0
	s_mov_b32 m0, s71
	v_lshl_add_u64 v[242:243], s[36:37], 0, v[202:203]
	ds_read_b128 v[148:151], v231 offset:32768
	ds_read_b128 v[156:159], v231 offset:33792
	ds_read_b128 v[160:163], v231 offset:34816
	ds_read_b128 v[208:211], v231 offset:35840
	ds_read_b128 v[212:215], v231 offset:36864
	ds_read_b128 v[216:219], v231 offset:37888
	ds_read_b128 v[232:235], v231 offset:38912
	ds_read_b128 v[236:239], v231 offset:39936
	global_load_lds_dwordx4 v[242:243], off
	v_lshl_add_u64 v[242:243], s[36:37], 0, v[200:201]
	s_mov_b32 m0, s72
	s_nop 0
	global_load_lds_dwordx4 v[242:243], off
	s_waitcnt vmcnt(8)
	s_waitcnt lgkmcnt(0)
	s_barrier
	s_waitcnt lgkmcnt(0)
	v_mfma_f32_16x16x32_bf16 v[168:171], v[48:51], v[148:151], v[168:171]
	v_mfma_f32_16x16x32_bf16 v[164:167], v[64:67], v[148:151], v[164:167]
	v_mfma_f32_16x16x32_bf16 v[136:139], v[48:51], v[160:163], v[136:139]
	v_mfma_f32_16x16x32_bf16 v[132:135], v[64:67], v[160:163], v[132:135]
	v_mfma_f32_16x16x32_bf16 v[112:115], v[48:51], v[212:215], v[112:115]
	v_mfma_f32_16x16x32_bf16 v[108:111], v[64:67], v[212:215], v[108:111]
	v_mfma_f32_16x16x32_bf16 v[92:95], v[48:51], v[232:235], v[92:95]
	v_mfma_f32_16x16x32_bf16 v[88:91], v[64:67], v[232:235], v[88:91]
	v_mfma_f32_16x16x32_bf16 v[168:171], v[52:55], v[156:159], v[168:171]
	v_mfma_f32_16x16x32_bf16 v[164:167], v[68:71], v[156:159], v[164:167]
	v_mfma_f32_16x16x32_bf16 v[136:139], v[52:55], v[208:211], v[136:139]
	v_mfma_f32_16x16x32_bf16 v[132:135], v[68:71], v[208:211], v[132:135]
	v_mfma_f32_16x16x32_bf16 v[112:115], v[52:55], v[216:219], v[112:115]
	v_mfma_f32_16x16x32_bf16 v[108:111], v[68:71], v[216:219], v[108:111]
	v_mfma_f32_16x16x32_bf16 v[92:95], v[52:55], v[236:239], v[92:95]
	v_mfma_f32_16x16x32_bf16 v[88:91], v[68:71], v[236:239], v[88:91]
	v_mfma_f32_16x16x32_bf16 v[152:155], v[104:107], v[148:151], v[152:155]
	v_mfma_f32_16x16x32_bf16 v[144:147], v[128:131], v[148:151], v[144:147]
	v_mfma_f32_16x16x32_bf16 v[124:127], v[104:107], v[160:163], v[124:127]
	v_mfma_f32_16x16x32_bf16 v[120:123], v[128:131], v[160:163], v[120:123]
	v_mfma_f32_16x16x32_bf16 v[100:103], v[104:107], v[212:215], v[100:103]
	v_mfma_f32_16x16x32_bf16 v[96:99], v[128:131], v[212:215], v[96:99]
	v_mfma_f32_16x16x32_bf16 v[84:87], v[104:107], v[232:235], v[84:87]
	v_mfma_f32_16x16x32_bf16 v[80:83], v[128:131], v[232:235], v[80:83]
	v_mfma_f32_16x16x32_bf16 v[152:155], v[116:119], v[156:159], v[152:155]
	v_mfma_f32_16x16x32_bf16 v[148:151], v[140:143], v[156:159], v[144:147]
	v_mfma_f32_16x16x32_bf16 v[124:127], v[116:119], v[208:211], v[124:127]
	v_mfma_f32_16x16x32_bf16 v[120:123], v[140:143], v[208:211], v[120:123]
	v_mfma_f32_16x16x32_bf16 v[100:103], v[116:119], v[216:219], v[100:103]
	v_mfma_f32_16x16x32_bf16 v[96:99], v[140:143], v[216:219], v[96:99]
	v_mfma_f32_16x16x32_bf16 v[84:87], v[116:119], v[236:239], v[84:87]
	v_mfma_f32_16x16x32_bf16 v[80:83], v[140:143], v[236:239], v[80:83]
	s_barrier
; #define PG8_STAGE(bufoff, gbase, voff) do { _Pragma("unroll") for (int _i = 0; _i < 2; ++_i) \
;         __builtin_amdgcn_global_load_lds((const unsigned*)((const char*)(gbase) + (voff)[_i]), (LAS unsigned*)(lds + (bufoff) + ldsw + _i * 8192), 16, 0, 0); } while (0)
; #define PG8_LDA(dst, b, h) do { _Pragma("unroll") for (int m = 0; m < 4; ++m) _Pragma("unroll") for (int k = 0; k < 2; ++k) dst[m][k] = *(const LAS bf16x8*)(lds + PG8_SA(b, h) + aoff + m * 2048 + k * 1024); } while (0)
; #define PG8_MMA(ai, bj, At, Bt) do { __builtin_amdgcn_s_setprio(1); _Pragma("unroll") for (int m = 0; m < 4; ++m) _Pragma("unroll") for (int n = 0; n < 2; ++n) _Pragma("unroll") for (int k = 0; k < 2; ++k) \
;         acc[ai][bj][m][n] = __builtin_amdgcn_mfma_f32_16x16x32_bf16(Bt[n][k], At[m][k], acc[ai][bj][m][n], 0, 0, 0); __builtin_amdgcn_s_setprio(0); } while (0)
; #define PG8_WAIT_V(n) asm volatile("s_waitcnt vmcnt(" #n ")" ::: "memory")
; #define PG8_WAIT_L(n) asm volatile("s_waitcnt lgkmcnt(" #n ")" ::: "memory")
; #define PG8_BAR __builtin_amdgcn_s_barrier()
; #define PG8_SCHED __builtin_amdgcn_sched_barrier(0)
; template <class Epi>
; __device__ __forceinline__ void gemm_phase(LAS unsigned char* lds, const Sched& S, const int K, const Epi& E) {
;     ...
;             PG8_LDA(At, 1, 1); PG8_STAGE(PG8_SB(1, 0), b3, voffB); PG8_STAGE(PG8_SB(1, 1), b3 + hstepB, voffB); PG8_STAGE(PG8_SA(1, 0), a3, voffA);
;             PG8_WAIT_V(8); PG8_WAIT_L(0); PG8_BAR; PG8_MMA(1, 0, At, B0); PG8_MMA(1, 1, At, B1); PG8_BAR; PG8_SCHED;
;         }
	s_add_i32 s36, s76, s68
	v_lshl_add_u64 v[194:195], v[194:195], 0, s[74:75]
	s_mov_b32 m0, s36
	ds_read_b128 v[144:147], v231 offset:49152
	ds_read_b128 v[156:159], v231 offset:50176
	ds_read_b128 v[160:163], v231 offset:51200
	ds_read_b128 v[208:211], v231 offset:52224
	ds_read_b128 v[212:215], v231 offset:53248
	ds_read_b128 v[216:219], v231 offset:54272
	ds_read_b128 v[232:235], v231 offset:55296
	ds_read_b128 v[236:239], v231 offset:56320
	global_load_lds_dwordx4 v[194:195], off
	s_add_i32 m0, s36, 0x2000
	s_add_u32 s36, s92, 0x30080
	v_lshl_add_u64 v[194:195], v[220:221], 0, s[74:75]
	s_addc_u32 s37, s93, 0
	s_add_i32 s76, s77, s68
	global_load_lds_dwordx4 v[194:195], off
	v_lshl_add_u64 v[194:195], s[36:37], 0, v[172:173]
	s_mov_b32 m0, s76
	s_nop 0
	global_load_lds_dwordx4 v[194:195], off
	v_lshl_add_u64 v[194:195], s[36:37], 0, v[198:199]
	s_add_i32 m0, s76, 0x2000
	s_nop 0
	global_load_lds_dwordx4 v[194:195], off
	v_lshl_add_u64 v[194:195], v[224:225], 0, s[74:75]
	s_mov_b32 m0, s2
	s_nop 0
	global_load_lds_dwordx4 v[194:195], off
	v_lshl_add_u64 v[194:195], v[240:241], 0, s[74:75]
	s_mov_b32 m0, s73
	s_nop 0
	global_load_lds_dwordx4 v[194:195], off
	s_waitcnt vmcnt(8)
	s_waitcnt lgkmcnt(0)
	s_barrier
	s_waitcnt lgkmcnt(0)
	v_mfma_f32_16x16x32_bf16 v[76:79], v[48:51], v[144:147], v[76:79]
	v_mfma_f32_16x16x32_bf16 v[72:75], v[64:67], v[144:147], v[72:75]
	v_mfma_f32_16x16x32_bf16 v[60:63], v[48:51], v[160:163], v[60:63]
	v_mfma_f32_16x16x32_bf16 v[56:59], v[64:67], v[160:163], v[56:59]
	v_mfma_f32_16x16x32_bf16 v[28:31], v[48:51], v[212:215], v[28:31]
	v_mfma_f32_16x16x32_bf16 v[24:27], v[64:67], v[212:215], v[24:27]
	v_mfma_f32_16x16x32_bf16 v[12:15], v[48:51], v[232:235], v[12:15]
	v_mfma_f32_16x16x32_bf16 v[8:11], v[64:67], v[232:235], v[8:11]
	v_mfma_f32_16x16x32_bf16 v[76:79], v[52:55], v[156:159], v[76:79]
	v_mfma_f32_16x16x32_bf16 v[72:75], v[68:71], v[156:159], v[72:75]
	v_mfma_f32_16x16x32_bf16 v[60:63], v[52:55], v[208:211], v[60:63]
	v_mfma_f32_16x16x32_bf16 v[56:59], v[68:71], v[208:211], v[56:59]
	v_mfma_f32_16x16x32_bf16 v[28:31], v[52:55], v[216:219], v[28:31]
	v_mfma_f32_16x16x32_bf16 v[24:27], v[68:71], v[216:219], v[24:27]
	v_mfma_f32_16x16x32_bf16 v[12:15], v[52:55], v[236:239], v[12:15]
	v_mfma_f32_16x16x32_bf16 v[8:11], v[68:71], v[236:239], v[8:11]
	v_mfma_f32_16x16x32_bf16 v[32:35], v[104:107], v[144:147], v[32:35]
	v_mfma_f32_16x16x32_bf16 v[68:71], v[116:119], v[156:159], v[32:35]
	v_mfma_f32_16x16x32_bf16 v[32:35], v[128:131], v[144:147], v[36:39]
	v_mfma_f32_16x16x32_bf16 v[64:67], v[140:143], v[156:159], v[32:35]
	v_mfma_f32_16x16x32_bf16 v[32:35], v[104:107], v[160:163], v[44:47]
	v_mfma_f32_16x16x32_bf16 v[44:47], v[116:119], v[208:211], v[32:35]
	v_mfma_f32_16x16x32_bf16 v[32:35], v[128:131], v[160:163], v[40:43]
	v_mfma_f32_16x16x32_bf16 v[20:23], v[104:107], v[212:215], v[20:23]
	v_mfma_f32_16x16x32_bf16 v[16:19], v[128:131], v[212:215], v[16:19]
	v_mfma_f32_16x16x32_bf16 v[4:7], v[104:107], v[232:235], v[4:7]
	v_mfma_f32_16x16x32_bf16 v[0:3], v[128:131], v[232:235], v[0:3]
	v_mfma_f32_16x16x32_bf16 v[40:43], v[140:143], v[208:211], v[32:35]
	v_mfma_f32_16x16x32_bf16 v[20:23], v[116:119], v[216:219], v[20:23]
	v_mfma_f32_16x16x32_bf16 v[16:19], v[140:143], v[216:219], v[16:19]
	v_mfma_f32_16x16x32_bf16 v[4:7], v[116:119], v[236:239], v[4:7]
	v_mfma_f32_16x16x32_bf16 v[0:3], v[140:143], v[236:239], v[0:3]
	s_barrier
	s_add_i32 s96, s96, 2
	s_add_u32 s64, s64, 0x100
	s_addc_u32 s97, s97, 0
	s_cmp_gt_u32 s96, 9
	s_mov_b64 s[36:37], s[58:59]
	s_cbranch_scc0 .LBB0_993
	s_and_b64 vcc, exec, s[50:51]
	s_cbranch_vccz .LBB0_996
	s_barrier

; #define PG8_STAGE(bufoff, gbase, voff) do { _Pragma("unroll") for (int _i = 0; _i < 2; ++_i) \
;         __builtin_amdgcn_global_load_lds((const unsigned*)((const char*)(gbase) + (voff)[_i]), (LAS unsigned*)(lds + (bufoff) + ldsw + _i * 8192), 16, 0, 0); } while (0)
; #define PG8_LDA(dst, b, h) do { _Pragma("unroll") for (int m = 0; m < 4; ++m) _Pragma("unroll") for (int k = 0; k < 2; ++k) dst[m][k] = *(const LAS bf16x8*)(lds + PG8_SA(b, h) + aoff + m * 2048 + k * 1024); } while (0)
; #define PG8_LDB(dst, b, h) do { _Pragma("unroll") for (int n = 0; n < 2; ++n) _Pragma("unroll") for (int k = 0; k < 2; ++k) dst[n][k] = *(const LAS bf16x8*)(lds + PG8_SB(b, h) + boff + n * 2048 + k * 1024); } while (0)
; #define PG8_MMA(ai, bj, At, Bt) do { __builtin_amdgcn_s_setprio(1); _Pragma("unroll") for (int m = 0; m < 4; ++m) _Pragma("unroll") for (int n = 0; n < 2; ++n) _Pragma("unroll") for (int k = 0; k < 2; ++k) \
;         acc[ai][bj][m][n] = __builtin_amdgcn_mfma_f32_16x16x32_bf16(Bt[n][k], At[m][k], acc[ai][bj][m][n], 0, 0, 0); __builtin_amdgcn_s_setprio(0); } while (0)
; #define PG8_WAIT_V(n) asm volatile("s_waitcnt vmcnt(" #n ")" ::: "memory")
; #define PG8_WAIT_L(n) asm volatile("s_waitcnt lgkmcnt(" #n ")" ::: "memory")
; #define PG8_BAR __builtin_amdgcn_s_barrier()
; #define PG8_SCHED __builtin_amdgcn_sched_barrier(0)
; template <class Epi>
; __device__ __forceinline__ void gemm_phase(LAS unsigned char* lds, const Sched& S, const int K, const Epi& E) {
;     ...
;         for (int t = 0; t < nt; t += 2) {
;             const bool last = (t == nt - 2);
;             const char* a1 = cA + (size_t)(t + 1) * kstep;
;             const char* a2 = last ? nA : cA + (size_t)(t + 2) * kstep; const char* b2 = last ? nB : cB + (size_t)(t + 2) * kstep;
;             const char* a3 = a2 + kstep; const char* b3 = b2 + kstep;
;             PG8_LDB(B0, 0, 0); PG8_LDB(B1, 0, 1); PG8_SCHED; PG8_LDA(At, 0, 0); PG8_STAGE(PG8_SA(1, 1), a1 + hstepA, voffA);
;             PG8_WAIT_V(8); PG8_WAIT_L(0); PG8_BAR; PG8_MMA(0, 0, At, B0); PG8_MMA(0, 1, At, B1); PG8_BAR; PG8_SCHED;
;             PG8_LDA(At, 0, 1); PG8_STAGE(PG8_SB(0, 0), b2, voffB); PG8_STAGE(PG8_SB(0, 1), b2 + hstepB, voffB); PG8_STAGE(PG8_SA(0, 0), a2, voffA);
.LBB0_1239:
	s_add_u32 s52, s36, 0xfff80080
	s_addc_u32 s53, s37, -1
	s_add_i32 s76, 0, 0x10000
	s_cmp_eq_u32 vcc_lo, 28
	s_cselect_b32 s55, s29, s53
	s_cselect_b32 s54, s28, s52
	s_cselect_b32 s53, s35, s97
	s_cselect_b32 s52, s34, s47
	s_add_i32 s78, 0, 0x14000
	v_add_u32_e32 v140, s76, v165
	v_add_u32_e32 v162, s78, v165
	ds_read_b128 v[128:131], v140
	ds_read_b128 v[132:135], v140 offset:1024
	ds_read_b128 v[136:139], v140 offset:2048
	ds_read_b128 v[140:143], v140 offset:3072
	ds_read_b128 v[144:147], v162
	ds_read_b128 v[148:151], v162 offset:1024
	ds_read_b128 v[152:155], v162 offset:2048
	ds_read_b128 v[168:171], v162 offset:3072
	v_lshl_add_u64 v[162:163], s[36:37], 0, v[160:161]
	s_add_i32 m0, s60, 0xc000
	ds_read_b128 v[198:201], v167
	ds_read_b128 v[202:205], v167 offset:1024
	ds_read_b128 v[206:209], v167 offset:2048
	ds_read_b128 v[210:213], v167 offset:3072
	ds_read_b128 v[214:217], v167 offset:4096
	ds_read_b128 v[218:221], v167 offset:5120
	ds_read_b128 v[228:231], v167 offset:6144
	ds_read_b128 v[232:235], v167 offset:7168
	global_load_lds_dwordx4 v[162:163], off
	v_lshl_add_u64 v[162:163], s[36:37], 0, v[158:159]
	s_add_i32 m0, s60, 0xe000
	s_nop 0
	global_load_lds_dwordx4 v[162:163], off
	s_waitcnt vmcnt(8)
	s_waitcnt lgkmcnt(0)
	s_barrier
	s_waitcnt lgkmcnt(0)
	v_mfma_f32_16x16x32_bf16 v[124:127], v[128:131], v[198:201], v[124:127]
	v_mfma_f32_16x16x32_bf16 v[120:123], v[136:139], v[198:201], v[120:123]
	v_mfma_f32_16x16x32_bf16 v[116:119], v[128:131], v[206:209], v[116:119]
	v_mfma_f32_16x16x32_bf16 v[104:107], v[136:139], v[206:209], v[104:107]
	v_mfma_f32_16x16x32_bf16 v[100:103], v[128:131], v[214:217], v[100:103]
	v_mfma_f32_16x16x32_bf16 v[88:91], v[136:139], v[214:217], v[88:91]
	v_mfma_f32_16x16x32_bf16 v[84:87], v[128:131], v[228:231], v[84:87]
	v_mfma_f32_16x16x32_bf16 v[72:75], v[136:139], v[228:231], v[72:75]
	v_mfma_f32_16x16x32_bf16 v[124:127], v[132:135], v[202:205], v[124:127]
	v_mfma_f32_16x16x32_bf16 v[120:123], v[140:143], v[202:205], v[120:123]
	v_mfma_f32_16x16x32_bf16 v[116:119], v[132:135], v[210:213], v[116:119]
	v_mfma_f32_16x16x32_bf16 v[104:107], v[140:143], v[210:213], v[104:107]
	v_mfma_f32_16x16x32_bf16 v[100:103], v[132:135], v[218:221], v[100:103]
	v_mfma_f32_16x16x32_bf16 v[88:91], v[140:143], v[218:221], v[88:91]
	v_mfma_f32_16x16x32_bf16 v[84:87], v[132:135], v[232:235], v[84:87]
	v_mfma_f32_16x16x32_bf16 v[72:75], v[140:143], v[232:235], v[72:75]
	v_mfma_f32_16x16x32_bf16 v[112:115], v[144:147], v[198:201], v[112:115]
	v_mfma_f32_16x16x32_bf16 v[108:111], v[152:155], v[198:201], v[108:111]
	v_mfma_f32_16x16x32_bf16 v[96:99], v[144:147], v[206:209], v[96:99]
	v_mfma_f32_16x16x32_bf16 v[92:95], v[152:155], v[206:209], v[92:95]
	v_mfma_f32_16x16x32_bf16 v[80:83], v[144:147], v[214:217], v[80:83]
	v_mfma_f32_16x16x32_bf16 v[76:79], v[152:155], v[214:217], v[76:79]
	v_mfma_f32_16x16x32_bf16 v[68:71], v[144:147], v[228:231], v[68:71]
	v_mfma_f32_16x16x32_bf16 v[64:67], v[152:155], v[228:231], v[64:67]
	v_mfma_f32_16x16x32_bf16 v[112:115], v[148:151], v[202:205], v[112:115]
	v_mfma_f32_16x16x32_bf16 v[108:111], v[168:171], v[202:205], v[108:111]
	v_mfma_f32_16x16x32_bf16 v[96:99], v[148:151], v[210:213], v[96:99]
	v_mfma_f32_16x16x32_bf16 v[92:95], v[168:171], v[210:213], v[92:95]
	v_mfma_f32_16x16x32_bf16 v[80:83], v[148:151], v[218:221], v[80:83]
	v_mfma_f32_16x16x32_bf16 v[76:79], v[168:171], v[218:221], v[76:79]
	v_mfma_f32_16x16x32_bf16 v[68:71], v[148:151], v[232:235], v[68:71]
	v_mfma_f32_16x16x32_bf16 v[64:67], v[168:171], v[232:235], v[64:67]
	s_barrier
	s_add_i32 s76, s76, s59
	v_lshl_add_u64 v[162:163], s[52:53], 0, v[172:173]
	s_mov_b32 m0, s76
	ds_read_b128 v[198:201], v167 offset:16384
	ds_read_b128 v[202:205], v167 offset:17408
	ds_read_b128 v[206:209], v167 offset:18432
	ds_read_b128 v[210:213], v167 offset:19456
	ds_read_b128 v[214:217], v167 offset:20480
	ds_read_b128 v[218:221], v167 offset:21504
	ds_read_b128 v[228:231], v167 offset:22528
	ds_read_b128 v[232:235], v167 offset:23552
	global_load_lds_dwordx4 v[162:163], off
	s_add_i32 m0, s76, 0x2000
	s_add_u32 s76, s52, 0x80000
	v_lshl_add_u64 v[194:195], s[52:53], 0, v[156:157]
	s_addc_u32 s77, s53, 0
	s_add_i32 s78, s78, s59
	global_load_lds_dwordx4 v[194:195], off
	v_lshl_add_u64 v[224:225], s[76:77], 0, v[172:173]
	s_mov_b32 m0, s78
	v_lshl_add_u64 v[236:237], s[54:55], 0, v[156:157]
	global_load_lds_dwordx4 v[224:225], off
	v_lshl_add_u64 v[224:225], s[76:77], 0, v[156:157]
	s_add_i32 m0, s78, 0x2000
	s_nop 0
	global_load_lds_dwordx4 v[224:225], off
	v_lshl_add_u64 v[224:225], s[54:55], 0, v[172:173]
	s_mov_b32 m0, s60
	s_nop 0
	global_load_lds_dwordx4 v[224:225], off
	s_mov_b32 m0, s63
	s_nop 0
	global_load_lds_dwordx4 v[236:237], off
	s_waitcnt vmcnt(8)
	s_waitcnt lgkmcnt(0)
	s_barrier
; #define PG8_STAGE(bufoff, gbase, voff) do { _Pragma("unroll") for (int _i = 0; _i < 2; ++_i) \
;         __builtin_amdgcn_global_load_lds((const unsigned*)((const char*)(gbase) + (voff)[_i]), (LAS unsigned*)(lds + (bufoff) + ldsw + _i * 8192), 16, 0, 0); } while (0)
; #define PG8_LDA(dst, b, h) do { _Pragma("unroll") for (int m = 0; m < 4; ++m) _Pragma("unroll") for (int k = 0; k < 2; ++k) dst[m][k] = *(const LAS bf16x8*)(lds + PG8_SA(b, h) + aoff + m * 2048 + k * 1024); } while (0)
; #define PG8_LDB(dst, b, h) do { _Pragma("unroll") for (int n = 0; n < 2; ++n) _Pragma("unroll") for (int k = 0; k < 2; ++k) dst[n][k] = *(const LAS bf16x8*)(lds + PG8_SB(b, h) + boff + n * 2048 + k * 1024); } while (0)
; #define PG8_MMA(ai, bj, At, Bt) do { __builtin_amdgcn_s_setprio(1); _Pragma("unroll") for (int m = 0; m < 4; ++m) _Pragma("unroll") for (int n = 0; n < 2; ++n) _Pragma("unroll") for (int k = 0; k < 2; ++k) \
;         acc[ai][bj][m][n] = __builtin_amdgcn_mfma_f32_16x16x32_bf16(Bt[n][k], At[m][k], acc[ai][bj][m][n], 0, 0, 0); __builtin_amdgcn_s_setprio(0); } while (0)
; #define PG8_WAIT_V(n) asm volatile("s_waitcnt vmcnt(" #n ")" ::: "memory")
; #define PG8_WAIT_L(n) asm volatile("s_waitcnt lgkmcnt(" #n ")" ::: "memory")
; #define PG8_BAR __builtin_amdgcn_s_barrier()
; #define PG8_SCHED __builtin_amdgcn_sched_barrier(0)
; template <class Epi>
; __device__ __forceinline__ void gemm_phase(LAS unsigned char* lds, const Sched& S, const int K, const Epi& E) {
;     ...
;             PG8_WAIT_V(8); PG8_WAIT_L(0); PG8_BAR; PG8_MMA(1, 0, At, B0); PG8_MMA(1, 1, At, B1); PG8_BAR; PG8_SCHED;
;             PG8_LDB(B0, 1, 0); PG8_LDB(B1, 1, 1); PG8_SCHED; PG8_LDA(At, 1, 0); PG8_STAGE(PG8_SA(0, 1), a2 + hstepA, voffA);
;             PG8_WAIT_V(8); PG8_WAIT_L(0); PG8_BAR; PG8_MMA(0, 0, At, B0); PG8_MMA(0, 1, At, B1); PG8_BAR; PG8_SCHED;
	s_waitcnt lgkmcnt(0)
	v_mfma_f32_16x16x32_bf16 v[60:63], v[128:131], v[198:201], v[60:63]
	v_mfma_f32_16x16x32_bf16 v[56:59], v[136:139], v[198:201], v[56:59]
	v_mfma_f32_16x16x32_bf16 v[52:55], v[128:131], v[206:209], v[52:55]
	v_mfma_f32_16x16x32_bf16 v[40:43], v[136:139], v[206:209], v[40:43]
	v_mfma_f32_16x16x32_bf16 v[36:39], v[128:131], v[214:217], v[36:39]
	v_mfma_f32_16x16x32_bf16 v[24:27], v[136:139], v[214:217], v[24:27]
	v_mfma_f32_16x16x32_bf16 v[16:19], v[128:131], v[228:231], v[16:19]
	v_mfma_f32_16x16x32_bf16 v[8:11], v[136:139], v[228:231], v[8:11]
	v_mfma_f32_16x16x32_bf16 v[60:63], v[132:135], v[202:205], v[60:63]
	v_mfma_f32_16x16x32_bf16 v[56:59], v[140:143], v[202:205], v[56:59]
	v_mfma_f32_16x16x32_bf16 v[52:55], v[132:135], v[210:213], v[52:55]
	v_mfma_f32_16x16x32_bf16 v[40:43], v[140:143], v[210:213], v[40:43]
	v_mfma_f32_16x16x32_bf16 v[36:39], v[132:135], v[218:221], v[36:39]
	v_mfma_f32_16x16x32_bf16 v[24:27], v[140:143], v[218:221], v[24:27]
	v_mfma_f32_16x16x32_bf16 v[16:19], v[132:135], v[232:235], v[16:19]
	v_mfma_f32_16x16x32_bf16 v[8:11], v[140:143], v[232:235], v[8:11]
	v_mfma_f32_16x16x32_bf16 v[48:51], v[144:147], v[198:201], v[48:51]
	v_mfma_f32_16x16x32_bf16 v[44:47], v[152:155], v[198:201], v[44:47]
	v_mfma_f32_16x16x32_bf16 v[32:35], v[144:147], v[206:209], v[32:35]
	v_mfma_f32_16x16x32_bf16 v[28:31], v[152:155], v[206:209], v[28:31]
	v_mfma_f32_16x16x32_bf16 v[20:23], v[144:147], v[214:217], v[20:23]
	v_mfma_f32_16x16x32_bf16 v[12:15], v[152:155], v[214:217], v[12:15]
	v_mfma_f32_16x16x32_bf16 v[4:7], v[144:147], v[228:231], v[4:7]
	v_mfma_f32_16x16x32_bf16 v[0:3], v[152:155], v[228:231], v[0:3]
	v_mfma_f32_16x16x32_bf16 v[48:51], v[148:151], v[202:205], v[48:51]
	v_mfma_f32_16x16x32_bf16 v[44:47], v[168:171], v[202:205], v[44:47]
	v_mfma_f32_16x16x32_bf16 v[32:35], v[148:151], v[210:213], v[32:35]
	v_mfma_f32_16x16x32_bf16 v[28:31], v[168:171], v[210:213], v[28:31]
	v_mfma_f32_16x16x32_bf16 v[20:23], v[148:151], v[218:221], v[20:23]
	v_mfma_f32_16x16x32_bf16 v[12:15], v[168:171], v[218:221], v[12:15]
	v_mfma_f32_16x16x32_bf16 v[4:7], v[148:151], v[232:235], v[4:7]
	v_mfma_f32_16x16x32_bf16 v[0:3], v[168:171], v[232:235], v[0:3]
	s_barrier
	s_add_i32 s76, 0, 0x18000
	s_add_i32 s77, 0, 0x1c000
	v_add_u32_e32 v140, s76, v165
	v_add_u32_e32 v168, s77, v165
	ds_read_b128 v[128:131], v140
	ds_read_b128 v[132:135], v140 offset:1024
	ds_read_b128 v[136:139], v140 offset:2048
	ds_read_b128 v[140:143], v140 offset:3072
	ds_read_b128 v[144:147], v168
	ds_read_b128 v[148:151], v168 offset:1024
	ds_read_b128 v[152:155], v168 offset:2048
	ds_read_b128 v[168:171], v168 offset:3072
	s_add_u32 s54, s54, 0x80000
	s_addc_u32 s55, s55, 0
	s_mov_b32 m0, s65
	v_lshl_add_u64 v[238:239], s[54:55], 0, v[172:173]
	ds_read_b128 v[198:201], v167 offset:32768
	ds_read_b128 v[202:205], v167 offset:33792
	ds_read_b128 v[206:209], v167 offset:34816
	ds_read_b128 v[210:213], v167 offset:35840
	ds_read_b128 v[214:217], v167 offset:36864
	ds_read_b128 v[218:221], v167 offset:37888
	ds_read_b128 v[228:231], v167 offset:38912
	ds_read_b128 v[232:235], v167 offset:39936
	global_load_lds_dwordx4 v[238:239], off
	v_lshl_add_u64 v[238:239], s[54:55], 0, v[156:157]
	s_mov_b32 m0, s66
	s_nop 0
	global_load_lds_dwordx4 v[238:239], off
	s_waitcnt vmcnt(8)
	s_waitcnt lgkmcnt(0)
	s_barrier
	s_waitcnt lgkmcnt(0)
	v_mfma_f32_16x16x32_bf16 v[124:127], v[128:131], v[198:201], v[124:127]
	v_mfma_f32_16x16x32_bf16 v[120:123], v[136:139], v[198:201], v[120:123]
	v_mfma_f32_16x16x32_bf16 v[116:119], v[128:131], v[206:209], v[116:119]
	v_mfma_f32_16x16x32_bf16 v[104:107], v[136:139], v[206:209], v[104:107]
	v_mfma_f32_16x16x32_bf16 v[100:103], v[128:131], v[214:217], v[100:103]
	v_mfma_f32_16x16x32_bf16 v[88:91], v[136:139], v[214:217], v[88:91]
	v_mfma_f32_16x16x32_bf16 v[84:87], v[128:131], v[228:231], v[84:87]
	v_mfma_f32_16x16x32_bf16 v[72:75], v[136:139], v[228:231], v[72:75]
	v_mfma_f32_16x16x32_bf16 v[124:127], v[132:135], v[202:205], v[124:127]
	v_mfma_f32_16x16x32_bf16 v[120:123], v[140:143], v[202:205], v[120:123]
	v_mfma_f32_16x16x32_bf16 v[116:119], v[132:135], v[210:213], v[116:119]
	v_mfma_f32_16x16x32_bf16 v[104:107], v[140:143], v[210:213], v[104:107]
	v_mfma_f32_16x16x32_bf16 v[100:103], v[132:135], v[218:221], v[100:103]
	v_mfma_f32_16x16x32_bf16 v[88:91], v[140:143], v[218:221], v[88:91]
	v_mfma_f32_16x16x32_bf16 v[84:87], v[132:135], v[232:235], v[84:87]
	v_mfma_f32_16x16x32_bf16 v[72:75], v[140:143], v[232:235], v[72:75]
	v_mfma_f32_16x16x32_bf16 v[112:115], v[144:147], v[198:201], v[112:115]
	v_mfma_f32_16x16x32_bf16 v[108:111], v[152:155], v[198:201], v[108:111]
	v_mfma_f32_16x16x32_bf16 v[96:99], v[144:147], v[206:209], v[96:99]
	v_mfma_f32_16x16x32_bf16 v[92:95], v[152:155], v[206:209], v[92:95]
	v_mfma_f32_16x16x32_bf16 v[80:83], v[144:147], v[214:217], v[80:83]
	v_mfma_f32_16x16x32_bf16 v[76:79], v[152:155], v[214:217], v[76:79]
	v_mfma_f32_16x16x32_bf16 v[68:71], v[144:147], v[228:231], v[68:71]
	v_mfma_f32_16x16x32_bf16 v[64:67], v[152:155], v[228:231], v[64:67]
	v_mfma_f32_16x16x32_bf16 v[112:115], v[148:151], v[202:205], v[112:115]
	v_mfma_f32_16x16x32_bf16 v[108:111], v[168:171], v[202:205], v[108:111]
	v_mfma_f32_16x16x32_bf16 v[96:99], v[148:151], v[210:213], v[96:99]
	v_mfma_f32_16x16x32_bf16 v[92:95], v[168:171], v[210:213], v[92:95]
	v_mfma_f32_16x16x32_bf16 v[80:83], v[148:151], v[218:221], v[80:83]
	v_mfma_f32_16x16x32_bf16 v[76:79], v[168:171], v[218:221], v[76:79]
	v_mfma_f32_16x16x32_bf16 v[68:71], v[148:151], v[232:235], v[68:71]
	v_mfma_f32_16x16x32_bf16 v[64:67], v[168:171], v[232:235], v[64:67]
	s_barrier
; #define PG8_STAGE(bufoff, gbase, voff) do { _Pragma("unroll") for (int _i = 0; _i < 2; ++_i) \
;         __builtin_amdgcn_global_load_lds((const unsigned*)((const char*)(gbase) + (voff)[_i]), (LAS unsigned*)(lds + (bufoff) + ldsw + _i * 8192), 16, 0, 0); } while (0)
; #define PG8_LDA(dst, b, h) do { _Pragma("unroll") for (int m = 0; m < 4; ++m) _Pragma("unroll") for (int k = 0; k < 2; ++k) dst[m][k] = *(const LAS bf16x8*)(lds + PG8_SA(b, h) + aoff + m * 2048 + k * 1024); } while (0)
; #define PG8_MMA(ai, bj, At, Bt) do { __builtin_amdgcn_s_setprio(1); _Pragma("unroll") for (int m = 0; m < 4; ++m) _Pragma("unroll") for (int n = 0; n < 2; ++n) _Pragma("unroll") for (int k = 0; k < 2; ++k) \
;         acc[ai][bj][m][n] = __builtin_amdgcn_mfma_f32_16x16x32_bf16(Bt[n][k], At[m][k], acc[ai][bj][m][n], 0, 0, 0); __builtin_amdgcn_s_setprio(0); } while (0)
; #define PG8_WAIT_V(n) asm volatile("s_waitcnt vmcnt(" #n ")" ::: "memory")
; #define PG8_WAIT_L(n) asm volatile("s_waitcnt lgkmcnt(" #n ")" ::: "memory")
; #define PG8_BAR __builtin_amdgcn_s_barrier()
; #define PG8_SCHED __builtin_amdgcn_sched_barrier(0)
; template <class Epi>
; __device__ __forceinline__ void gemm_phase(LAS unsigned char* lds, const Sched& S, const int K, const Epi& E) {
;     ...
;             PG8_LDA(At, 1, 1); PG8_STAGE(PG8_SB(1, 0), b3, voffB); PG8_STAGE(PG8_SB(1, 1), b3 + hstepB, voffB); PG8_STAGE(PG8_SA(1, 0), a3, voffA);
;             PG8_WAIT_V(8); PG8_WAIT_L(0); PG8_BAR; PG8_MMA(1, 0, At, B0); PG8_MMA(1, 1, At, B1); PG8_BAR; PG8_SCHED;
;         }
	s_add_i32 s54, s76, s59
	v_lshl_add_u64 v[162:163], v[162:163], 0, s[74:75]
	s_mov_b32 m0, s54
	ds_read_b128 v[198:201], v167 offset:49152
	ds_read_b128 v[202:205], v167 offset:50176
	ds_read_b128 v[206:209], v167 offset:51200
	ds_read_b128 v[210:213], v167 offset:52224
	ds_read_b128 v[214:217], v167 offset:53248
	ds_read_b128 v[218:221], v167 offset:54272
	ds_read_b128 v[228:231], v167 offset:55296
	ds_read_b128 v[232:235], v167 offset:56320
	global_load_lds_dwordx4 v[162:163], off
	s_add_i32 m0, s54, 0x2000
	s_add_u32 s52, s52, 0x80080
	v_lshl_add_u64 v[162:163], v[194:195], 0, s[74:75]
	s_addc_u32 s53, s53, 0
	s_add_i32 s54, s77, s59
	global_load_lds_dwordx4 v[162:163], off
	v_lshl_add_u64 v[162:163], s[52:53], 0, v[172:173]
	s_mov_b32 m0, s54
	s_nop 0
	global_load_lds_dwordx4 v[162:163], off
	v_lshl_add_u64 v[162:163], s[52:53], 0, v[156:157]
	s_add_i32 m0, s54, 0x2000
	s_nop 0
	global_load_lds_dwordx4 v[162:163], off
	v_lshl_add_u64 v[162:163], v[224:225], 0, s[74:75]
	s_mov_b32 m0, s71
	s_nop 0
	global_load_lds_dwordx4 v[162:163], off
	v_lshl_add_u64 v[162:163], v[236:237], 0, s[74:75]
	s_mov_b32 m0, s72
	s_nop 0
	global_load_lds_dwordx4 v[162:163], off
	s_waitcnt vmcnt(8)
	s_waitcnt lgkmcnt(0)
	s_barrier
	s_waitcnt lgkmcnt(0)
	v_mfma_f32_16x16x32_bf16 v[60:63], v[128:131], v[198:201], v[60:63]
	v_mfma_f32_16x16x32_bf16 v[56:59], v[136:139], v[198:201], v[56:59]
	v_mfma_f32_16x16x32_bf16 v[52:55], v[128:131], v[206:209], v[52:55]
	v_mfma_f32_16x16x32_bf16 v[40:43], v[136:139], v[206:209], v[40:43]
	v_mfma_f32_16x16x32_bf16 v[36:39], v[128:131], v[214:217], v[36:39]
	v_mfma_f32_16x16x32_bf16 v[24:27], v[136:139], v[214:217], v[24:27]
	v_mfma_f32_16x16x32_bf16 v[16:19], v[128:131], v[228:231], v[16:19]
	v_mfma_f32_16x16x32_bf16 v[8:11], v[136:139], v[228:231], v[8:11]
	v_mfma_f32_16x16x32_bf16 v[60:63], v[132:135], v[202:205], v[60:63]
	v_mfma_f32_16x16x32_bf16 v[56:59], v[140:143], v[202:205], v[56:59]
	v_mfma_f32_16x16x32_bf16 v[52:55], v[132:135], v[210:213], v[52:55]
	v_mfma_f32_16x16x32_bf16 v[40:43], v[140:143], v[210:213], v[40:43]
	v_mfma_f32_16x16x32_bf16 v[36:39], v[132:135], v[218:221], v[36:39]
	v_mfma_f32_16x16x32_bf16 v[24:27], v[140:143], v[218:221], v[24:27]
	v_mfma_f32_16x16x32_bf16 v[16:19], v[132:135], v[232:235], v[16:19]
	v_mfma_f32_16x16x32_bf16 v[8:11], v[140:143], v[232:235], v[8:11]
	v_mfma_f32_16x16x32_bf16 v[48:51], v[144:147], v[198:201], v[48:51]
	v_mfma_f32_16x16x32_bf16 v[44:47], v[152:155], v[198:201], v[44:47]
	v_mfma_f32_16x16x32_bf16 v[32:35], v[144:147], v[206:209], v[32:35]
	v_mfma_f32_16x16x32_bf16 v[28:31], v[152:155], v[206:209], v[28:31]
	v_mfma_f32_16x16x32_bf16 v[20:23], v[144:147], v[214:217], v[20:23]
	v_mfma_f32_16x16x32_bf16 v[12:15], v[152:155], v[214:217], v[12:15]
	v_mfma_f32_16x16x32_bf16 v[4:7], v[144:147], v[228:231], v[4:7]
	v_mfma_f32_16x16x32_bf16 v[0:3], v[152:155], v[228:231], v[0:3]
	v_mfma_f32_16x16x32_bf16 v[48:51], v[148:151], v[202:205], v[48:51]
	v_mfma_f32_16x16x32_bf16 v[44:47], v[168:171], v[202:205], v[44:47]
	v_mfma_f32_16x16x32_bf16 v[32:35], v[148:151], v[210:213], v[32:35]
	v_mfma_f32_16x16x32_bf16 v[28:31], v[168:171], v[210:213], v[28:31]
	v_mfma_f32_16x16x32_bf16 v[20:23], v[148:151], v[218:221], v[20:23]
	v_mfma_f32_16x16x32_bf16 v[12:15], v[168:171], v[218:221], v[12:15]
	v_mfma_f32_16x16x32_bf16 v[4:7], v[148:151], v[232:235], v[4:7]
	v_mfma_f32_16x16x32_bf16 v[0:3], v[168:171], v[232:235], v[0:3]
	s_barrier
	s_add_i32 vcc_lo, vcc_lo, 2
	s_add_u32 s47, s47, 0x100
	s_addc_u32 s97, s97, 0
	s_add_u32 s36, s36, 0x100
	s_addc_u32 s37, s37, 0
	s_cmp_gt_u32 vcc_lo, 29
	s_cbranch_scc0 .LBB0_1239
	s_and_b64 vcc, exec, s[44:45]
	s_cbranch_vccz .LBB0_1242
	s_barrier

; #define PG8_STAGE(bufoff, gbase, voff) do { _Pragma("unroll") for (int _i = 0; _i < 2; ++_i) \
;         __builtin_amdgcn_global_load_lds((const unsigned*)((const char*)(gbase) + (voff)[_i]), (LAS unsigned*)(lds + (bufoff) + ldsw + _i * 8192), 16, 0, 0); } while (0)
; #define PG8_LDA(dst, b, h) do { _Pragma("unroll") for (int m = 0; m < 4; ++m) _Pragma("unroll") for (int k = 0; k < 2; ++k) dst[m][k] = *(const LAS bf16x8*)(lds + PG8_SA(b, h) + aoff + m * 2048 + k * 1024); } while (0)
; #define PG8_LDB(dst, b, h) do { _Pragma("unroll") for (int n = 0; n < 2; ++n) _Pragma("unroll") for (int k = 0; k < 2; ++k) dst[n][k] = *(const LAS bf16x8*)(lds + PG8_SB(b, h) + boff + n * 2048 + k * 1024); } while (0)
; #define PG8_MMA(ai, bj, At, Bt) do { __builtin_amdgcn_s_setprio(1); _Pragma("unroll") for (int m = 0; m < 4; ++m) _Pragma("unroll") for (int n = 0; n < 2; ++n) _Pragma("unroll") for (int k = 0; k < 2; ++k) \
;         acc[ai][bj][m][n] = __builtin_amdgcn_mfma_f32_16x16x32_bf16(Bt[n][k], At[m][k], acc[ai][bj][m][n], 0, 0, 0); __builtin_amdgcn_s_setprio(0); } while (0)
; #define PG8_WAIT_V(n) asm volatile("s_waitcnt vmcnt(" #n ")" ::: "memory")
; #define PG8_WAIT_L(n) asm volatile("s_waitcnt lgkmcnt(" #n ")" ::: "memory")
; #define PG8_BAR __builtin_amdgcn_s_barrier()
; #define PG8_SCHED __builtin_amdgcn_sched_barrier(0)
; template <class Epi>
; __device__ __forceinline__ void gemm_phase(LAS unsigned char* lds, const Sched& S, const int K, const Epi& E) {
;     ...
;         for (int t = 0; t < nt; t += 2) {
;             const bool last = (t == nt - 2);
;             const char* a1 = cA + (size_t)(t + 1) * kstep;
;             const char* a2 = last ? nA : cA + (size_t)(t + 2) * kstep; const char* b2 = last ? nB : cB + (size_t)(t + 2) * kstep;
;             const char* a3 = a2 + kstep; const char* b3 = b2 + kstep;
;             PG8_LDB(B0, 0, 0); PG8_LDB(B1, 0, 1); PG8_SCHED; PG8_LDA(At, 0, 0); PG8_STAGE(PG8_SA(1, 1), a1 + hstepA, voffA);
;             PG8_WAIT_V(8); PG8_WAIT_L(0); PG8_BAR; PG8_MMA(0, 0, At, B0); PG8_MMA(0, 1, At, B1); PG8_BAR; PG8_SCHED;
;             PG8_LDA(At, 0, 1); PG8_STAGE(PG8_SB(0, 0), b2, voffB); PG8_STAGE(PG8_SB(0, 1), b2 + hstepB, voffB); PG8_STAGE(PG8_SA(0, 0), a2, voffA);
.LBB0_1400:
	s_add_u32 s50, s36, 0xfff80080
	s_addc_u32 s51, s37, -1
	s_add_i32 s73, 0, 0x10000
	s_cmp_eq_u32 s72, 28
	s_cselect_b32 s53, s29, s51
	s_cselect_b32 s52, s28, s50
	s_cselect_b32 s51, s35, s71
	s_cselect_b32 s50, s34, s45
	s_add_i32 s78, 0, 0x14000
	v_add_u32_e32 v154, s73, v139
	v_add_u32_e32 v170, s78, v139
	ds_read_b128 v[142:145], v154
	ds_read_b128 v[146:149], v154 offset:1024
	ds_read_b128 v[150:153], v154 offset:2048
	ds_read_b128 v[154:157], v154 offset:3072
	ds_read_b128 v[158:161], v170
	ds_read_b128 v[162:165], v170 offset:1024
	ds_read_b128 v[166:169], v170 offset:2048
	ds_read_b128 v[198:201], v170 offset:3072
	v_lshl_add_u64 v[170:171], s[36:37], 0, v[134:135]
	s_add_i32 m0, s59, 0xc000
	ds_read_b128 v[202:205], v141
	ds_read_b128 v[206:209], v141 offset:1024
	ds_read_b128 v[210:213], v141 offset:2048
	ds_read_b128 v[214:217], v141 offset:3072
	ds_read_b128 v[218:221], v141 offset:4096
	ds_read_b128 v[228:231], v141 offset:5120
	ds_read_b128 v[232:235], v141 offset:6144
	ds_read_b128 v[236:239], v141 offset:7168
	global_load_lds_dwordx4 v[170:171], off
	v_lshl_add_u64 v[170:171], s[36:37], 0, v[136:137]
	s_add_i32 m0, s59, 0xe000
	s_nop 0
	global_load_lds_dwordx4 v[170:171], off
	s_waitcnt vmcnt(8)
	s_waitcnt lgkmcnt(0)
	s_barrier
	s_waitcnt lgkmcnt(0)
	v_mfma_f32_16x16x32_bf16 v[124:127], v[142:145], v[202:205], v[124:127]
	v_mfma_f32_16x16x32_bf16 v[116:119], v[150:153], v[202:205], v[116:119]
	v_mfma_f32_16x16x32_bf16 v[108:111], v[142:145], v[210:213], v[108:111]
	v_mfma_f32_16x16x32_bf16 v[100:103], v[150:153], v[210:213], v[100:103]
	v_mfma_f32_16x16x32_bf16 v[92:95], v[142:145], v[218:221], v[92:95]
	v_mfma_f32_16x16x32_bf16 v[84:87], v[150:153], v[218:221], v[84:87]
	v_mfma_f32_16x16x32_bf16 v[76:79], v[142:145], v[232:235], v[76:79]
	v_mfma_f32_16x16x32_bf16 v[68:71], v[150:153], v[232:235], v[68:71]
	v_mfma_f32_16x16x32_bf16 v[124:127], v[146:149], v[206:209], v[124:127]
	v_mfma_f32_16x16x32_bf16 v[116:119], v[154:157], v[206:209], v[116:119]
	v_mfma_f32_16x16x32_bf16 v[108:111], v[146:149], v[214:217], v[108:111]
	v_mfma_f32_16x16x32_bf16 v[100:103], v[154:157], v[214:217], v[100:103]
	v_mfma_f32_16x16x32_bf16 v[92:95], v[146:149], v[228:231], v[92:95]
	v_mfma_f32_16x16x32_bf16 v[84:87], v[154:157], v[228:231], v[84:87]
	v_mfma_f32_16x16x32_bf16 v[76:79], v[146:149], v[236:239], v[76:79]
	v_mfma_f32_16x16x32_bf16 v[68:71], v[154:157], v[236:239], v[68:71]
	v_mfma_f32_16x16x32_bf16 v[120:123], v[158:161], v[202:205], v[120:123]
	v_mfma_f32_16x16x32_bf16 v[112:115], v[166:169], v[202:205], v[112:115]
	v_mfma_f32_16x16x32_bf16 v[104:107], v[158:161], v[210:213], v[104:107]
	v_mfma_f32_16x16x32_bf16 v[96:99], v[166:169], v[210:213], v[96:99]
	v_mfma_f32_16x16x32_bf16 v[88:91], v[158:161], v[218:221], v[88:91]
	v_mfma_f32_16x16x32_bf16 v[80:83], v[166:169], v[218:221], v[80:83]
	v_mfma_f32_16x16x32_bf16 v[72:75], v[158:161], v[232:235], v[72:75]
	v_mfma_f32_16x16x32_bf16 v[64:67], v[166:169], v[232:235], v[64:67]
	v_mfma_f32_16x16x32_bf16 v[120:123], v[162:165], v[206:209], v[120:123]
	v_mfma_f32_16x16x32_bf16 v[112:115], v[198:201], v[206:209], v[112:115]
	v_mfma_f32_16x16x32_bf16 v[104:107], v[162:165], v[214:217], v[104:107]
	v_mfma_f32_16x16x32_bf16 v[96:99], v[198:201], v[214:217], v[96:99]
	v_mfma_f32_16x16x32_bf16 v[88:91], v[162:165], v[228:231], v[88:91]
	v_mfma_f32_16x16x32_bf16 v[80:83], v[198:201], v[228:231], v[80:83]
	v_mfma_f32_16x16x32_bf16 v[72:75], v[162:165], v[236:239], v[72:75]
	v_mfma_f32_16x16x32_bf16 v[64:67], v[198:201], v[236:239], v[64:67]
	s_barrier
	s_add_i32 s73, s73, s58
	v_lshl_add_u64 v[170:171], s[50:51], 0, v[172:173]
	s_mov_b32 m0, s73
	ds_read_b128 v[202:205], v141 offset:16384
	ds_read_b128 v[206:209], v141 offset:17408
	ds_read_b128 v[210:213], v141 offset:18432
	ds_read_b128 v[214:217], v141 offset:19456
	ds_read_b128 v[218:221], v141 offset:20480
	ds_read_b128 v[228:231], v141 offset:21504
	ds_read_b128 v[232:235], v141 offset:22528
	ds_read_b128 v[236:239], v141 offset:23552
	global_load_lds_dwordx4 v[170:171], off
	s_add_i32 m0, s73, 0x2000
	s_add_u32 s76, s50, 0x80000
	v_lshl_add_u64 v[194:195], s[50:51], 0, v[128:129]
	s_addc_u32 s77, s51, 0
	s_add_i32 s73, s78, s58
	global_load_lds_dwordx4 v[194:195], off
	v_lshl_add_u64 v[224:225], s[76:77], 0, v[172:173]
	s_mov_b32 m0, s73
	v_lshl_add_u64 v[240:241], s[52:53], 0, v[130:131]
	global_load_lds_dwordx4 v[224:225], off
	v_lshl_add_u64 v[224:225], s[76:77], 0, v[128:129]
	s_add_i32 m0, s73, 0x2000
	s_nop 0
	global_load_lds_dwordx4 v[224:225], off
	v_lshl_add_u64 v[224:225], s[52:53], 0, v[132:133]
	s_mov_b32 m0, s59
	s_nop 0
	global_load_lds_dwordx4 v[224:225], off
	s_mov_b32 m0, s60
	s_nop 0
	global_load_lds_dwordx4 v[240:241], off
	s_waitcnt vmcnt(8)
	s_waitcnt lgkmcnt(0)
	s_barrier
; #define PG8_STAGE(bufoff, gbase, voff) do { _Pragma("unroll") for (int _i = 0; _i < 2; ++_i) \
;         __builtin_amdgcn_global_load_lds((const unsigned*)((const char*)(gbase) + (voff)[_i]), (LAS unsigned*)(lds + (bufoff) + ldsw + _i * 8192), 16, 0, 0); } while (0)
; #define PG8_LDA(dst, b, h) do { _Pragma("unroll") for (int m = 0; m < 4; ++m) _Pragma("unroll") for (int k = 0; k < 2; ++k) dst[m][k] = *(const LAS bf16x8*)(lds + PG8_SA(b, h) + aoff + m * 2048 + k * 1024); } while (0)
; #define PG8_LDB(dst, b, h) do { _Pragma("unroll") for (int n = 0; n < 2; ++n) _Pragma("unroll") for (int k = 0; k < 2; ++k) dst[n][k] = *(const LAS bf16x8*)(lds + PG8_SB(b, h) + boff + n * 2048 + k * 1024); } while (0)
; #define PG8_MMA(ai, bj, At, Bt) do { __builtin_amdgcn_s_setprio(1); _Pragma("unroll") for (int m = 0; m < 4; ++m) _Pragma("unroll") for (int n = 0; n < 2; ++n) _Pragma("unroll") for (int k = 0; k < 2; ++k) \
;         acc[ai][bj][m][n] = __builtin_amdgcn_mfma_f32_16x16x32_bf16(Bt[n][k], At[m][k], acc[ai][bj][m][n], 0, 0, 0); __builtin_amdgcn_s_setprio(0); } while (0)
; #define PG8_WAIT_V(n) asm volatile("s_waitcnt vmcnt(" #n ")" ::: "memory")
; #define PG8_WAIT_L(n) asm volatile("s_waitcnt lgkmcnt(" #n ")" ::: "memory")
; #define PG8_BAR __builtin_amdgcn_s_barrier()
; #define PG8_SCHED __builtin_amdgcn_sched_barrier(0)
; template <class Epi>
; __device__ __forceinline__ void gemm_phase(LAS unsigned char* lds, const Sched& S, const int K, const Epi& E) {
;     ...
;             PG8_WAIT_V(8); PG8_WAIT_L(0); PG8_BAR; PG8_MMA(1, 0, At, B0); PG8_MMA(1, 1, At, B1); PG8_BAR; PG8_SCHED;
;             PG8_LDB(B0, 1, 0); PG8_LDB(B1, 1, 1); PG8_SCHED; PG8_LDA(At, 1, 0); PG8_STAGE(PG8_SA(0, 1), a2 + hstepA, voffA);
;             PG8_WAIT_V(8); PG8_WAIT_L(0); PG8_BAR; PG8_MMA(0, 0, At, B0); PG8_MMA(0, 1, At, B1); PG8_BAR; PG8_SCHED;
	s_waitcnt lgkmcnt(0)
	v_mfma_f32_16x16x32_bf16 v[60:63], v[142:145], v[202:205], v[60:63]
	v_mfma_f32_16x16x32_bf16 v[52:55], v[150:153], v[202:205], v[52:55]
	v_mfma_f32_16x16x32_bf16 v[44:47], v[142:145], v[210:213], v[44:47]
	v_mfma_f32_16x16x32_bf16 v[36:39], v[150:153], v[210:213], v[36:39]
	v_mfma_f32_16x16x32_bf16 v[28:31], v[142:145], v[218:221], v[28:31]
	v_mfma_f32_16x16x32_bf16 v[20:23], v[150:153], v[218:221], v[20:23]
	v_mfma_f32_16x16x32_bf16 v[12:15], v[142:145], v[232:235], v[12:15]
	v_mfma_f32_16x16x32_bf16 v[4:7], v[150:153], v[232:235], v[4:7]
	v_mfma_f32_16x16x32_bf16 v[60:63], v[146:149], v[206:209], v[60:63]
	v_mfma_f32_16x16x32_bf16 v[52:55], v[154:157], v[206:209], v[52:55]
	v_mfma_f32_16x16x32_bf16 v[44:47], v[146:149], v[214:217], v[44:47]
	v_mfma_f32_16x16x32_bf16 v[36:39], v[154:157], v[214:217], v[36:39]
	v_mfma_f32_16x16x32_bf16 v[28:31], v[146:149], v[228:231], v[28:31]
	v_mfma_f32_16x16x32_bf16 v[20:23], v[154:157], v[228:231], v[20:23]
	v_mfma_f32_16x16x32_bf16 v[12:15], v[146:149], v[236:239], v[12:15]
	v_mfma_f32_16x16x32_bf16 v[4:7], v[154:157], v[236:239], v[4:7]
	v_mfma_f32_16x16x32_bf16 v[56:59], v[158:161], v[202:205], v[56:59]
	v_mfma_f32_16x16x32_bf16 v[48:51], v[166:169], v[202:205], v[48:51]
	v_mfma_f32_16x16x32_bf16 v[40:43], v[158:161], v[210:213], v[40:43]
	v_mfma_f32_16x16x32_bf16 v[32:35], v[166:169], v[210:213], v[32:35]
	v_mfma_f32_16x16x32_bf16 v[24:27], v[158:161], v[218:221], v[24:27]
	v_mfma_f32_16x16x32_bf16 v[16:19], v[166:169], v[218:221], v[16:19]
	v_mfma_f32_16x16x32_bf16 v[8:11], v[158:161], v[232:235], v[8:11]
	v_mfma_f32_16x16x32_bf16 v[0:3], v[166:169], v[232:235], v[0:3]
	v_mfma_f32_16x16x32_bf16 v[56:59], v[162:165], v[206:209], v[56:59]
	v_mfma_f32_16x16x32_bf16 v[48:51], v[198:201], v[206:209], v[48:51]
	v_mfma_f32_16x16x32_bf16 v[40:43], v[162:165], v[214:217], v[40:43]
	v_mfma_f32_16x16x32_bf16 v[32:35], v[198:201], v[214:217], v[32:35]
	v_mfma_f32_16x16x32_bf16 v[24:27], v[162:165], v[228:231], v[24:27]
	v_mfma_f32_16x16x32_bf16 v[16:19], v[198:201], v[228:231], v[16:19]
	v_mfma_f32_16x16x32_bf16 v[8:11], v[162:165], v[236:239], v[8:11]
	v_mfma_f32_16x16x32_bf16 v[0:3], v[198:201], v[236:239], v[0:3]
	s_barrier
	s_add_i32 s73, 0, 0x18000
	s_add_i32 s76, 0, 0x1c000
	v_add_u32_e32 v154, s73, v139
	v_add_u32_e32 v198, s76, v139
	ds_read_b128 v[142:145], v154
	ds_read_b128 v[146:149], v154 offset:1024
	ds_read_b128 v[150:153], v154 offset:2048
	ds_read_b128 v[154:157], v154 offset:3072
	ds_read_b128 v[158:161], v198
	ds_read_b128 v[162:165], v198 offset:1024
	ds_read_b128 v[166:169], v198 offset:2048
	ds_read_b128 v[198:201], v198 offset:3072
	s_add_u32 s52, s52, 0x80000
	s_addc_u32 s53, s53, 0
	s_mov_b32 m0, s63
	v_lshl_add_u64 v[242:243], s[52:53], 0, v[132:133]
	ds_read_b128 v[202:205], v141 offset:32768
	ds_read_b128 v[206:209], v141 offset:33792
	ds_read_b128 v[210:213], v141 offset:34816
	ds_read_b128 v[214:217], v141 offset:35840
	ds_read_b128 v[218:221], v141 offset:36864
	ds_read_b128 v[228:231], v141 offset:37888
	ds_read_b128 v[232:235], v141 offset:38912
	ds_read_b128 v[236:239], v141 offset:39936
	global_load_lds_dwordx4 v[242:243], off
	v_lshl_add_u64 v[242:243], s[52:53], 0, v[130:131]
	s_mov_b32 m0, s65
	s_nop 0
	global_load_lds_dwordx4 v[242:243], off
	s_waitcnt vmcnt(8)
	s_waitcnt lgkmcnt(0)
	s_barrier
	s_waitcnt lgkmcnt(0)
	v_mfma_f32_16x16x32_bf16 v[124:127], v[142:145], v[202:205], v[124:127]
	v_mfma_f32_16x16x32_bf16 v[116:119], v[150:153], v[202:205], v[116:119]
	v_mfma_f32_16x16x32_bf16 v[108:111], v[142:145], v[210:213], v[108:111]
	v_mfma_f32_16x16x32_bf16 v[100:103], v[150:153], v[210:213], v[100:103]
	v_mfma_f32_16x16x32_bf16 v[92:95], v[142:145], v[218:221], v[92:95]
	v_mfma_f32_16x16x32_bf16 v[84:87], v[150:153], v[218:221], v[84:87]
	v_mfma_f32_16x16x32_bf16 v[76:79], v[142:145], v[232:235], v[76:79]
	v_mfma_f32_16x16x32_bf16 v[68:71], v[150:153], v[232:235], v[68:71]
	v_mfma_f32_16x16x32_bf16 v[124:127], v[146:149], v[206:209], v[124:127]
	v_mfma_f32_16x16x32_bf16 v[116:119], v[154:157], v[206:209], v[116:119]
	v_mfma_f32_16x16x32_bf16 v[108:111], v[146:149], v[214:217], v[108:111]
	v_mfma_f32_16x16x32_bf16 v[100:103], v[154:157], v[214:217], v[100:103]
	v_mfma_f32_16x16x32_bf16 v[92:95], v[146:149], v[228:231], v[92:95]
	v_mfma_f32_16x16x32_bf16 v[84:87], v[154:157], v[228:231], v[84:87]
	v_mfma_f32_16x16x32_bf16 v[76:79], v[146:149], v[236:239], v[76:79]
	v_mfma_f32_16x16x32_bf16 v[68:71], v[154:157], v[236:239], v[68:71]
	v_mfma_f32_16x16x32_bf16 v[120:123], v[158:161], v[202:205], v[120:123]
	v_mfma_f32_16x16x32_bf16 v[112:115], v[166:169], v[202:205], v[112:115]
	v_mfma_f32_16x16x32_bf16 v[104:107], v[158:161], v[210:213], v[104:107]
	v_mfma_f32_16x16x32_bf16 v[96:99], v[166:169], v[210:213], v[96:99]
	v_mfma_f32_16x16x32_bf16 v[88:91], v[158:161], v[218:221], v[88:91]
	v_mfma_f32_16x16x32_bf16 v[80:83], v[166:169], v[218:221], v[80:83]
	v_mfma_f32_16x16x32_bf16 v[72:75], v[158:161], v[232:235], v[72:75]
	v_mfma_f32_16x16x32_bf16 v[64:67], v[166:169], v[232:235], v[64:67]
	v_mfma_f32_16x16x32_bf16 v[120:123], v[162:165], v[206:209], v[120:123]
	v_mfma_f32_16x16x32_bf16 v[112:115], v[198:201], v[206:209], v[112:115]
	v_mfma_f32_16x16x32_bf16 v[104:107], v[162:165], v[214:217], v[104:107]
	v_mfma_f32_16x16x32_bf16 v[96:99], v[198:201], v[214:217], v[96:99]
	v_mfma_f32_16x16x32_bf16 v[88:91], v[162:165], v[228:231], v[88:91]
	v_mfma_f32_16x16x32_bf16 v[80:83], v[198:201], v[228:231], v[80:83]
	v_mfma_f32_16x16x32_bf16 v[72:75], v[162:165], v[236:239], v[72:75]
	v_mfma_f32_16x16x32_bf16 v[64:67], v[198:201], v[236:239], v[64:67]
	s_barrier
; #define PG8_STAGE(bufoff, gbase, voff) do { _Pragma("unroll") for (int _i = 0; _i < 2; ++_i) \
;         __builtin_amdgcn_global_load_lds((const unsigned*)((const char*)(gbase) + (voff)[_i]), (LAS unsigned*)(lds + (bufoff) + ldsw + _i * 8192), 16, 0, 0); } while (0)
; #define PG8_LDA(dst, b, h) do { _Pragma("unroll") for (int m = 0; m < 4; ++m) _Pragma("unroll") for (int k = 0; k < 2; ++k) dst[m][k] = *(const LAS bf16x8*)(lds + PG8_SA(b, h) + aoff + m * 2048 + k * 1024); } while (0)
; #define PG8_MMA(ai, bj, At, Bt) do { __builtin_amdgcn_s_setprio(1); _Pragma("unroll") for (int m = 0; m < 4; ++m) _Pragma("unroll") for (int n = 0; n < 2; ++n) _Pragma("unroll") for (int k = 0; k < 2; ++k) \
;         acc[ai][bj][m][n] = __builtin_amdgcn_mfma_f32_16x16x32_bf16(Bt[n][k], At[m][k], acc[ai][bj][m][n], 0, 0, 0); __builtin_amdgcn_s_setprio(0); } while (0)
; #define PG8_WAIT_V(n) asm volatile("s_waitcnt vmcnt(" #n ")" ::: "memory")
; #define PG8_WAIT_L(n) asm volatile("s_waitcnt lgkmcnt(" #n ")" ::: "memory")
; #define PG8_BAR __builtin_amdgcn_s_barrier()
; #define PG8_SCHED __builtin_amdgcn_sched_barrier(0)
; template <class Epi>
; __device__ __forceinline__ void gemm_phase(LAS unsigned char* lds, const Sched& S, const int K, const Epi& E) {
;     ...
;             PG8_LDA(At, 1, 1); PG8_STAGE(PG8_SB(1, 0), b3, voffB); PG8_STAGE(PG8_SB(1, 1), b3 + hstepB, voffB); PG8_STAGE(PG8_SA(1, 0), a3, voffA);
;             PG8_WAIT_V(8); PG8_WAIT_L(0); PG8_BAR; PG8_MMA(1, 0, At, B0); PG8_MMA(1, 1, At, B1); PG8_BAR; PG8_SCHED;
;         }
	s_add_i32 s52, s73, s58
	v_lshl_add_u64 v[170:171], v[170:171], 0, s[74:75]
	s_mov_b32 m0, s52
	ds_read_b128 v[202:205], v141 offset:49152
	ds_read_b128 v[206:209], v141 offset:50176
	ds_read_b128 v[210:213], v141 offset:51200
	ds_read_b128 v[214:217], v141 offset:52224
	ds_read_b128 v[218:221], v141 offset:53248
	ds_read_b128 v[228:231], v141 offset:54272
	ds_read_b128 v[232:235], v141 offset:55296
	ds_read_b128 v[236:239], v141 offset:56320
	global_load_lds_dwordx4 v[170:171], off
	s_add_i32 m0, s52, 0x2000
	s_add_u32 s50, s50, 0x80080
	v_lshl_add_u64 v[170:171], v[194:195], 0, s[74:75]
	s_addc_u32 s51, s51, 0
	s_add_i32 s52, s76, s58
	global_load_lds_dwordx4 v[170:171], off
	v_lshl_add_u64 v[170:171], s[50:51], 0, v[172:173]
	s_mov_b32 m0, s52
	s_nop 0
	global_load_lds_dwordx4 v[170:171], off
	v_lshl_add_u64 v[170:171], s[50:51], 0, v[128:129]
	s_add_i32 m0, s52, 0x2000
	s_nop 0
	global_load_lds_dwordx4 v[170:171], off
	v_lshl_add_u64 v[170:171], v[224:225], 0, s[74:75]
	s_mov_b32 m0, s66
	s_nop 0
	global_load_lds_dwordx4 v[170:171], off
	v_lshl_add_u64 v[170:171], v[240:241], 0, s[74:75]
	s_mov_b32 m0, s67
	s_nop 0
	global_load_lds_dwordx4 v[170:171], off
	s_waitcnt vmcnt(8)
	s_waitcnt lgkmcnt(0)
	s_barrier
	s_waitcnt lgkmcnt(0)
	v_mfma_f32_16x16x32_bf16 v[60:63], v[142:145], v[202:205], v[60:63]
	v_mfma_f32_16x16x32_bf16 v[52:55], v[150:153], v[202:205], v[52:55]
	v_mfma_f32_16x16x32_bf16 v[44:47], v[142:145], v[210:213], v[44:47]
	v_mfma_f32_16x16x32_bf16 v[36:39], v[150:153], v[210:213], v[36:39]
	v_mfma_f32_16x16x32_bf16 v[28:31], v[142:145], v[218:221], v[28:31]
	v_mfma_f32_16x16x32_bf16 v[20:23], v[150:153], v[218:221], v[20:23]
	v_mfma_f32_16x16x32_bf16 v[12:15], v[142:145], v[232:235], v[12:15]
	v_mfma_f32_16x16x32_bf16 v[4:7], v[150:153], v[232:235], v[4:7]
	v_mfma_f32_16x16x32_bf16 v[60:63], v[146:149], v[206:209], v[60:63]
	v_mfma_f32_16x16x32_bf16 v[52:55], v[154:157], v[206:209], v[52:55]
	v_mfma_f32_16x16x32_bf16 v[44:47], v[146:149], v[214:217], v[44:47]
	v_mfma_f32_16x16x32_bf16 v[36:39], v[154:157], v[214:217], v[36:39]
	v_mfma_f32_16x16x32_bf16 v[28:31], v[146:149], v[228:231], v[28:31]
	v_mfma_f32_16x16x32_bf16 v[20:23], v[154:157], v[228:231], v[20:23]
	v_mfma_f32_16x16x32_bf16 v[12:15], v[146:149], v[236:239], v[12:15]
	v_mfma_f32_16x16x32_bf16 v[4:7], v[154:157], v[236:239], v[4:7]
	v_mfma_f32_16x16x32_bf16 v[56:59], v[158:161], v[202:205], v[56:59]
	v_mfma_f32_16x16x32_bf16 v[48:51], v[166:169], v[202:205], v[48:51]
	v_mfma_f32_16x16x32_bf16 v[40:43], v[158:161], v[210:213], v[40:43]
	v_mfma_f32_16x16x32_bf16 v[32:35], v[166:169], v[210:213], v[32:35]
	v_mfma_f32_16x16x32_bf16 v[24:27], v[158:161], v[218:221], v[24:27]
	v_mfma_f32_16x16x32_bf16 v[16:19], v[166:169], v[218:221], v[16:19]
	v_mfma_f32_16x16x32_bf16 v[8:11], v[158:161], v[232:235], v[8:11]
	v_mfma_f32_16x16x32_bf16 v[0:3], v[166:169], v[232:235], v[0:3]
	v_mfma_f32_16x16x32_bf16 v[56:59], v[162:165], v[206:209], v[56:59]
	v_mfma_f32_16x16x32_bf16 v[48:51], v[198:201], v[206:209], v[48:51]
	v_mfma_f32_16x16x32_bf16 v[40:43], v[162:165], v[214:217], v[40:43]
	v_mfma_f32_16x16x32_bf16 v[32:35], v[198:201], v[214:217], v[32:35]
	v_mfma_f32_16x16x32_bf16 v[24:27], v[162:165], v[228:231], v[24:27]
	v_mfma_f32_16x16x32_bf16 v[16:19], v[198:201], v[228:231], v[16:19]
	v_mfma_f32_16x16x32_bf16 v[8:11], v[162:165], v[236:239], v[8:11]
	v_mfma_f32_16x16x32_bf16 v[0:3], v[198:201], v[236:239], v[0:3]
	s_barrier
	s_add_i32 s72, s72, 2
	s_add_u32 s45, s45, 0x100
	s_addc_u32 s71, s71, 0
	s_add_u32 s36, s36, 0x100
	s_addc_u32 s37, s37, 0
	s_cmp_gt_u32 s72, 29
	s_cbranch_scc0 .LBB0_1400
	s_and_b64 vcc, exec, s[42:43]
	s_cbranch_vccz .LBB0_1403
	s_barrier

; #define PG8_STAGE(bufoff, gbase, voff) do { _Pragma("unroll") for (int _i = 0; _i < 2; ++_i) \
;         __builtin_amdgcn_global_load_lds((const unsigned*)((const char*)(gbase) + (voff)[_i]), (LAS unsigned*)(lds + (bufoff) + ldsw + _i * 8192), 16, 0, 0); } while (0)
; #define PG8_LDA(dst, b, h) do { _Pragma("unroll") for (int m = 0; m < 4; ++m) _Pragma("unroll") for (int k = 0; k < 2; ++k) dst[m][k] = *(const LAS bf16x8*)(lds + PG8_SA(b, h) + aoff + m * 2048 + k * 1024); } while (0)
; #define PG8_LDB(dst, b, h) do { _Pragma("unroll") for (int n = 0; n < 2; ++n) _Pragma("unroll") for (int k = 0; k < 2; ++k) dst[n][k] = *(const LAS bf16x8*)(lds + PG8_SB(b, h) + boff + n * 2048 + k * 1024); } while (0)
; #define PG8_MMA(ai, bj, At, Bt) do { __builtin_amdgcn_s_setprio(1); _Pragma("unroll") for (int m = 0; m < 4; ++m) _Pragma("unroll") for (int n = 0; n < 2; ++n) _Pragma("unroll") for (int k = 0; k < 2; ++k) \
;         acc[ai][bj][m][n] = __builtin_amdgcn_mfma_f32_16x16x32_bf16(Bt[n][k], At[m][k], acc[ai][bj][m][n], 0, 0, 0); __builtin_amdgcn_s_setprio(0); } while (0)
; #define PG8_WAIT_V(n) asm volatile("s_waitcnt vmcnt(" #n ")" ::: "memory")
; #define PG8_WAIT_L(n) asm volatile("s_waitcnt lgkmcnt(" #n ")" ::: "memory")
; #define PG8_BAR __builtin_amdgcn_s_barrier()
; #define PG8_SCHED __builtin_amdgcn_sched_barrier(0)
; template <class Epi>
; __device__ __forceinline__ void gemm_phase(LAS unsigned char* lds, const Sched& S, const int K, const Epi& E) {
;     ...
;         for (int t = 0; t < nt; t += 2) {
;             const bool last = (t == nt - 2);
;             const char* a1 = cA + (size_t)(t + 1) * kstep;
;             const char* a2 = last ? nA : cA + (size_t)(t + 2) * kstep; const char* b2 = last ? nB : cB + (size_t)(t + 2) * kstep;
;             const char* a3 = a2 + kstep; const char* b3 = b2 + kstep;
;             PG8_LDB(B0, 0, 0); PG8_LDB(B1, 0, 1); PG8_SCHED; PG8_LDA(At, 0, 0); PG8_STAGE(PG8_SA(1, 1), a1 + hstepA, voffA);
;             PG8_WAIT_V(8); PG8_WAIT_L(0); PG8_BAR; PG8_MMA(0, 0, At, B0); PG8_MMA(0, 1, At, B1); PG8_BAR; PG8_SCHED;
;             PG8_LDA(At, 0, 1); PG8_STAGE(PG8_SB(0, 0), b2, voffB); PG8_STAGE(PG8_SB(0, 1), b2 + hstepB, voffB); PG8_STAGE(PG8_SA(0, 0), a2, voffA);
.LBB0_1487:
	s_add_u32 s48, s36, 0x100
	s_addc_u32 s49, s37, 0
	s_add_i32 s76, 0, 0x10000
	s_cmpk_eq_i32 s92, 0x54
	s_cselect_b32 s53, s29, s49
	s_cselect_b32 s52, s28, s48
	v_add_u32_e32 v134, s76, v137
	s_cselect_b32 s51, s35, s73
	s_cselect_b32 s50, s34, s72
	s_add_i32 s77, 0, 0x14000
	ds_read_b128 v[140:143], v134
	ds_read_b128 v[144:147], v134 offset:1024
	ds_read_b128 v[148:151], v134 offset:2048
	ds_read_b128 v[152:155], v134 offset:3072
	v_add_u32_e32 v134, s77, v137
	ds_read_b128 v[156:159], v134
	ds_read_b128 v[160:163], v134 offset:1024
	ds_read_b128 v[164:167], v134 offset:2048
	ds_read_b128 v[168:171], v134 offset:3072
	v_lshl_add_u64 v[134:135], s[36:37], 0, v[132:133]
	s_add_i32 m0, s59, 0xc000
	ds_read_b128 v[198:201], v139
	ds_read_b128 v[202:205], v139 offset:1024
	ds_read_b128 v[206:209], v139 offset:2048
	ds_read_b128 v[210:213], v139 offset:3072
	ds_read_b128 v[214:217], v139 offset:4096
	ds_read_b128 v[218:221], v139 offset:5120
	ds_read_b128 v[228:231], v139 offset:6144
	ds_read_b128 v[232:235], v139 offset:7168
	global_load_lds_dwordx4 v[134:135], off
	v_lshl_add_u64 v[134:135], s[36:37], 0, v[130:131]
	s_add_i32 m0, s59, 0xe000
	s_nop 0
	global_load_lds_dwordx4 v[134:135], off
	s_waitcnt vmcnt(8)
	s_waitcnt lgkmcnt(0)
	s_barrier
	s_waitcnt lgkmcnt(0)
	v_mfma_f32_16x16x32_bf16 v[124:127], v[140:143], v[198:201], v[124:127]
	v_mfma_f32_16x16x32_bf16 v[120:123], v[148:151], v[198:201], v[120:123]
	v_mfma_f32_16x16x32_bf16 v[116:119], v[140:143], v[206:209], v[116:119]
	v_mfma_f32_16x16x32_bf16 v[112:115], v[148:151], v[206:209], v[112:115]
	v_mfma_f32_16x16x32_bf16 v[104:107], v[140:143], v[214:217], v[104:107]
	v_mfma_f32_16x16x32_bf16 v[96:99], v[148:151], v[214:217], v[96:99]
	v_mfma_f32_16x16x32_bf16 v[88:91], v[140:143], v[228:231], v[88:91]
	v_mfma_f32_16x16x32_bf16 v[80:83], v[148:151], v[228:231], v[80:83]
	v_mfma_f32_16x16x32_bf16 v[124:127], v[144:147], v[202:205], v[124:127]
	v_mfma_f32_16x16x32_bf16 v[120:123], v[152:155], v[202:205], v[120:123]
	v_mfma_f32_16x16x32_bf16 v[116:119], v[144:147], v[210:213], v[116:119]
	v_mfma_f32_16x16x32_bf16 v[112:115], v[152:155], v[210:213], v[112:115]
	v_mfma_f32_16x16x32_bf16 v[104:107], v[144:147], v[218:221], v[104:107]
	v_mfma_f32_16x16x32_bf16 v[96:99], v[152:155], v[218:221], v[96:99]
	v_mfma_f32_16x16x32_bf16 v[88:91], v[144:147], v[232:235], v[88:91]
	v_mfma_f32_16x16x32_bf16 v[80:83], v[152:155], v[232:235], v[80:83]
	v_mfma_f32_16x16x32_bf16 v[108:111], v[156:159], v[198:201], v[108:111]
	v_mfma_f32_16x16x32_bf16 v[100:103], v[164:167], v[198:201], v[100:103]
	v_mfma_f32_16x16x32_bf16 v[92:95], v[156:159], v[206:209], v[92:95]
	v_mfma_f32_16x16x32_bf16 v[84:87], v[164:167], v[206:209], v[84:87]
	v_mfma_f32_16x16x32_bf16 v[76:79], v[156:159], v[214:217], v[76:79]
	v_mfma_f32_16x16x32_bf16 v[72:75], v[164:167], v[214:217], v[72:75]
	v_mfma_f32_16x16x32_bf16 v[68:71], v[156:159], v[228:231], v[68:71]
	v_mfma_f32_16x16x32_bf16 v[64:67], v[164:167], v[228:231], v[64:67]
	v_mfma_f32_16x16x32_bf16 v[108:111], v[160:163], v[202:205], v[108:111]
	v_mfma_f32_16x16x32_bf16 v[100:103], v[168:171], v[202:205], v[100:103]
	v_mfma_f32_16x16x32_bf16 v[92:95], v[160:163], v[210:213], v[92:95]
	v_mfma_f32_16x16x32_bf16 v[84:87], v[168:171], v[210:213], v[84:87]
	v_mfma_f32_16x16x32_bf16 v[76:79], v[160:163], v[218:221], v[76:79]
	v_mfma_f32_16x16x32_bf16 v[72:75], v[168:171], v[218:221], v[72:75]
	v_mfma_f32_16x16x32_bf16 v[68:71], v[160:163], v[232:235], v[68:71]
	v_mfma_f32_16x16x32_bf16 v[64:67], v[168:171], v[232:235], v[64:67]
	s_barrier
	s_add_i32 s36, s76, s58
	v_lshl_add_u64 v[134:135], s[50:51], 0, v[172:173]
	s_mov_b32 m0, s36
	ds_read_b128 v[198:201], v139 offset:16384
	ds_read_b128 v[202:205], v139 offset:17408
	ds_read_b128 v[206:209], v139 offset:18432
	ds_read_b128 v[210:213], v139 offset:19456
	ds_read_b128 v[214:217], v139 offset:20480
	ds_read_b128 v[218:221], v139 offset:21504
	ds_read_b128 v[228:231], v139 offset:22528
	ds_read_b128 v[232:235], v139 offset:23552
	global_load_lds_dwordx4 v[134:135], off
	s_add_i32 m0, s36, 0x2000
	s_add_u32 s36, s50, 0x160000
	v_lshl_add_u64 v[194:195], s[50:51], 0, v[128:129]
	s_addc_u32 s37, s51, 0
	s_add_i32 s76, s77, s58
	global_load_lds_dwordx4 v[194:195], off
	v_lshl_add_u64 v[224:225], s[36:37], 0, v[172:173]
	s_mov_b32 m0, s76
	v_lshl_add_u64 v[236:237], s[52:53], 0, v[128:129]
	global_load_lds_dwordx4 v[224:225], off
	v_lshl_add_u64 v[224:225], s[36:37], 0, v[128:129]
	s_add_i32 m0, s76, 0x2000
	s_nop 0
	global_load_lds_dwordx4 v[224:225], off
	v_lshl_add_u64 v[224:225], s[52:53], 0, v[172:173]
	s_mov_b32 m0, s59
	s_nop 0
	global_load_lds_dwordx4 v[224:225], off
	s_mov_b32 m0, s60
	s_nop 0
	global_load_lds_dwordx4 v[236:237], off
	s_waitcnt vmcnt(8)
	s_waitcnt lgkmcnt(0)
	s_barrier
; #define PG8_STAGE(bufoff, gbase, voff) do { _Pragma("unroll") for (int _i = 0; _i < 2; ++_i) \
;         __builtin_amdgcn_global_load_lds((const unsigned*)((const char*)(gbase) + (voff)[_i]), (LAS unsigned*)(lds + (bufoff) + ldsw + _i * 8192), 16, 0, 0); } while (0)
; #define PG8_LDA(dst, b, h) do { _Pragma("unroll") for (int m = 0; m < 4; ++m) _Pragma("unroll") for (int k = 0; k < 2; ++k) dst[m][k] = *(const LAS bf16x8*)(lds + PG8_SA(b, h) + aoff + m * 2048 + k * 1024); } while (0)
; #define PG8_LDB(dst, b, h) do { _Pragma("unroll") for (int n = 0; n < 2; ++n) _Pragma("unroll") for (int k = 0; k < 2; ++k) dst[n][k] = *(const LAS bf16x8*)(lds + PG8_SB(b, h) + boff + n * 2048 + k * 1024); } while (0)
; #define PG8_MMA(ai, bj, At, Bt) do { __builtin_amdgcn_s_setprio(1); _Pragma("unroll") for (int m = 0; m < 4; ++m) _Pragma("unroll") for (int n = 0; n < 2; ++n) _Pragma("unroll") for (int k = 0; k < 2; ++k) \
;         acc[ai][bj][m][n] = __builtin_amdgcn_mfma_f32_16x16x32_bf16(Bt[n][k], At[m][k], acc[ai][bj][m][n], 0, 0, 0); __builtin_amdgcn_s_setprio(0); } while (0)
; #define PG8_WAIT_V(n) asm volatile("s_waitcnt vmcnt(" #n ")" ::: "memory")
; #define PG8_WAIT_L(n) asm volatile("s_waitcnt lgkmcnt(" #n ")" ::: "memory")
; #define PG8_BAR __builtin_amdgcn_s_barrier()
; #define PG8_SCHED __builtin_amdgcn_sched_barrier(0)
; template <class Epi>
; __device__ __forceinline__ void gemm_phase(LAS unsigned char* lds, const Sched& S, const int K, const Epi& E) {
;     ...
;             PG8_WAIT_V(8); PG8_WAIT_L(0); PG8_BAR; PG8_MMA(1, 0, At, B0); PG8_MMA(1, 1, At, B1); PG8_BAR; PG8_SCHED;
;             PG8_LDB(B0, 1, 0); PG8_LDB(B1, 1, 1); PG8_SCHED; PG8_LDA(At, 1, 0); PG8_STAGE(PG8_SA(0, 1), a2 + hstepA, voffA);
;             PG8_WAIT_V(8); PG8_WAIT_L(0); PG8_BAR; PG8_MMA(0, 0, At, B0); PG8_MMA(0, 1, At, B1); PG8_BAR; PG8_SCHED;
	s_waitcnt lgkmcnt(0)
	v_mfma_f32_16x16x32_bf16 v[60:63], v[140:143], v[198:201], v[60:63]
	v_mfma_f32_16x16x32_bf16 v[56:59], v[148:151], v[198:201], v[56:59]
	v_mfma_f32_16x16x32_bf16 v[48:51], v[140:143], v[206:209], v[48:51]
	v_mfma_f32_16x16x32_bf16 v[40:43], v[148:151], v[206:209], v[40:43]
	v_mfma_f32_16x16x32_bf16 v[32:35], v[140:143], v[214:217], v[32:35]
	v_mfma_f32_16x16x32_bf16 v[24:27], v[148:151], v[214:217], v[24:27]
	v_mfma_f32_16x16x32_bf16 v[16:19], v[140:143], v[228:231], v[16:19]
	v_mfma_f32_16x16x32_bf16 v[8:11], v[148:151], v[228:231], v[8:11]
	v_mfma_f32_16x16x32_bf16 v[60:63], v[144:147], v[202:205], v[60:63]
	v_mfma_f32_16x16x32_bf16 v[56:59], v[152:155], v[202:205], v[56:59]
	v_mfma_f32_16x16x32_bf16 v[48:51], v[144:147], v[210:213], v[48:51]
	v_mfma_f32_16x16x32_bf16 v[40:43], v[152:155], v[210:213], v[40:43]
	v_mfma_f32_16x16x32_bf16 v[32:35], v[144:147], v[218:221], v[32:35]
	v_mfma_f32_16x16x32_bf16 v[24:27], v[152:155], v[218:221], v[24:27]
	v_mfma_f32_16x16x32_bf16 v[16:19], v[144:147], v[232:235], v[16:19]
	v_mfma_f32_16x16x32_bf16 v[8:11], v[152:155], v[232:235], v[8:11]
	v_mfma_f32_16x16x32_bf16 v[52:55], v[156:159], v[198:201], v[52:55]
	v_mfma_f32_16x16x32_bf16 v[44:47], v[164:167], v[198:201], v[44:47]
	v_mfma_f32_16x16x32_bf16 v[36:39], v[156:159], v[206:209], v[36:39]
	v_mfma_f32_16x16x32_bf16 v[28:31], v[164:167], v[206:209], v[28:31]
	v_mfma_f32_16x16x32_bf16 v[20:23], v[156:159], v[214:217], v[20:23]
	v_mfma_f32_16x16x32_bf16 v[12:15], v[164:167], v[214:217], v[12:15]
	v_mfma_f32_16x16x32_bf16 v[4:7], v[156:159], v[228:231], v[4:7]
	v_mfma_f32_16x16x32_bf16 v[0:3], v[164:167], v[228:231], v[0:3]
	v_mfma_f32_16x16x32_bf16 v[52:55], v[160:163], v[202:205], v[52:55]
	v_mfma_f32_16x16x32_bf16 v[44:47], v[168:171], v[202:205], v[44:47]
	v_mfma_f32_16x16x32_bf16 v[36:39], v[160:163], v[210:213], v[36:39]
	v_mfma_f32_16x16x32_bf16 v[28:31], v[168:171], v[210:213], v[28:31]
	v_mfma_f32_16x16x32_bf16 v[20:23], v[160:163], v[218:221], v[20:23]
	v_mfma_f32_16x16x32_bf16 v[12:15], v[168:171], v[218:221], v[12:15]
	v_mfma_f32_16x16x32_bf16 v[4:7], v[160:163], v[232:235], v[4:7]
	v_mfma_f32_16x16x32_bf16 v[0:3], v[168:171], v[232:235], v[0:3]
	s_barrier
	s_add_i32 s76, 0, 0x18000
	s_add_i32 s77, 0, 0x1c000
	v_add_u32_e32 v152, s76, v137
	v_add_u32_e32 v168, s77, v137
	ds_read_b128 v[140:143], v152
	ds_read_b128 v[144:147], v152 offset:1024
	ds_read_b128 v[148:151], v152 offset:2048
	ds_read_b128 v[152:155], v152 offset:3072
	ds_read_b128 v[156:159], v168
	ds_read_b128 v[160:163], v168 offset:1024
	ds_read_b128 v[164:167], v168 offset:2048
	ds_read_b128 v[168:171], v168 offset:3072
	s_add_u32 s36, s52, 0x160000
	s_addc_u32 s37, s53, 0
	s_mov_b32 m0, s63
	v_lshl_add_u64 v[238:239], s[36:37], 0, v[172:173]
	ds_read_b128 v[198:201], v139 offset:32768
	ds_read_b128 v[202:205], v139 offset:33792
	ds_read_b128 v[206:209], v139 offset:34816
	ds_read_b128 v[210:213], v139 offset:35840
	ds_read_b128 v[214:217], v139 offset:36864
	ds_read_b128 v[218:221], v139 offset:37888
	ds_read_b128 v[228:231], v139 offset:38912
	ds_read_b128 v[232:235], v139 offset:39936
	global_load_lds_dwordx4 v[238:239], off
	v_lshl_add_u64 v[238:239], s[36:37], 0, v[128:129]
	s_mov_b32 m0, s65
	s_nop 0
	global_load_lds_dwordx4 v[238:239], off
	s_waitcnt vmcnt(8)
	s_waitcnt lgkmcnt(0)
	s_barrier
	s_waitcnt lgkmcnt(0)
	v_mfma_f32_16x16x32_bf16 v[124:127], v[140:143], v[198:201], v[124:127]
	v_mfma_f32_16x16x32_bf16 v[120:123], v[148:151], v[198:201], v[120:123]
	v_mfma_f32_16x16x32_bf16 v[116:119], v[140:143], v[206:209], v[116:119]
	v_mfma_f32_16x16x32_bf16 v[112:115], v[148:151], v[206:209], v[112:115]
	v_mfma_f32_16x16x32_bf16 v[104:107], v[140:143], v[214:217], v[104:107]
	v_mfma_f32_16x16x32_bf16 v[96:99], v[148:151], v[214:217], v[96:99]
	v_mfma_f32_16x16x32_bf16 v[88:91], v[140:143], v[228:231], v[88:91]
	v_mfma_f32_16x16x32_bf16 v[80:83], v[148:151], v[228:231], v[80:83]
	v_mfma_f32_16x16x32_bf16 v[124:127], v[144:147], v[202:205], v[124:127]
	v_mfma_f32_16x16x32_bf16 v[120:123], v[152:155], v[202:205], v[120:123]
	v_mfma_f32_16x16x32_bf16 v[116:119], v[144:147], v[210:213], v[116:119]
	v_mfma_f32_16x16x32_bf16 v[112:115], v[152:155], v[210:213], v[112:115]
	v_mfma_f32_16x16x32_bf16 v[104:107], v[144:147], v[218:221], v[104:107]
	v_mfma_f32_16x16x32_bf16 v[96:99], v[152:155], v[218:221], v[96:99]
	v_mfma_f32_16x16x32_bf16 v[88:91], v[144:147], v[232:235], v[88:91]
	v_mfma_f32_16x16x32_bf16 v[80:83], v[152:155], v[232:235], v[80:83]
	v_mfma_f32_16x16x32_bf16 v[108:111], v[156:159], v[198:201], v[108:111]
	v_mfma_f32_16x16x32_bf16 v[100:103], v[164:167], v[198:201], v[100:103]
	v_mfma_f32_16x16x32_bf16 v[92:95], v[156:159], v[206:209], v[92:95]
	v_mfma_f32_16x16x32_bf16 v[84:87], v[164:167], v[206:209], v[84:87]
	v_mfma_f32_16x16x32_bf16 v[76:79], v[156:159], v[214:217], v[76:79]
	v_mfma_f32_16x16x32_bf16 v[72:75], v[164:167], v[214:217], v[72:75]
	v_mfma_f32_16x16x32_bf16 v[68:71], v[156:159], v[228:231], v[68:71]
	v_mfma_f32_16x16x32_bf16 v[64:67], v[164:167], v[228:231], v[64:67]
	v_mfma_f32_16x16x32_bf16 v[108:111], v[160:163], v[202:205], v[108:111]
	v_mfma_f32_16x16x32_bf16 v[100:103], v[168:171], v[202:205], v[100:103]
	v_mfma_f32_16x16x32_bf16 v[92:95], v[160:163], v[210:213], v[92:95]
	v_mfma_f32_16x16x32_bf16 v[84:87], v[168:171], v[210:213], v[84:87]
	v_mfma_f32_16x16x32_bf16 v[76:79], v[160:163], v[218:221], v[76:79]
	v_mfma_f32_16x16x32_bf16 v[72:75], v[168:171], v[218:221], v[72:75]
	v_mfma_f32_16x16x32_bf16 v[68:71], v[160:163], v[232:235], v[68:71]
	v_mfma_f32_16x16x32_bf16 v[64:67], v[168:171], v[232:235], v[64:67]
	s_barrier
; #define PG8_STAGE(bufoff, gbase, voff) do { _Pragma("unroll") for (int _i = 0; _i < 2; ++_i) \
;         __builtin_amdgcn_global_load_lds((const unsigned*)((const char*)(gbase) + (voff)[_i]), (LAS unsigned*)(lds + (bufoff) + ldsw + _i * 8192), 16, 0, 0); } while (0)
; #define PG8_LDA(dst, b, h) do { _Pragma("unroll") for (int m = 0; m < 4; ++m) _Pragma("unroll") for (int k = 0; k < 2; ++k) dst[m][k] = *(const LAS bf16x8*)(lds + PG8_SA(b, h) + aoff + m * 2048 + k * 1024); } while (0)
; #define PG8_MMA(ai, bj, At, Bt) do { __builtin_amdgcn_s_setprio(1); _Pragma("unroll") for (int m = 0; m < 4; ++m) _Pragma("unroll") for (int n = 0; n < 2; ++n) _Pragma("unroll") for (int k = 0; k < 2; ++k) \
;         acc[ai][bj][m][n] = __builtin_amdgcn_mfma_f32_16x16x32_bf16(Bt[n][k], At[m][k], acc[ai][bj][m][n], 0, 0, 0); __builtin_amdgcn_s_setprio(0); } while (0)
; #define PG8_WAIT_V(n) asm volatile("s_waitcnt vmcnt(" #n ")" ::: "memory")
; #define PG8_WAIT_L(n) asm volatile("s_waitcnt lgkmcnt(" #n ")" ::: "memory")
; #define PG8_BAR __builtin_amdgcn_s_barrier()
; #define PG8_SCHED __builtin_amdgcn_sched_barrier(0)
; template <class Epi>
; __device__ __forceinline__ void gemm_phase(LAS unsigned char* lds, const Sched& S, const int K, const Epi& E) {
;     ...
;             PG8_LDA(At, 1, 1); PG8_STAGE(PG8_SB(1, 0), b3, voffB); PG8_STAGE(PG8_SB(1, 1), b3 + hstepB, voffB); PG8_STAGE(PG8_SA(1, 0), a3, voffA);
;             PG8_WAIT_V(8); PG8_WAIT_L(0); PG8_BAR; PG8_MMA(1, 0, At, B0); PG8_MMA(1, 1, At, B1); PG8_BAR; PG8_SCHED;
;         }
	s_add_i32 s36, s76, s58
	v_lshl_add_u64 v[134:135], v[134:135], 0, s[74:75]
	s_mov_b32 m0, s36
	ds_read_b128 v[198:201], v139 offset:49152
	ds_read_b128 v[202:205], v139 offset:50176
	ds_read_b128 v[206:209], v139 offset:51200
	ds_read_b128 v[210:213], v139 offset:52224
	ds_read_b128 v[214:217], v139 offset:53248
	ds_read_b128 v[218:221], v139 offset:54272
	ds_read_b128 v[228:231], v139 offset:55296
	ds_read_b128 v[232:235], v139 offset:56320
	global_load_lds_dwordx4 v[134:135], off
	s_add_i32 m0, s36, 0x2000
	s_add_u32 s36, s50, 0x160080
	v_lshl_add_u64 v[134:135], v[194:195], 0, s[74:75]
	s_addc_u32 s37, s51, 0
	s_add_i32 s50, s77, s58
	global_load_lds_dwordx4 v[134:135], off
	v_lshl_add_u64 v[134:135], s[36:37], 0, v[172:173]
	s_mov_b32 m0, s50
	s_nop 0
	global_load_lds_dwordx4 v[134:135], off
	v_lshl_add_u64 v[134:135], s[36:37], 0, v[128:129]
	s_add_i32 m0, s50, 0x2000
	s_nop 0
	global_load_lds_dwordx4 v[134:135], off
	v_lshl_add_u64 v[134:135], v[224:225], 0, s[74:75]
	s_mov_b32 m0, s66
	s_nop 0
	global_load_lds_dwordx4 v[134:135], off
	v_lshl_add_u64 v[134:135], v[236:237], 0, s[74:75]
	s_mov_b32 m0, s67
	s_nop 0
	global_load_lds_dwordx4 v[134:135], off
	s_waitcnt vmcnt(8)
	s_waitcnt lgkmcnt(0)
	s_barrier
	s_waitcnt lgkmcnt(0)
	v_mfma_f32_16x16x32_bf16 v[60:63], v[140:143], v[198:201], v[60:63]
	v_mfma_f32_16x16x32_bf16 v[56:59], v[148:151], v[198:201], v[56:59]
	v_mfma_f32_16x16x32_bf16 v[48:51], v[140:143], v[206:209], v[48:51]
	v_mfma_f32_16x16x32_bf16 v[40:43], v[148:151], v[206:209], v[40:43]
	v_mfma_f32_16x16x32_bf16 v[32:35], v[140:143], v[214:217], v[32:35]
	v_mfma_f32_16x16x32_bf16 v[24:27], v[148:151], v[214:217], v[24:27]
	v_mfma_f32_16x16x32_bf16 v[16:19], v[140:143], v[228:231], v[16:19]
	v_mfma_f32_16x16x32_bf16 v[8:11], v[148:151], v[228:231], v[8:11]
	v_mfma_f32_16x16x32_bf16 v[60:63], v[144:147], v[202:205], v[60:63]
	v_mfma_f32_16x16x32_bf16 v[56:59], v[152:155], v[202:205], v[56:59]
	v_mfma_f32_16x16x32_bf16 v[48:51], v[144:147], v[210:213], v[48:51]
	v_mfma_f32_16x16x32_bf16 v[40:43], v[152:155], v[210:213], v[40:43]
	v_mfma_f32_16x16x32_bf16 v[32:35], v[144:147], v[218:221], v[32:35]
	v_mfma_f32_16x16x32_bf16 v[24:27], v[152:155], v[218:221], v[24:27]
	v_mfma_f32_16x16x32_bf16 v[16:19], v[144:147], v[232:235], v[16:19]
	v_mfma_f32_16x16x32_bf16 v[8:11], v[152:155], v[232:235], v[8:11]
	v_mfma_f32_16x16x32_bf16 v[52:55], v[156:159], v[198:201], v[52:55]
	v_mfma_f32_16x16x32_bf16 v[44:47], v[164:167], v[198:201], v[44:47]
	v_mfma_f32_16x16x32_bf16 v[36:39], v[156:159], v[206:209], v[36:39]
	v_mfma_f32_16x16x32_bf16 v[28:31], v[164:167], v[206:209], v[28:31]
	v_mfma_f32_16x16x32_bf16 v[20:23], v[156:159], v[214:217], v[20:23]
	v_mfma_f32_16x16x32_bf16 v[12:15], v[164:167], v[214:217], v[12:15]
	v_mfma_f32_16x16x32_bf16 v[4:7], v[156:159], v[228:231], v[4:7]
	v_mfma_f32_16x16x32_bf16 v[0:3], v[164:167], v[228:231], v[0:3]
	v_mfma_f32_16x16x32_bf16 v[52:55], v[160:163], v[202:205], v[52:55]
	v_mfma_f32_16x16x32_bf16 v[44:47], v[168:171], v[202:205], v[44:47]
	v_mfma_f32_16x16x32_bf16 v[36:39], v[160:163], v[210:213], v[36:39]
	v_mfma_f32_16x16x32_bf16 v[28:31], v[168:171], v[210:213], v[28:31]
	v_mfma_f32_16x16x32_bf16 v[20:23], v[160:163], v[218:221], v[20:23]
	v_mfma_f32_16x16x32_bf16 v[12:15], v[168:171], v[218:221], v[12:15]
	v_mfma_f32_16x16x32_bf16 v[4:7], v[160:163], v[232:235], v[4:7]
	v_mfma_f32_16x16x32_bf16 v[0:3], v[168:171], v[232:235], v[0:3]
	s_barrier
	s_add_i32 s92, s92, 2
	s_add_u32 s72, s72, 0x100
	s_addc_u32 s73, s73, 0
	s_cmpk_gt_u32 s92, 0x55
	s_mov_b64 s[36:37], s[48:49]
	s_cbranch_scc0 .LBB0_1487
	s_and_b64 vcc, exec, s[42:43]
	s_cbranch_vccz .LBB0_1490
	s_barrier
